# PEER gather restructured into two passes per token (16 dot products, one vector erf/gate evaluation for all experts, 16 accumulations) with separate u/v register rings
# speedup vs baseline: 1.1182x; 1.0018x over previous
.LBB0_1557:
	s_or_b64 exec, exec, s[42:43]
	s_waitcnt lgkmcnt(1)
	v_max_u32_dpp v3, v2, v2 quad_perm:[1,0,3,2] row_mask:0xf bank_mask:0xf bound_ctrl:1
	s_add_u32 s44, s92, 0x12224000
	s_addc_u32 s45, s93, 0
	v_max_u32_dpp v3, v3, v3 quad_perm:[2,3,0,1] row_mask:0xf bank_mask:0xf bound_ctrl:1
	s_add_u32 s42, s92, 0x4d60000
	s_addc_u32 s43, s93, 0
	v_max_u32_dpp v3, v3, v3 row_half_mirror row_mask:0xf bank_mask:0xf bound_ctrl:1
	v_bitop3_b32 v1, v1, s52, v1 bitop3:0xc
	v_bitop3_b32 v0, v0, s52, v0 bitop3:0xc
	v_max_u32_dpp v3, v3, v3 row_mirror row_mask:0xf bank_mask:0xf bound_ctrl:1
	v_lshlrev_b32_e32 v38, 4, v166
	v_readlane_b32 s47, v3, 32
	v_readlane_b32 s48, v3, 48
	v_readlane_b32 s46, v3, 16
	s_max_u32 s47, s47, s48
	v_readlane_b32 s4, v3, 0
	v_mov_b32_e32 v3, s46
	s_waitcnt lgkmcnt(0)
	v_mov_b32_e32 v4, s47
	v_max3_u32 v3, s4, v3, v4
	v_cmp_ne_u32_e32 vcc, v2, v3
	v_cndmask_b32_e64 v3, 0, v3, s[8:9]
	v_lshlrev_b32_e32 v176, 2, v172
	v_cndmask_b32_e32 v2, 0, v2, vcc
	v_lshlrev_b32_e32 v120, 2, v36
	v_add_u32_e32 v124, 0x800, v120
	v_max_u32_dpp v4, v2, v2 quad_perm:[1,0,3,2] row_mask:0xf bank_mask:0xf bound_ctrl:1
	v_readlane_b32 s56, v241, 54
	v_lshl_add_u64 v[34:35], s[86:87], 0, v[34:35]
	v_max_u32_dpp v4, v4, v4 quad_perm:[2,3,0,1] row_mask:0xf bank_mask:0xf bound_ctrl:1
	v_ashrrev_i32_e32 v121, 31, v120
	v_ashrrev_i32_e32 v125, 31, v124
	v_max_u32_dpp v4, v4, v4 row_half_mirror row_mask:0xf bank_mask:0xf bound_ctrl:1
	v_readlane_b32 s57, v241, 55
	v_readlane_b32 s58, v241, 56
	v_max_u32_dpp v4, v4, v4 row_mirror row_mask:0xf bank_mask:0xf bound_ctrl:1
	v_readlane_b32 s59, v241, 57
	v_readlane_b32 s47, v4, 32
	v_readlane_b32 s48, v4, 48
	v_readlane_b32 s46, v4, 16
	s_max_u32 s47, s47, s48
	v_readlane_b32 s4, v4, 0
	v_mov_b32_e32 v4, s46
	v_mov_b32_e32 v5, s47
	v_max3_u32 v4, s4, v4, v5
	v_cmp_ne_u32_e32 vcc, v2, v4
	v_cndmask_b32_e64 v3, v3, v4, s[10:11]
	v_readlane_b32 s60, v241, 58
	v_cndmask_b32_e32 v2, 0, v2, vcc
	v_readlane_b32 s61, v241, 59
	v_readlane_b32 s62, v241, 60
	v_max_u32_dpp v4, v2, v2 quad_perm:[1,0,3,2] row_mask:0xf bank_mask:0xf bound_ctrl:1
	v_readlane_b32 s63, v241, 61
	v_readlane_b32 s64, v241, 62
	v_max_u32_dpp v4, v4, v4 quad_perm:[2,3,0,1] row_mask:0xf bank_mask:0xf bound_ctrl:1
	v_readlane_b32 s65, v241, 63
	v_lshlrev_b32_e32 v177, 4, v36
	v_max_u32_dpp v4, v4, v4 row_half_mirror row_mask:0xf bank_mask:0xf bound_ctrl:1
	v_add_u32_e32 v178, 0x2800, v120
	v_lshl_add_u64 v[122:123], v[120:121], 2, s[90:91]
	v_max_u32_dpp v4, v4, v4 row_mirror row_mask:0xf bank_mask:0xf bound_ctrl:1
	v_lshlrev_b32_e32 v180, 2, v32
	v_readlane_b32 s47, v4, 32
	v_readlane_b32 s48, v4, 48
	v_readlane_b32 s46, v4, 16
	s_max_u32 s47, s47, s48
	v_readlane_b32 s4, v4, 0
	v_mov_b32_e32 v4, s46
	v_mov_b32_e32 v5, s47
	v_max3_u32 v4, s4, v4, v5
	v_cmp_ne_u32_e32 vcc, v2, v4
	v_cndmask_b32_e64 v3, v3, v4, s[12:13]
	v_lshl_add_u64 v[126:127], v[124:125], 2, s[58:59]
	v_cndmask_b32_e32 v2, 0, v2, vcc
	v_lshl_add_u64 v[130:131], v[34:35], 0, v[112:113]
	s_mov_b32 s55, 0x378e98ab
	v_max_u32_dpp v4, v2, v2 quad_perm:[1,0,3,2] row_mask:0xf bank_mask:0xf bound_ctrl:1
	s_mov_b32 s56, 0x3b7cd369
	s_mov_b32 s57, 0xbcc618b2
	v_max_u32_dpp v4, v4, v4 quad_perm:[2,3,0,1] row_mask:0xf bank_mask:0xf bound_ctrl:1
	s_mov_b32 s58, 0x3dda74e4
	s_mov_b32 s59, 0x3f228afd
	v_max_u32_dpp v4, v4, v4 row_half_mirror row_mask:0xf bank_mask:0xf bound_ctrl:1
	s_mov_b32 s60, 0x3e03c728
	s_mov_b32 s61, 0xbfb8aa3b
	v_max_u32_dpp v4, v4, v4 row_mirror row_mask:0xf bank_mask:0xf bound_ctrl:1
	s_mov_b32 s62, 0x42ce8ed0
	v_readlane_b32 s47, v4, 32
	v_readlane_b32 s48, v4, 48
	v_readlane_b32 s46, v4, 16
	s_max_u32 s47, s47, s48
	v_readlane_b32 s4, v4, 0
	v_mov_b32_e32 v4, s46
	v_mov_b32_e32 v5, s47
	v_max3_u32 v4, s4, v4, v5
	v_cmp_ne_u32_e32 vcc, v2, v4
	v_cndmask_b32_e64 v3, v3, v4, s[14:15]
	s_mov_b32 s63, 0xc2b17218
	v_cndmask_b32_e32 v2, 0, v2, vcc
	v_mov_b32_e32 v112, 0x3ba10414
	s_brev_b32 s64, -2
	v_max_u32_dpp v4, v2, v2 quad_perm:[1,0,3,2] row_mask:0xf bank_mask:0xf bound_ctrl:1
	v_mov_b32_e32 v182, 0x358637bd
	s_movk_i32 s65, 0x7fff
	v_max_u32_dpp v4, v4, v4 quad_perm:[2,3,0,1] row_mask:0xf bank_mask:0xf bound_ctrl:1
	v_mov_b32_e32 v183, 0xb9c68948
	v_mov_b32_e32 v184, 0x7f800000
	v_max_u32_dpp v4, v4, v4 row_half_mirror row_mask:0xf bank_mask:0xf bound_ctrl:1
	v_mov_b32_e32 v185, 1
	v_readlane_b32 s66, v240, 0
	v_max_u32_dpp v4, v4, v4 row_mirror row_mask:0xf bank_mask:0xf bound_ctrl:1
	v_readlane_b32 s67, v240, 1
	v_readlane_b32 s47, v4, 32
	v_readlane_b32 s48, v4, 48
	v_readlane_b32 s46, v4, 16
	s_max_u32 s47, s47, s48
	v_readlane_b32 s4, v4, 0
	v_mov_b32_e32 v4, s46
	v_mov_b32_e32 v5, s47
	v_max3_u32 v4, s4, v4, v5
	v_cmp_ne_u32_e32 vcc, v2, v4
	v_cndmask_b32_e64 v3, v3, v4, s[16:17]
	v_readlane_b32 s68, v240, 2
	v_cndmask_b32_e32 v2, 0, v2, vcc
	v_readlane_b32 s69, v240, 3
	v_readlane_b32 s70, v240, 4
	v_max_u32_dpp v4, v2, v2 quad_perm:[1,0,3,2] row_mask:0xf bank_mask:0xf bound_ctrl:1
	v_readlane_b32 s71, v240, 5
	s_nop 0
	v_max_u32_dpp v4, v4, v4 quad_perm:[2,3,0,1] row_mask:0xf bank_mask:0xf bound_ctrl:1
	s_nop 1
	v_max_u32_dpp v4, v4, v4 row_half_mirror row_mask:0xf bank_mask:0xf bound_ctrl:1
	s_nop 1
	v_max_u32_dpp v4, v4, v4 row_mirror row_mask:0xf bank_mask:0xf bound_ctrl:1
	s_nop 0
	v_readlane_b32 s47, v4, 32
	v_readlane_b32 s48, v4, 48
	v_readlane_b32 s46, v4, 16
	s_max_u32 s47, s47, s48
	v_readlane_b32 s4, v4, 0
	v_mov_b32_e32 v4, s46
	v_mov_b32_e32 v5, s47
	v_max3_u32 v4, s4, v4, v5
	v_cmp_ne_u32_e32 vcc, v2, v4
	v_cndmask_b32_e64 v3, v3, v4, s[18:19]
	s_nop 0
	v_cndmask_b32_e32 v2, 0, v2, vcc
	s_nop 1
	v_max_u32_dpp v4, v2, v2 quad_perm:[1,0,3,2] row_mask:0xf bank_mask:0xf bound_ctrl:1
	s_nop 1
	v_max_u32_dpp v4, v4, v4 quad_perm:[2,3,0,1] row_mask:0xf bank_mask:0xf bound_ctrl:1
	s_nop 1
	v_max_u32_dpp v4, v4, v4 row_half_mirror row_mask:0xf bank_mask:0xf bound_ctrl:1
	s_nop 1
	v_max_u32_dpp v4, v4, v4 row_mirror row_mask:0xf bank_mask:0xf bound_ctrl:1
	s_nop 0
	v_readlane_b32 s47, v4, 32
	v_readlane_b32 s48, v4, 48
	v_readlane_b32 s46, v4, 16
	s_max_u32 s47, s47, s48
	v_readlane_b32 s4, v4, 0
	v_mov_b32_e32 v4, s46
	v_mov_b32_e32 v5, s47
	v_max3_u32 v4, s4, v4, v5
	v_cmp_ne_u32_e32 vcc, v2, v4
	v_cndmask_b32_e64 v3, v3, v4, s[20:21]
	s_nop 0
	v_cndmask_b32_e32 v2, 0, v2, vcc
	s_nop 1
	v_max_u32_dpp v4, v2, v2 quad_perm:[1,0,3,2] row_mask:0xf bank_mask:0xf bound_ctrl:1
	s_nop 1
	v_max_u32_dpp v4, v4, v4 quad_perm:[2,3,0,1] row_mask:0xf bank_mask:0xf bound_ctrl:1
	s_nop 1
	v_max_u32_dpp v4, v4, v4 row_half_mirror row_mask:0xf bank_mask:0xf bound_ctrl:1
	s_nop 1
	v_max_u32_dpp v4, v4, v4 row_mirror row_mask:0xf bank_mask:0xf bound_ctrl:1
	s_nop 0
	v_readlane_b32 s47, v4, 32
	v_readlane_b32 s48, v4, 48
	v_readlane_b32 s46, v4, 16
	s_max_u32 s47, s47, s48
	v_readlane_b32 s4, v4, 0
	v_mov_b32_e32 v4, s46
	v_mov_b32_e32 v5, s47
	v_max3_u32 v4, s4, v4, v5
	v_cmp_ne_u32_e32 vcc, v2, v4
	v_cndmask_b32_e64 v3, v3, v4, s[22:23]
	s_nop 0
	v_cndmask_b32_e32 v2, 0, v2, vcc
	s_nop 1
	v_max_u32_dpp v4, v2, v2 quad_perm:[1,0,3,2] row_mask:0xf bank_mask:0xf bound_ctrl:1
	s_nop 1
	v_max_u32_dpp v4, v4, v4 quad_perm:[2,3,0,1] row_mask:0xf bank_mask:0xf bound_ctrl:1
	s_nop 1
	v_max_u32_dpp v4, v4, v4 row_half_mirror row_mask:0xf bank_mask:0xf bound_ctrl:1
	s_nop 1
	v_max_u32_dpp v4, v4, v4 row_mirror row_mask:0xf bank_mask:0xf bound_ctrl:1
	s_nop 0
	v_readlane_b32 s47, v4, 32
	v_readlane_b32 s48, v4, 48
	v_readlane_b32 s46, v4, 16
	s_max_u32 s47, s47, s48
	v_readlane_b32 s4, v4, 0
	v_mov_b32_e32 v4, s46
	v_mov_b32_e32 v5, s47
	v_max3_u32 v4, s4, v4, v5
	v_cmp_ne_u32_e32 vcc, v2, v4
	v_cndmask_b32_e64 v3, v3, v4, s[24:25]
	s_nop 0
	v_cndmask_b32_e32 v2, 0, v2, vcc
	s_nop 1
	v_max_u32_dpp v4, v2, v2 quad_perm:[1,0,3,2] row_mask:0xf bank_mask:0xf bound_ctrl:1
	s_nop 1
	v_max_u32_dpp v4, v4, v4 quad_perm:[2,3,0,1] row_mask:0xf bank_mask:0xf bound_ctrl:1
	s_nop 1
	v_max_u32_dpp v4, v4, v4 row_half_mirror row_mask:0xf bank_mask:0xf bound_ctrl:1
	s_nop 1
	v_max_u32_dpp v4, v4, v4 row_mirror row_mask:0xf bank_mask:0xf bound_ctrl:1
	s_nop 0
	v_readlane_b32 s47, v4, 32
	v_readlane_b32 s48, v4, 48
	v_readlane_b32 s46, v4, 16
	s_max_u32 s47, s47, s48
	v_readlane_b32 s4, v4, 0
	v_mov_b32_e32 v4, s46
	v_mov_b32_e32 v5, s47
	v_max3_u32 v4, s4, v4, v5
	v_cmp_ne_u32_e32 vcc, v2, v4
	v_cndmask_b32_e64 v3, v3, v4, s[26:27]
	s_nop 0
	v_cndmask_b32_e32 v2, 0, v2, vcc
	s_nop 1
	v_max_u32_dpp v4, v2, v2 quad_perm:[1,0,3,2] row_mask:0xf bank_mask:0xf bound_ctrl:1
	s_nop 1
	v_max_u32_dpp v4, v4, v4 quad_perm:[2,3,0,1] row_mask:0xf bank_mask:0xf bound_ctrl:1
	s_nop 1
	v_max_u32_dpp v4, v4, v4 row_half_mirror row_mask:0xf bank_mask:0xf bound_ctrl:1
	s_nop 1
	v_max_u32_dpp v4, v4, v4 row_mirror row_mask:0xf bank_mask:0xf bound_ctrl:1
	s_nop 0
	v_readlane_b32 s47, v4, 32
	v_readlane_b32 s48, v4, 48
	v_readlane_b32 s46, v4, 16
	s_max_u32 s47, s47, s48
	v_readlane_b32 s4, v4, 0
	v_mov_b32_e32 v4, s46
	v_mov_b32_e32 v5, s47
	v_max3_u32 v4, s4, v4, v5
	v_cmp_ne_u32_e32 vcc, v2, v4
	v_cndmask_b32_e64 v3, v3, v4, s[28:29]
	s_nop 0
	v_cndmask_b32_e32 v2, 0, v2, vcc
	s_nop 1
	v_max_u32_dpp v4, v2, v2 quad_perm:[1,0,3,2] row_mask:0xf bank_mask:0xf bound_ctrl:1
	s_nop 1
	v_max_u32_dpp v4, v4, v4 quad_perm:[2,3,0,1] row_mask:0xf bank_mask:0xf bound_ctrl:1
	s_nop 1
	v_max_u32_dpp v4, v4, v4 row_half_mirror row_mask:0xf bank_mask:0xf bound_ctrl:1
	s_nop 1
	v_max_u32_dpp v4, v4, v4 row_mirror row_mask:0xf bank_mask:0xf bound_ctrl:1
	s_nop 0
	v_readlane_b32 s47, v4, 32
	v_readlane_b32 s48, v4, 48
	v_readlane_b32 s46, v4, 16
	s_max_u32 s47, s47, s48
	v_readlane_b32 s4, v4, 0
	v_mov_b32_e32 v4, s46
	v_mov_b32_e32 v5, s47
	v_max3_u32 v4, s4, v4, v5
	v_cmp_ne_u32_e32 vcc, v2, v4
	v_cndmask_b32_e64 v3, v3, v4, s[30:31]
	s_nop 0
	v_cndmask_b32_e32 v2, 0, v2, vcc
	s_nop 1
	v_max_u32_dpp v4, v2, v2 quad_perm:[1,0,3,2] row_mask:0xf bank_mask:0xf bound_ctrl:1
	s_nop 1
	v_max_u32_dpp v4, v4, v4 quad_perm:[2,3,0,1] row_mask:0xf bank_mask:0xf bound_ctrl:1
	s_nop 1
	v_max_u32_dpp v4, v4, v4 row_half_mirror row_mask:0xf bank_mask:0xf bound_ctrl:1
	s_nop 1
	v_max_u32_dpp v4, v4, v4 row_mirror row_mask:0xf bank_mask:0xf bound_ctrl:1
	s_nop 0
	v_readlane_b32 s47, v4, 32
	v_readlane_b32 s48, v4, 48
	v_readlane_b32 s46, v4, 16
	s_max_u32 s47, s47, s48
	v_readlane_b32 s4, v4, 0
	v_mov_b32_e32 v4, s46
	v_mov_b32_e32 v5, s47
	v_max3_u32 v4, s4, v4, v5
	v_cmp_ne_u32_e32 vcc, v2, v4
	v_cndmask_b32_e64 v3, v3, v4, s[34:35]
	s_nop 0
	v_cndmask_b32_e32 v2, 0, v2, vcc
	s_nop 1
	v_max_u32_dpp v4, v2, v2 quad_perm:[1,0,3,2] row_mask:0xf bank_mask:0xf bound_ctrl:1
	s_nop 1
	v_max_u32_dpp v4, v4, v4 quad_perm:[2,3,0,1] row_mask:0xf bank_mask:0xf bound_ctrl:1
	s_nop 1
	v_max_u32_dpp v4, v4, v4 row_half_mirror row_mask:0xf bank_mask:0xf bound_ctrl:1
	s_nop 1
	v_max_u32_dpp v4, v4, v4 row_mirror row_mask:0xf bank_mask:0xf bound_ctrl:1
	s_nop 0
	v_readlane_b32 s47, v4, 32
	v_readlane_b32 s48, v4, 48
	v_readlane_b32 s46, v4, 16
	s_max_u32 s47, s47, s48
	v_readlane_b32 s4, v4, 0
	v_mov_b32_e32 v4, s46
	v_mov_b32_e32 v5, s47
	v_max3_u32 v4, s4, v4, v5
	v_cmp_ne_u32_e32 vcc, v2, v4
	v_cndmask_b32_e64 v3, v3, v4, s[36:37]
	s_nop 0
	v_cndmask_b32_e32 v2, 0, v2, vcc
	s_nop 1
	v_max_u32_dpp v4, v2, v2 quad_perm:[1,0,3,2] row_mask:0xf bank_mask:0xf bound_ctrl:1
	s_nop 1
	v_max_u32_dpp v4, v4, v4 quad_perm:[2,3,0,1] row_mask:0xf bank_mask:0xf bound_ctrl:1
	s_nop 1
	v_max_u32_dpp v4, v4, v4 row_half_mirror row_mask:0xf bank_mask:0xf bound_ctrl:1
	s_nop 1
	v_max_u32_dpp v4, v4, v4 row_mirror row_mask:0xf bank_mask:0xf bound_ctrl:1
	s_nop 0
	v_readlane_b32 s47, v4, 32
	v_readlane_b32 s48, v4, 48
	v_readlane_b32 s46, v4, 16
	s_max_u32 s47, s47, s48
	v_readlane_b32 s4, v4, 0
	v_mov_b32_e32 v4, s46
	v_mov_b32_e32 v5, s47
	v_max3_u32 v4, s4, v4, v5
	v_cmp_ne_u32_e32 vcc, v2, v4
	v_cndmask_b32_e64 v3, v3, v4, s[38:39]
	s_nop 0
	v_cndmask_b32_e32 v2, 0, v2, vcc
	s_nop 1
	v_max_u32_dpp v2, v2, v2 quad_perm:[1,0,3,2] row_mask:0xf bank_mask:0xf bound_ctrl:1
	s_nop 1
	v_max_u32_dpp v2, v2, v2 quad_perm:[2,3,0,1] row_mask:0xf bank_mask:0xf bound_ctrl:1
	s_nop 1
	v_max_u32_dpp v2, v2, v2 row_half_mirror row_mask:0xf bank_mask:0xf bound_ctrl:1
	s_nop 1
	v_max_u32_dpp v2, v2, v2 row_mirror row_mask:0xf bank_mask:0xf bound_ctrl:1
	s_nop 0
	v_readlane_b32 s47, v2, 32
	v_readlane_b32 s48, v2, 48
	v_readlane_b32 s46, v2, 16
	s_max_u32 s47, s47, s48
	v_readlane_b32 s4, v2, 0
	v_mov_b32_e32 v2, s46
	v_mov_b32_e32 v4, s47
	v_max3_u32 v2, s4, v2, v4
	v_cndmask_b32_e64 v2, v3, v2, s[40:41]
	v_and_or_b32 v3, v2, 63, v172
	v_lshlrev_b32_e32 v3, 2, v3
	v_xor_b32_e32 v3, 0xfc, v3
	ds_bpermute_b32 v4, v3, v171
	ds_bpermute_b32 v3, v3, v167
	v_cmp_lt_i32_e32 vcc, -1, v2
	s_mov_b32 s47, s5
	s_waitcnt lgkmcnt(1)
	v_and_or_b32 v4, v4, 63, v172
	s_waitcnt lgkmcnt(0)
	v_and_or_b32 v3, v3, 63, v172
	v_lshlrev_b32_e32 v4, 2, v4
	v_lshlrev_b32_e32 v3, 2, v3
	ds_bpermute_b32 v0, v4, v0
	ds_bpermute_b32 v1, v3, v1
	s_waitcnt lgkmcnt(0)
	v_lshl_add_u32 v0, v0, 7, v1
	v_and_or_b32 v1, v36, 15, v172
	v_and_b32_e32 v0, 0x3fff, v0
	v_lshlrev_b32_e32 v175, 2, v1
	ds_bpermute_b32 v132, v175, v0
	v_cndmask_b32_e64 v0, v169, -1, vcc
	v_bitop3_b32 v33, v0, v2, s3 bitop3:0x78
	ds_bpermute_b32 v37, v176, v33
	s_waitcnt lgkmcnt(1)
	v_readlane_b32 s4, v132, 1
	s_lshl_b64 s[48:49], s[4:5], 11
	s_add_u32 s50, s44, s48
	s_addc_u32 s51, s45, s49
	v_readlane_b32 s50, v240, 16
	v_readlane_b32 s46, v132, 0
	v_readlane_b32 s51, v240, 17
	s_add_u32 s48, s50, s48
	s_addc_u32 s49, s51, s49
	s_lshl_b64 s[46:47], s[46:47], 11
	s_add_u32 s48, s44, s46
	s_addc_u32 s49, s45, s47
	s_add_u32 s46, s50, s46
	s_addc_u32 s47, s51, s47
	s_waitcnt lgkmcnt(0)
	v_sub_f32_e32 v33, v33, v37
	v_mul_f32_e32 v33, 0x3fb8aa3b, v33
	v_exp_f32_e32 v33, v33
	s_add_u32 s53, s92, 0x5f64000
	s_addc_u32 s54, s93, 0
	v_cndmask_b32_e64 v33, 0, v33, s[6:7]
	s_nop 1
	v_add_f32_dpp v37, v33, v33 quad_perm:[1,0,3,2] row_mask:0xf bank_mask:0xf bound_ctrl:1
	s_nop 1
	v_add_f32_dpp v37, v37, v37 quad_perm:[2,3,0,1] row_mask:0xf bank_mask:0xf bound_ctrl:1
	s_nop 1
	v_add_f32_dpp v37, v37, v37 row_half_mirror row_mask:0xf bank_mask:0xf bound_ctrl:1
	s_nop 1
	v_add_f32_dpp v37, v37, v37 row_mirror row_mask:0xf bank_mask:0xf bound_ctrl:1
	s_nop 0
	v_readlane_b32 s4, v37, 16
	v_readlane_b32 s48, v37, 48
	v_readlane_b32 s46, v37, 0
	v_readlane_b32 s47, v37, 32
	v_mov_b32_e32 v40, s4
	v_mov_b32_e32 v41, s48
	v_pk_add_f32 v[40:41], s[46:47], v[40:41]
	s_nop 0
	v_add_f32_e32 v37, v40, v41
	v_div_scale_f32 v39, s[46:47], v37, v37, v33
	v_rcp_f32_e32 v40, v39
	v_readlane_b32 s46, v240, 6
	v_readlane_b32 s47, v240, 7
	v_fma_f32 v41, -v39, v40, 1.0
	v_fmac_f32_e32 v40, v41, v40
	v_div_scale_f32 v41, vcc, v33, v37, v33
	v_mul_f32_e32 v42, v41, v40
	v_fma_f32 v43, -v39, v42, v41
	v_fmac_f32_e32 v42, v43, v40
	v_fma_f32 v39, -v39, v42, v41
	v_div_fmas_f32 v39, v39, v40, v42
	v_div_fixup_f32 v33, v39, v37, v33
	ds_bpermute_b32 v179, v175, v33
	v_mov_b32_e32 v39, v113
	v_lshlrev_b32_e32 v33, 6, v166
	v_lshlrev_b32_e32 v40, 5, v166
	v_mov_b32_e32 v41, v113
	v_lshlrev_b32_e32 v37, 13, v32
	v_lshl_add_u64 v[114:115], s[46:47], 0, v[40:41]
	v_lshl_add_u64 v[116:117], s[50:51], 0, v[38:39]
	v_lshl_add_u64 v[118:119], s[44:45], 0, v[38:39]
	s_mov_b64 s[96:97], s[50:51]
	s_mov_b64 s[98:99], s[44:45]
	v_readlane_b32 s100, v132, 0
	s_nop 0
	s_lshl_b32 s100, s100, 11
	s_add_u32 s100, s96, s100
	s_addc_u32 s101, s97, 0
	global_load_dwordx4 v[0:3], v38, s[100:101]
	global_load_dwordx4 v[4:7], v38, s[100:101] offset:1024
	v_readlane_b32 s100, v132, 1
	s_nop 0
	s_lshl_b32 s100, s100, 11
	s_add_u32 s100, s96, s100
	s_addc_u32 s101, s97, 0
	global_load_dwordx4 v[8:11], v38, s[100:101]
	global_load_dwordx4 v[12:15], v38, s[100:101] offset:1024
	v_readlane_b32 s100, v132, 2
	s_nop 0
	s_lshl_b32 s100, s100, 11
	s_add_u32 s100, s96, s100
	s_addc_u32 s101, s97, 0
	global_load_dwordx4 v[16:19], v38, s[100:101]
	global_load_dwordx4 v[20:23], v38, s[100:101] offset:1024
	v_readlane_b32 s100, v132, 3
	s_nop 0
	s_lshl_b32 s100, s100, 11
	s_add_u32 s100, s96, s100
	s_addc_u32 s101, s97, 0
	global_load_dwordx4 v[24:27], v38, s[100:101]
	global_load_dwordx4 v[28:31], v38, s[100:101] offset:1024
	v_readlane_b32 s100, v132, 4
	s_nop 0
	s_lshl_b32 s100, s100, 11
	s_add_u32 s100, s96, s100
	s_addc_u32 s101, s97, 0
	global_load_dwordx4 v[96:99], v38, s[100:101]
	global_load_dwordx4 v[100:103], v38, s[100:101] offset:1024
	v_readlane_b32 s100, v132, 5
	s_nop 0
	s_lshl_b32 s100, s100, 11
	s_add_u32 s100, s96, s100
	s_addc_u32 s101, s97, 0
	global_load_dwordx4 v[104:107], v38, s[100:101]
	global_load_dwordx4 v[108:111], v38, s[100:101] offset:1024
	v_lshl_add_u64 v[128:129], v[120:121], 1, s[46:47]
	v_add_u32_e32 v181, v33, v37
	v_readlane_b32 s44, v240, 10
	v_readlane_b32 s45, v240, 11
	s_branch .LBB0_1559

.LBB0_1561:
	s_or_b64 exec, exec, s[46:47]
	s_waitcnt lgkmcnt(1)
	v_max_u32_dpp v36, v35, v35 quad_perm:[1,0,3,2] row_mask:0xf bank_mask:0xf bound_ctrl:1
	v_bitop3_b32 v32, v32, s52, v32 bitop3:0xc
	v_bitop3_b32 v33, v33, s52, v33 bitop3:0xc
	v_max_u32_dpp v36, v36, v36 quad_perm:[2,3,0,1] row_mask:0xf bank_mask:0xf bound_ctrl:1
	v_ashrrev_i32_e32 v133, 31, v132
	v_mov_b64_e32 v[74:75], v[18:19]
	v_max_u32_dpp v36, v36, v36 row_half_mirror row_mask:0xf bank_mask:0xf bound_ctrl:1
	v_mov_b64_e32 v[82:83], v[22:23]
	v_mov_b64_e32 v[90:91], v[26:27]
	v_max_u32_dpp v36, v36, v36 row_mirror row_mask:0xf bank_mask:0xf bound_ctrl:1
	v_mov_b64_e32 v[94:95], v[30:31]
	v_readlane_b32 s46, v36, 32
	v_readlane_b32 s47, v36, 48
	v_readlane_b32 s45, v36, 16
	s_max_u32 s46, s46, s47
	v_readlane_b32 s4, v36, 0
	v_mov_b32_e32 v36, s45
	s_waitcnt lgkmcnt(0)
	v_mov_b32_e32 v37, s46
	v_max3_u32 v36, s4, v36, v37
	v_cmp_ne_u32_e32 vcc, v35, v36
	v_cndmask_b32_e64 v36, 0, v36, s[8:9]
	s_mov_b32 s74, 0
	v_cndmask_b32_e32 v35, 0, v35, vcc
	s_mov_b32 s75, 5
	v_mov_b64_e32 v[72:73], v[16:17]
	v_max_u32_dpp v37, v35, v35 quad_perm:[1,0,3,2] row_mask:0xf bank_mask:0xf bound_ctrl:1
	v_mov_b64_e32 v[80:81], v[20:21]
	v_mov_b64_e32 v[88:89], v[24:25]
	v_max_u32_dpp v37, v37, v37 quad_perm:[2,3,0,1] row_mask:0xf bank_mask:0xf bound_ctrl:1
	v_mov_b64_e32 v[92:93], v[28:29]
	v_mov_b32_e32 v58, v34
	v_max_u32_dpp v37, v37, v37 row_half_mirror row_mask:0xf bank_mask:0xf bound_ctrl:1
	v_mov_b32_e32 v59, v34
	v_mov_b32_e32 v56, v34
	v_max_u32_dpp v37, v37, v37 row_mirror row_mask:0xf bank_mask:0xf bound_ctrl:1
	v_mov_b32_e32 v57, v34
	v_readlane_b32 s46, v37, 32
	v_readlane_b32 s47, v37, 48
	v_readlane_b32 s45, v37, 16
	s_max_u32 s46, s46, s47
	v_readlane_b32 s4, v37, 0
	v_mov_b32_e32 v37, s45
	v_mov_b32_e32 v38, s46
	v_max3_u32 v37, s4, v37, v38
	v_cmp_ne_u32_e32 vcc, v35, v37
	v_cndmask_b32_e64 v36, v36, v37, s[10:11]
	v_mov_b32_e32 v62, v34
	v_cndmask_b32_e32 v35, 0, v35, vcc
	v_mov_b32_e32 v63, v34
	v_mov_b32_e32 v60, v34
	v_max_u32_dpp v37, v35, v35 quad_perm:[1,0,3,2] row_mask:0xf bank_mask:0xf bound_ctrl:1
	v_mov_b32_e32 v61, v34
	v_mov_b32_e32 v70, v34
	v_max_u32_dpp v37, v37, v37 quad_perm:[2,3,0,1] row_mask:0xf bank_mask:0xf bound_ctrl:1
	v_mov_b32_e32 v71, v34
	v_mov_b32_e32 v68, v34
	v_max_u32_dpp v37, v37, v37 row_half_mirror row_mask:0xf bank_mask:0xf bound_ctrl:1
	v_mov_b32_e32 v69, v34
	s_nop 0
	v_max_u32_dpp v37, v37, v37 row_mirror row_mask:0xf bank_mask:0xf bound_ctrl:1
	s_nop 0
	v_readlane_b32 s46, v37, 32
	v_readlane_b32 s47, v37, 48
	v_readlane_b32 s45, v37, 16
	s_max_u32 s46, s46, s47
	v_readlane_b32 s4, v37, 0
	v_mov_b32_e32 v37, s45
	v_mov_b32_e32 v38, s46
	v_max3_u32 v37, s4, v37, v38
	v_cmp_ne_u32_e32 vcc, v35, v37
	v_cndmask_b32_e64 v36, v36, v37, s[12:13]
	s_nop 0
	v_cndmask_b32_e32 v35, 0, v35, vcc
	s_nop 1
	v_max_u32_dpp v37, v35, v35 quad_perm:[1,0,3,2] row_mask:0xf bank_mask:0xf bound_ctrl:1
	s_nop 1
	v_max_u32_dpp v37, v37, v37 quad_perm:[2,3,0,1] row_mask:0xf bank_mask:0xf bound_ctrl:1
	s_nop 1
	v_max_u32_dpp v37, v37, v37 row_half_mirror row_mask:0xf bank_mask:0xf bound_ctrl:1
	s_nop 1
	v_max_u32_dpp v37, v37, v37 row_mirror row_mask:0xf bank_mask:0xf bound_ctrl:1
	s_nop 0
	v_readlane_b32 s46, v37, 32
	v_readlane_b32 s47, v37, 48
	v_readlane_b32 s45, v37, 16
	s_max_u32 s46, s46, s47
	v_readlane_b32 s4, v37, 0
	v_mov_b32_e32 v37, s45
	v_mov_b32_e32 v38, s46
	v_max3_u32 v37, s4, v37, v38
	v_cmp_ne_u32_e32 vcc, v35, v37
	v_cndmask_b32_e64 v36, v36, v37, s[14:15]
	s_nop 0
	v_cndmask_b32_e32 v35, 0, v35, vcc
	s_nop 1
	v_max_u32_dpp v37, v35, v35 quad_perm:[1,0,3,2] row_mask:0xf bank_mask:0xf bound_ctrl:1
	s_nop 1
	v_max_u32_dpp v37, v37, v37 quad_perm:[2,3,0,1] row_mask:0xf bank_mask:0xf bound_ctrl:1
	s_nop 1
	v_max_u32_dpp v37, v37, v37 row_half_mirror row_mask:0xf bank_mask:0xf bound_ctrl:1
	s_nop 1
	v_max_u32_dpp v37, v37, v37 row_mirror row_mask:0xf bank_mask:0xf bound_ctrl:1
	s_nop 0
	v_readlane_b32 s46, v37, 32
	v_readlane_b32 s47, v37, 48
	v_readlane_b32 s45, v37, 16
	s_max_u32 s46, s46, s47
	v_readlane_b32 s4, v37, 0
	v_mov_b32_e32 v37, s45
	v_mov_b32_e32 v38, s46
	v_max3_u32 v37, s4, v37, v38
	v_cmp_ne_u32_e32 vcc, v35, v37
	v_cndmask_b32_e64 v36, v36, v37, s[16:17]
	s_nop 0
	v_cndmask_b32_e32 v35, 0, v35, vcc
	s_nop 1
	v_max_u32_dpp v37, v35, v35 quad_perm:[1,0,3,2] row_mask:0xf bank_mask:0xf bound_ctrl:1
	s_nop 1
	v_max_u32_dpp v37, v37, v37 quad_perm:[2,3,0,1] row_mask:0xf bank_mask:0xf bound_ctrl:1
	s_nop 1
	v_max_u32_dpp v37, v37, v37 row_half_mirror row_mask:0xf bank_mask:0xf bound_ctrl:1
	s_nop 1
	v_max_u32_dpp v37, v37, v37 row_mirror row_mask:0xf bank_mask:0xf bound_ctrl:1
	s_nop 0
	v_readlane_b32 s46, v37, 32
	v_readlane_b32 s47, v37, 48
	v_readlane_b32 s45, v37, 16
	s_max_u32 s46, s46, s47
	v_readlane_b32 s4, v37, 0
	v_mov_b32_e32 v37, s45
	v_mov_b32_e32 v38, s46
	v_max3_u32 v37, s4, v37, v38
	v_cmp_ne_u32_e32 vcc, v35, v37
	v_cndmask_b32_e64 v36, v36, v37, s[18:19]
	s_nop 0
	v_cndmask_b32_e32 v35, 0, v35, vcc
	s_nop 1
	v_max_u32_dpp v37, v35, v35 quad_perm:[1,0,3,2] row_mask:0xf bank_mask:0xf bound_ctrl:1
	s_nop 1
	v_max_u32_dpp v37, v37, v37 quad_perm:[2,3,0,1] row_mask:0xf bank_mask:0xf bound_ctrl:1
	s_nop 1
	v_max_u32_dpp v37, v37, v37 row_half_mirror row_mask:0xf bank_mask:0xf bound_ctrl:1
	s_nop 1
	v_max_u32_dpp v37, v37, v37 row_mirror row_mask:0xf bank_mask:0xf bound_ctrl:1
	s_nop 0
	v_readlane_b32 s46, v37, 32
	v_readlane_b32 s47, v37, 48
	v_readlane_b32 s45, v37, 16
	s_max_u32 s46, s46, s47
	v_readlane_b32 s4, v37, 0
	v_mov_b32_e32 v37, s45
	v_mov_b32_e32 v38, s46
	v_max3_u32 v37, s4, v37, v38
	v_cmp_ne_u32_e32 vcc, v35, v37
	v_cndmask_b32_e64 v36, v36, v37, s[20:21]
	s_nop 0
	v_cndmask_b32_e32 v35, 0, v35, vcc
	s_nop 1
	v_max_u32_dpp v37, v35, v35 quad_perm:[1,0,3,2] row_mask:0xf bank_mask:0xf bound_ctrl:1
	s_nop 1
	v_max_u32_dpp v37, v37, v37 quad_perm:[2,3,0,1] row_mask:0xf bank_mask:0xf bound_ctrl:1
	s_nop 1
	v_max_u32_dpp v37, v37, v37 row_half_mirror row_mask:0xf bank_mask:0xf bound_ctrl:1
	s_nop 1
	v_max_u32_dpp v37, v37, v37 row_mirror row_mask:0xf bank_mask:0xf bound_ctrl:1
	s_nop 0
	v_readlane_b32 s46, v37, 32
	v_readlane_b32 s47, v37, 48
	v_readlane_b32 s45, v37, 16
	s_max_u32 s46, s46, s47
	v_readlane_b32 s4, v37, 0
	v_mov_b32_e32 v37, s45
	v_mov_b32_e32 v38, s46
	v_max3_u32 v37, s4, v37, v38
	v_cmp_ne_u32_e32 vcc, v35, v37
	v_cndmask_b32_e64 v36, v36, v37, s[22:23]
	s_nop 0
	v_cndmask_b32_e32 v35, 0, v35, vcc
	s_nop 1
	v_max_u32_dpp v37, v35, v35 quad_perm:[1,0,3,2] row_mask:0xf bank_mask:0xf bound_ctrl:1
	s_nop 1
	v_max_u32_dpp v37, v37, v37 quad_perm:[2,3,0,1] row_mask:0xf bank_mask:0xf bound_ctrl:1
	s_nop 1
	v_max_u32_dpp v37, v37, v37 row_half_mirror row_mask:0xf bank_mask:0xf bound_ctrl:1
	s_nop 1
	v_max_u32_dpp v37, v37, v37 row_mirror row_mask:0xf bank_mask:0xf bound_ctrl:1
	s_nop 0
	v_readlane_b32 s46, v37, 32
	v_readlane_b32 s47, v37, 48
	v_readlane_b32 s45, v37, 16
	s_max_u32 s46, s46, s47
	v_readlane_b32 s4, v37, 0
	v_mov_b32_e32 v37, s45
	v_mov_b32_e32 v38, s46
	v_max3_u32 v37, s4, v37, v38
	v_cmp_ne_u32_e32 vcc, v35, v37
	v_cndmask_b32_e64 v36, v36, v37, s[24:25]
	s_nop 0
	v_cndmask_b32_e32 v35, 0, v35, vcc
	s_nop 1
	v_max_u32_dpp v37, v35, v35 quad_perm:[1,0,3,2] row_mask:0xf bank_mask:0xf bound_ctrl:1
	s_nop 1
	v_max_u32_dpp v37, v37, v37 quad_perm:[2,3,0,1] row_mask:0xf bank_mask:0xf bound_ctrl:1
	s_nop 1
	v_max_u32_dpp v37, v37, v37 row_half_mirror row_mask:0xf bank_mask:0xf bound_ctrl:1
	s_nop 1
	v_max_u32_dpp v37, v37, v37 row_mirror row_mask:0xf bank_mask:0xf bound_ctrl:1
	s_nop 0
	v_readlane_b32 s46, v37, 32
	v_readlane_b32 s47, v37, 48
	v_readlane_b32 s45, v37, 16
	s_max_u32 s46, s46, s47
	v_readlane_b32 s4, v37, 0
	v_mov_b32_e32 v37, s45
	v_mov_b32_e32 v38, s46
	v_max3_u32 v37, s4, v37, v38
	v_cmp_ne_u32_e32 vcc, v35, v37
	v_cndmask_b32_e64 v36, v36, v37, s[26:27]
	s_nop 0
	v_cndmask_b32_e32 v35, 0, v35, vcc
	s_nop 1
	v_max_u32_dpp v37, v35, v35 quad_perm:[1,0,3,2] row_mask:0xf bank_mask:0xf bound_ctrl:1
	s_nop 1
	v_max_u32_dpp v37, v37, v37 quad_perm:[2,3,0,1] row_mask:0xf bank_mask:0xf bound_ctrl:1
	s_nop 1
	v_max_u32_dpp v37, v37, v37 row_half_mirror row_mask:0xf bank_mask:0xf bound_ctrl:1
	s_nop 1
	v_max_u32_dpp v37, v37, v37 row_mirror row_mask:0xf bank_mask:0xf bound_ctrl:1
	s_nop 0
	v_readlane_b32 s46, v37, 32
	v_readlane_b32 s47, v37, 48
	v_readlane_b32 s45, v37, 16
	s_max_u32 s46, s46, s47
	v_readlane_b32 s4, v37, 0
	v_mov_b32_e32 v37, s45
	v_mov_b32_e32 v38, s46
	v_max3_u32 v37, s4, v37, v38
	v_cmp_ne_u32_e32 vcc, v35, v37
	v_cndmask_b32_e64 v36, v36, v37, s[28:29]
	s_nop 0
	v_cndmask_b32_e32 v35, 0, v35, vcc
	s_nop 1
	v_max_u32_dpp v37, v35, v35 quad_perm:[1,0,3,2] row_mask:0xf bank_mask:0xf bound_ctrl:1
	s_nop 1
	v_max_u32_dpp v37, v37, v37 quad_perm:[2,3,0,1] row_mask:0xf bank_mask:0xf bound_ctrl:1
	s_nop 1
	v_max_u32_dpp v37, v37, v37 row_half_mirror row_mask:0xf bank_mask:0xf bound_ctrl:1
	s_nop 1
	v_max_u32_dpp v37, v37, v37 row_mirror row_mask:0xf bank_mask:0xf bound_ctrl:1
	s_nop 0
	v_readlane_b32 s46, v37, 32
	v_readlane_b32 s47, v37, 48
	v_readlane_b32 s45, v37, 16
	s_max_u32 s46, s46, s47
	v_readlane_b32 s4, v37, 0
	v_mov_b32_e32 v37, s45
	v_mov_b32_e32 v38, s46
	v_max3_u32 v37, s4, v37, v38
	v_cmp_ne_u32_e32 vcc, v35, v37
	v_cndmask_b32_e64 v36, v36, v37, s[30:31]
	s_nop 0
	v_cndmask_b32_e32 v35, 0, v35, vcc
	s_nop 1
	v_max_u32_dpp v37, v35, v35 quad_perm:[1,0,3,2] row_mask:0xf bank_mask:0xf bound_ctrl:1
	s_nop 1
	v_max_u32_dpp v37, v37, v37 quad_perm:[2,3,0,1] row_mask:0xf bank_mask:0xf bound_ctrl:1
	s_nop 1
	v_max_u32_dpp v37, v37, v37 row_half_mirror row_mask:0xf bank_mask:0xf bound_ctrl:1
	s_nop 1
	v_max_u32_dpp v37, v37, v37 row_mirror row_mask:0xf bank_mask:0xf bound_ctrl:1
	s_nop 0
	v_readlane_b32 s46, v37, 32
	v_readlane_b32 s47, v37, 48
	v_readlane_b32 s45, v37, 16
	s_max_u32 s46, s46, s47
	v_readlane_b32 s4, v37, 0
	v_mov_b32_e32 v37, s45
	v_mov_b32_e32 v38, s46
	v_max3_u32 v37, s4, v37, v38
	v_cmp_ne_u32_e32 vcc, v35, v37
	v_cndmask_b32_e64 v44, v36, v37, s[34:35]
	s_ashr_i32 s45, s44, 31
	v_cndmask_b32_e32 v35, 0, v35, vcc
	s_lshl_b64 s[46:47], s[44:45], 12
	v_lshl_add_u64 v[48:49], v[114:115], 0, s[46:47]
	v_max_u32_dpp v36, v35, v35 quad_perm:[1,0,3,2] row_mask:0xf bank_mask:0xf bound_ctrl:1
	s_nop 1
	v_max_u32_dpp v45, v36, v36 quad_perm:[2,3,0,1] row_mask:0xf bank_mask:0xf bound_ctrl:1
	global_load_dwordx4 v[36:39], v[48:49], off offset:16
	global_load_dwordx4 v[40:43], v[48:49], off
	v_max_u32_dpp v45, v45, v45 row_half_mirror row_mask:0xf bank_mask:0xf bound_ctrl:1
	s_waitcnt vmcnt(1)
	v_lshlrev_b32_e32 v142, 16, v36
	v_max_u32_dpp v45, v45, v45 row_mirror row_mask:0xf bank_mask:0xf bound_ctrl:1
	s_waitcnt vmcnt(0)
	v_lshlrev_b32_e32 v134, 16, v40
	v_readlane_b32 s47, v45, 32
	v_readlane_b32 s48, v45, 48
	v_readlane_b32 s46, v45, 16
	s_max_u32 s47, s47, s48
	v_readlane_b32 s4, v45, 0
	v_mov_b32_e32 v45, s46
	v_mov_b32_e32 v46, s47
	v_max3_u32 v45, s4, v45, v46
	v_cmp_ne_u32_e32 vcc, v35, v45
	v_cndmask_b32_e64 v52, v44, v45, s[36:37]
	global_load_dwordx4 v[44:47], v[48:49], off offset:2064
	s_nop 0
	global_load_dwordx4 v[48:51], v[48:49], off offset:2048
	v_cndmask_b32_e32 v35, 0, v35, vcc
	v_and_b32_e32 v135, 0xffff0000, v40
	v_lshlrev_b32_e32 v136, 16, v41
	v_max_u32_dpp v53, v35, v35 quad_perm:[1,0,3,2] row_mask:0xf bank_mask:0xf bound_ctrl:1
	v_and_b32_e32 v137, 0xffff0000, v41
	v_lshlrev_b32_e32 v138, 16, v42
	v_max_u32_dpp v53, v53, v53 quad_perm:[2,3,0,1] row_mask:0xf bank_mask:0xf bound_ctrl:1
	v_and_b32_e32 v139, 0xffff0000, v42
	v_lshlrev_b32_e32 v140, 16, v43
	v_max_u32_dpp v53, v53, v53 row_half_mirror row_mask:0xf bank_mask:0xf bound_ctrl:1
	v_and_b32_e32 v141, 0xffff0000, v43
	v_and_b32_e32 v143, 0xffff0000, v36
	v_max_u32_dpp v53, v53, v53 row_mirror row_mask:0xf bank_mask:0xf bound_ctrl:1
	v_lshlrev_b32_e32 v144, 16, v37
	v_readlane_b32 s47, v53, 32
	v_readlane_b32 s48, v53, 48
	v_readlane_b32 s46, v53, 16
	s_max_u32 s47, s47, s48
	v_readlane_b32 s4, v53, 0
	v_mov_b32_e32 v53, s46
	v_mov_b32_e32 v54, s47
	v_max3_u32 v53, s4, v53, v54
	v_cmp_ne_u32_e32 vcc, v35, v53
	v_cndmask_b32_e64 v52, v52, v53, s[38:39]
	v_and_b32_e32 v145, 0xffff0000, v37
	v_cndmask_b32_e32 v35, 0, v35, vcc
	v_lshlrev_b32_e32 v146, 16, v38
	v_and_b32_e32 v147, 0xffff0000, v38
	v_max_u32_dpp v35, v35, v35 quad_perm:[1,0,3,2] row_mask:0xf bank_mask:0xf bound_ctrl:1
	v_lshlrev_b32_e32 v148, 16, v39
	v_and_b32_e32 v149, 0xffff0000, v39
	v_max_u32_dpp v35, v35, v35 quad_perm:[2,3,0,1] row_mask:0xf bank_mask:0xf bound_ctrl:1
	v_mov_b32_e32 v38, v34
	v_mov_b32_e32 v39, v34
	v_max_u32_dpp v35, v35, v35 row_half_mirror row_mask:0xf bank_mask:0xf bound_ctrl:1
	v_mov_b32_e32 v36, v34
	v_mov_b32_e32 v37, v34
	v_max_u32_dpp v35, v35, v35 row_mirror row_mask:0xf bank_mask:0xf bound_ctrl:1
	v_mov_b32_e32 v42, v34
	v_readlane_b32 s47, v35, 32
	v_readlane_b32 s48, v35, 48
	v_readlane_b32 s46, v35, 16
	s_max_u32 s47, s47, s48
	v_readlane_b32 s4, v35, 0
	v_mov_b32_e32 v35, s46
	v_mov_b32_e32 v53, s47
	v_max3_u32 v35, s4, v35, v53
	v_cndmask_b32_e64 v35, v52, v35, s[40:41]
	v_and_or_b32 v52, v35, 63, v172
	v_lshlrev_b32_e32 v52, 2, v52
	v_xor_b32_e32 v52, 0xfc, v52
	v_cmp_lt_i32_e32 vcc, -1, v35
	ds_bpermute_b32 v53, v52, v171
	ds_bpermute_b32 v52, v52, v167
	v_cndmask_b32_e64 v54, v169, -1, vcc
	v_bitop3_b32 v35, v54, v35, s3 bitop3:0x78
	ds_bpermute_b32 v54, v176, v35
	s_waitcnt lgkmcnt(2)
	v_and_or_b32 v53, v53, 63, v172
	v_lshlrev_b32_e32 v53, 2, v53
	ds_bpermute_b32 v55, v53, v32
	v_readlane_b32 s46, v240, 14
	s_waitcnt lgkmcnt(1)
	v_sub_f32_e32 v32, v35, v54
	v_mul_f32_e32 v32, 0x3fb8aa3b, v32
	v_exp_f32_e32 v32, v32
	v_and_or_b32 v35, v52, 63, v172
	v_lshlrev_b32_e32 v35, 2, v35
	ds_bpermute_b32 v35, v35, v33
	v_cndmask_b32_e64 v186, 0, v32, s[6:7]
	v_lshlrev_b64 v[32:33], 2, v[132:133]
	v_readlane_b32 s47, v240, 15
	v_add_f32_dpp v54, v186, v186 quad_perm:[1,0,3,2] row_mask:0xf bank_mask:0xf bound_ctrl:1
	v_mov_b32_e32 v43, v34
	v_lshl_add_u64 v[52:53], s[46:47], 0, v[32:33]
	v_lshl_add_u64 v[32:33], s[42:43], 0, v[32:33]
	global_load_dword v187, v[52:53], off
	global_load_dword v188, v[32:33], off
	v_add_f32_dpp v32, v54, v54 quad_perm:[2,3,0,1] row_mask:0xf bank_mask:0xf bound_ctrl:1
	v_mov_b32_e32 v33, v34
	v_mov_b32_e32 v40, v34
	v_add_f32_dpp v32, v32, v32 row_half_mirror row_mask:0xf bank_mask:0xf bound_ctrl:1
	s_waitcnt vmcnt(2)
	v_lshlrev_b32_e32 v150, 16, v48
	v_and_b32_e32 v151, 0xffff0000, v48
	v_add_f32_dpp v32, v32, v32 row_mirror row_mask:0xf bank_mask:0xf bound_ctrl:1
	v_lshlrev_b32_e32 v152, 16, v49
	v_readlane_b32 s67, v32, 0
	v_readlane_b32 s69, v32, 16
	v_readlane_b32 s68, v32, 32
	v_readlane_b32 s71, v32, 48
	s_waitcnt lgkmcnt(0)
	v_lshl_add_u32 v32, v55, 7, v35
	v_and_b32_e32 v32, 0x3fff, v32
	ds_bpermute_b32 v133, v175, v32
	v_and_b32_e32 v153, 0xffff0000, v49
	v_lshlrev_b32_e32 v154, 16, v50
	v_and_b32_e32 v155, 0xffff0000, v50
	v_lshlrev_b32_e32 v156, 16, v51
	v_and_b32_e32 v157, 0xffff0000, v51
	v_lshlrev_b32_e32 v158, 16, v44
	v_and_b32_e32 v159, 0xffff0000, v44
	v_lshlrev_b32_e32 v160, 16, v45
	v_and_b32_e32 v161, 0xffff0000, v45
	v_lshlrev_b32_e32 v162, 16, v46
	v_and_b32_e32 v163, 0xffff0000, v46
	v_lshlrev_b32_e32 v164, 16, v47
	v_and_b32_e32 v165, 0xffff0000, v47
	v_mov_b32_e32 v35, v34
	v_mov_b32_e32 v32, v34
	v_mov_b32_e32 v41, v34
	v_mov_b32_e32 v50, v34
	v_mov_b32_e32 v51, v34
	v_mov_b32_e32 v48, v34
	v_mov_b32_e32 v49, v34
	v_mov_b32_e32 v54, v34
	v_mov_b32_e32 v55, v34
	v_mov_b32_e32 v52, v34
	v_mov_b32_e32 v53, v34
	s_waitcnt vmcnt(0) lgkmcnt(0)
	v_subrev_u32_e32 v254, s96, v116
	s_nop 1
	v_readlane_b32 s100, v132, 6
	s_nop 0
	s_lshl_b32 s100, s100, 11
	s_add_u32 s100, s96, s100
	s_addc_u32 s101, s97, 0
	global_load_dwordx4 v[80:83], v254, s[100:101]
	global_load_dwordx4 v[84:87], v254, s[100:101] offset:1024
	s_waitcnt vmcnt(12)
	v_cvt_pk_f32_fp8_e32 v[44:45], v0
	v_pk_fma_f32 v[72:73], v[44:45], v[134:135], 0 op_sel_hi:[1,1,0]
	v_cvt_pk_f32_fp8_sdwa v[46:47], v0 src0_sel:WORD_1
	v_pk_fma_f32 v[72:73], v[46:47], v[136:137], v[72:73]
	v_cvt_pk_f32_fp8_e32 v[64:65], v1
	v_pk_fma_f32 v[72:73], v[64:65], v[138:139], v[72:73]
	v_cvt_pk_f32_fp8_sdwa v[66:67], v1 src0_sel:WORD_1
	v_pk_fma_f32 v[72:73], v[66:67], v[140:141], v[72:73]
	v_cvt_pk_f32_fp8_e32 v[44:45], v2
	v_pk_fma_f32 v[72:73], v[44:45], v[142:143], v[72:73]
	v_cvt_pk_f32_fp8_sdwa v[46:47], v2 src0_sel:WORD_1
	v_pk_fma_f32 v[72:73], v[46:47], v[144:145], v[72:73]
	v_cvt_pk_f32_fp8_e32 v[64:65], v3
	v_pk_fma_f32 v[72:73], v[64:65], v[146:147], v[72:73]
	v_cvt_pk_f32_fp8_sdwa v[66:67], v3 src0_sel:WORD_1
	v_pk_fma_f32 v[72:73], v[66:67], v[148:149], v[72:73]
	v_cvt_pk_f32_fp8_e32 v[44:45], v4
	v_pk_fma_f32 v[72:73], v[44:45], v[150:151], v[72:73]
	v_cvt_pk_f32_fp8_sdwa v[46:47], v4 src0_sel:WORD_1
	v_pk_fma_f32 v[72:73], v[46:47], v[152:153], v[72:73]
	v_cvt_pk_f32_fp8_e32 v[64:65], v5
	v_pk_fma_f32 v[72:73], v[64:65], v[154:155], v[72:73]
	v_cvt_pk_f32_fp8_sdwa v[66:67], v5 src0_sel:WORD_1
	v_pk_fma_f32 v[72:73], v[66:67], v[156:157], v[72:73]
	v_cvt_pk_f32_fp8_e32 v[44:45], v6
	v_pk_fma_f32 v[72:73], v[44:45], v[158:159], v[72:73]
	v_cvt_pk_f32_fp8_sdwa v[46:47], v6 src0_sel:WORD_1
	v_pk_fma_f32 v[72:73], v[46:47], v[160:161], v[72:73]
	v_cvt_pk_f32_fp8_e32 v[64:65], v7
	v_pk_fma_f32 v[72:73], v[64:65], v[162:163], v[72:73]
	v_cvt_pk_f32_fp8_sdwa v[66:67], v7 src0_sel:WORD_1
	v_pk_fma_f32 v[72:73], v[66:67], v[164:165], v[72:73]
	s_nop 1
	v_readlane_b32 s100, v132, 7
	v_add_f32_e32 v72, v72, v73
	s_lshl_b32 s100, s100, 11
	s_add_u32 s100, s96, s100
	s_addc_u32 s101, s97, 0
	global_load_dwordx4 v[88:91], v254, s[100:101]
	global_load_dwordx4 v[92:95], v254, s[100:101] offset:1024
	s_waitcnt vmcnt(12)
	v_cvt_pk_f32_fp8_e32 v[44:45], v8
	v_pk_fma_f32 v[74:75], v[44:45], v[134:135], 0 op_sel_hi:[1,1,0]
	v_cvt_pk_f32_fp8_sdwa v[46:47], v8 src0_sel:WORD_1
	v_pk_fma_f32 v[74:75], v[46:47], v[136:137], v[74:75]
	v_cvt_pk_f32_fp8_e32 v[64:65], v9
	v_pk_fma_f32 v[74:75], v[64:65], v[138:139], v[74:75]
	v_cvt_pk_f32_fp8_sdwa v[66:67], v9 src0_sel:WORD_1
	v_pk_fma_f32 v[74:75], v[66:67], v[140:141], v[74:75]
	v_cvt_pk_f32_fp8_e32 v[44:45], v10
	v_pk_fma_f32 v[74:75], v[44:45], v[142:143], v[74:75]
	v_cvt_pk_f32_fp8_sdwa v[46:47], v10 src0_sel:WORD_1
	v_pk_fma_f32 v[74:75], v[46:47], v[144:145], v[74:75]
	v_add_f32_dpp v72, v72, v72 quad_perm:[1,0,3,2] row_mask:0xf bank_mask:0xf bound_ctrl:1
	v_cvt_pk_f32_fp8_e32 v[64:65], v11
	v_pk_fma_f32 v[74:75], v[64:65], v[146:147], v[74:75]
	v_cvt_pk_f32_fp8_sdwa v[66:67], v11 src0_sel:WORD_1
	v_add_f32_dpp v72, v72, v72 quad_perm:[2,3,0,1] row_mask:0xf bank_mask:0xf bound_ctrl:1
	v_pk_fma_f32 v[74:75], v[66:67], v[148:149], v[74:75]
	v_cvt_pk_f32_fp8_e32 v[44:45], v12
	v_pk_fma_f32 v[74:75], v[44:45], v[150:151], v[74:75]
	v_add_f32_dpp v72, v72, v72 row_half_mirror row_mask:0xf bank_mask:0xf bound_ctrl:1
	v_cvt_pk_f32_fp8_sdwa v[46:47], v12 src0_sel:WORD_1
	v_pk_fma_f32 v[74:75], v[46:47], v[152:153], v[74:75]
	v_cvt_pk_f32_fp8_e32 v[64:65], v13
	v_add_f32_dpp v72, v72, v72 row_mirror row_mask:0xf bank_mask:0xf bound_ctrl:1
	v_pk_fma_f32 v[74:75], v[64:65], v[154:155], v[74:75]
	v_cvt_pk_f32_fp8_sdwa v[66:67], v13 src0_sel:WORD_1
	v_pk_fma_f32 v[74:75], v[66:67], v[156:157], v[74:75]
	v_add_f32_dpp v72, v72, v72 row_bcast:15 row_mask:0xa bank_mask:0xf
	v_cvt_pk_f32_fp8_e32 v[44:45], v14
	v_pk_fma_f32 v[74:75], v[44:45], v[158:159], v[74:75]
	v_cvt_pk_f32_fp8_sdwa v[46:47], v14 src0_sel:WORD_1
	v_add_f32_dpp v72, v72, v72 row_bcast:31 row_mask:0xc bank_mask:0xf
	v_pk_fma_f32 v[74:75], v[46:47], v[160:161], v[74:75]
	v_cvt_pk_f32_fp8_e32 v[64:65], v15
	v_readlane_b32 s48, v72, 63
	v_pk_fma_f32 v[74:75], v[64:65], v[162:163], v[74:75]
	v_cvt_pk_f32_fp8_sdwa v[66:67], v15 src0_sel:WORD_1
	v_pk_fma_f32 v[74:75], v[66:67], v[164:165], v[74:75]
	v_writelane_b32 v189, s48, 0
	s_nop 1
	v_readlane_b32 s100, v132, 8
	v_add_f32_e32 v74, v74, v75
	s_lshl_b32 s100, s100, 11
	s_add_u32 s100, s96, s100
	s_addc_u32 s101, s97, 0
	global_load_dwordx4 v[0:3], v254, s[100:101]
	global_load_dwordx4 v[4:7], v254, s[100:101] offset:1024
	s_waitcnt vmcnt(12)
	v_cvt_pk_f32_fp8_e32 v[44:45], v16
	v_pk_fma_f32 v[72:73], v[44:45], v[134:135], 0 op_sel_hi:[1,1,0]
	v_cvt_pk_f32_fp8_sdwa v[46:47], v16 src0_sel:WORD_1
	v_pk_fma_f32 v[72:73], v[46:47], v[136:137], v[72:73]
	v_cvt_pk_f32_fp8_e32 v[64:65], v17
	v_pk_fma_f32 v[72:73], v[64:65], v[138:139], v[72:73]
	v_cvt_pk_f32_fp8_sdwa v[66:67], v17 src0_sel:WORD_1
	v_pk_fma_f32 v[72:73], v[66:67], v[140:141], v[72:73]
	v_cvt_pk_f32_fp8_e32 v[44:45], v18
	v_pk_fma_f32 v[72:73], v[44:45], v[142:143], v[72:73]
	v_cvt_pk_f32_fp8_sdwa v[46:47], v18 src0_sel:WORD_1
	v_pk_fma_f32 v[72:73], v[46:47], v[144:145], v[72:73]
	v_add_f32_dpp v74, v74, v74 quad_perm:[1,0,3,2] row_mask:0xf bank_mask:0xf bound_ctrl:1
	v_cvt_pk_f32_fp8_e32 v[64:65], v19
	v_pk_fma_f32 v[72:73], v[64:65], v[146:147], v[72:73]
	v_cvt_pk_f32_fp8_sdwa v[66:67], v19 src0_sel:WORD_1
	v_add_f32_dpp v74, v74, v74 quad_perm:[2,3,0,1] row_mask:0xf bank_mask:0xf bound_ctrl:1
	v_pk_fma_f32 v[72:73], v[66:67], v[148:149], v[72:73]
	v_cvt_pk_f32_fp8_e32 v[44:45], v20
	v_pk_fma_f32 v[72:73], v[44:45], v[150:151], v[72:73]
	v_add_f32_dpp v74, v74, v74 row_half_mirror row_mask:0xf bank_mask:0xf bound_ctrl:1
	v_cvt_pk_f32_fp8_sdwa v[46:47], v20 src0_sel:WORD_1
	v_pk_fma_f32 v[72:73], v[46:47], v[152:153], v[72:73]
	v_cvt_pk_f32_fp8_e32 v[64:65], v21
	v_add_f32_dpp v74, v74, v74 row_mirror row_mask:0xf bank_mask:0xf bound_ctrl:1
	v_pk_fma_f32 v[72:73], v[64:65], v[154:155], v[72:73]
	v_cvt_pk_f32_fp8_sdwa v[66:67], v21 src0_sel:WORD_1
	v_pk_fma_f32 v[72:73], v[66:67], v[156:157], v[72:73]
	v_add_f32_dpp v74, v74, v74 row_bcast:15 row_mask:0xa bank_mask:0xf
	v_cvt_pk_f32_fp8_e32 v[44:45], v22
	v_pk_fma_f32 v[72:73], v[44:45], v[158:159], v[72:73]
	v_cvt_pk_f32_fp8_sdwa v[46:47], v22 src0_sel:WORD_1
	v_add_f32_dpp v74, v74, v74 row_bcast:31 row_mask:0xc bank_mask:0xf
	v_pk_fma_f32 v[72:73], v[46:47], v[160:161], v[72:73]
	v_cvt_pk_f32_fp8_e32 v[64:65], v23
	v_readlane_b32 s48, v74, 63
	v_pk_fma_f32 v[72:73], v[64:65], v[162:163], v[72:73]
	v_cvt_pk_f32_fp8_sdwa v[66:67], v23 src0_sel:WORD_1
	v_pk_fma_f32 v[72:73], v[66:67], v[164:165], v[72:73]
	v_writelane_b32 v189, s48, 1
	s_nop 1
	v_readlane_b32 s100, v132, 9
	v_add_f32_e32 v72, v72, v73
	s_lshl_b32 s100, s100, 11
	s_add_u32 s100, s96, s100
	s_addc_u32 s101, s97, 0
	global_load_dwordx4 v[8:11], v254, s[100:101]
	global_load_dwordx4 v[12:15], v254, s[100:101] offset:1024
	s_waitcnt vmcnt(12)
	v_cvt_pk_f32_fp8_e32 v[44:45], v24
	v_pk_fma_f32 v[74:75], v[44:45], v[134:135], 0 op_sel_hi:[1,1,0]
	v_cvt_pk_f32_fp8_sdwa v[46:47], v24 src0_sel:WORD_1
	v_pk_fma_f32 v[74:75], v[46:47], v[136:137], v[74:75]
	v_cvt_pk_f32_fp8_e32 v[64:65], v25
	v_pk_fma_f32 v[74:75], v[64:65], v[138:139], v[74:75]
	v_cvt_pk_f32_fp8_sdwa v[66:67], v25 src0_sel:WORD_1
	v_pk_fma_f32 v[74:75], v[66:67], v[140:141], v[74:75]
	v_cvt_pk_f32_fp8_e32 v[44:45], v26
	v_pk_fma_f32 v[74:75], v[44:45], v[142:143], v[74:75]
	v_cvt_pk_f32_fp8_sdwa v[46:47], v26 src0_sel:WORD_1
	v_pk_fma_f32 v[74:75], v[46:47], v[144:145], v[74:75]
	v_add_f32_dpp v72, v72, v72 quad_perm:[1,0,3,2] row_mask:0xf bank_mask:0xf bound_ctrl:1
	v_cvt_pk_f32_fp8_e32 v[64:65], v27
	v_pk_fma_f32 v[74:75], v[64:65], v[146:147], v[74:75]
	v_cvt_pk_f32_fp8_sdwa v[66:67], v27 src0_sel:WORD_1
	v_add_f32_dpp v72, v72, v72 quad_perm:[2,3,0,1] row_mask:0xf bank_mask:0xf bound_ctrl:1
	v_pk_fma_f32 v[74:75], v[66:67], v[148:149], v[74:75]
	v_cvt_pk_f32_fp8_e32 v[44:45], v28
	v_pk_fma_f32 v[74:75], v[44:45], v[150:151], v[74:75]
	v_add_f32_dpp v72, v72, v72 row_half_mirror row_mask:0xf bank_mask:0xf bound_ctrl:1
	v_cvt_pk_f32_fp8_sdwa v[46:47], v28 src0_sel:WORD_1
	v_pk_fma_f32 v[74:75], v[46:47], v[152:153], v[74:75]
	v_cvt_pk_f32_fp8_e32 v[64:65], v29
	v_add_f32_dpp v72, v72, v72 row_mirror row_mask:0xf bank_mask:0xf bound_ctrl:1
	v_pk_fma_f32 v[74:75], v[64:65], v[154:155], v[74:75]
	v_cvt_pk_f32_fp8_sdwa v[66:67], v29 src0_sel:WORD_1
	v_pk_fma_f32 v[74:75], v[66:67], v[156:157], v[74:75]
	v_add_f32_dpp v72, v72, v72 row_bcast:15 row_mask:0xa bank_mask:0xf
	v_cvt_pk_f32_fp8_e32 v[44:45], v30
	v_pk_fma_f32 v[74:75], v[44:45], v[158:159], v[74:75]
	v_cvt_pk_f32_fp8_sdwa v[46:47], v30 src0_sel:WORD_1
	v_add_f32_dpp v72, v72, v72 row_bcast:31 row_mask:0xc bank_mask:0xf
	v_pk_fma_f32 v[74:75], v[46:47], v[160:161], v[74:75]
	v_cvt_pk_f32_fp8_e32 v[64:65], v31
	v_readlane_b32 s48, v72, 63
	v_pk_fma_f32 v[74:75], v[64:65], v[162:163], v[74:75]
	v_cvt_pk_f32_fp8_sdwa v[66:67], v31 src0_sel:WORD_1
	v_pk_fma_f32 v[74:75], v[66:67], v[164:165], v[74:75]
	v_writelane_b32 v189, s48, 2
	s_nop 1
	v_readlane_b32 s100, v132, 10
	v_add_f32_e32 v74, v74, v75
	s_lshl_b32 s100, s100, 11
	s_add_u32 s100, s96, s100
	s_addc_u32 s101, s97, 0
	global_load_dwordx4 v[16:19], v254, s[100:101]
	global_load_dwordx4 v[20:23], v254, s[100:101] offset:1024
	s_waitcnt vmcnt(12)
	v_cvt_pk_f32_fp8_e32 v[44:45], v96
	v_pk_fma_f32 v[72:73], v[44:45], v[134:135], 0 op_sel_hi:[1,1,0]
	v_cvt_pk_f32_fp8_sdwa v[46:47], v96 src0_sel:WORD_1
	v_pk_fma_f32 v[72:73], v[46:47], v[136:137], v[72:73]
	v_cvt_pk_f32_fp8_e32 v[64:65], v97
	v_pk_fma_f32 v[72:73], v[64:65], v[138:139], v[72:73]
	v_cvt_pk_f32_fp8_sdwa v[66:67], v97 src0_sel:WORD_1
	v_pk_fma_f32 v[72:73], v[66:67], v[140:141], v[72:73]
	v_cvt_pk_f32_fp8_e32 v[44:45], v98
	v_pk_fma_f32 v[72:73], v[44:45], v[142:143], v[72:73]
	v_cvt_pk_f32_fp8_sdwa v[46:47], v98 src0_sel:WORD_1
	v_pk_fma_f32 v[72:73], v[46:47], v[144:145], v[72:73]
	v_add_f32_dpp v74, v74, v74 quad_perm:[1,0,3,2] row_mask:0xf bank_mask:0xf bound_ctrl:1
	v_cvt_pk_f32_fp8_e32 v[64:65], v99
	v_pk_fma_f32 v[72:73], v[64:65], v[146:147], v[72:73]
	v_cvt_pk_f32_fp8_sdwa v[66:67], v99 src0_sel:WORD_1
	v_add_f32_dpp v74, v74, v74 quad_perm:[2,3,0,1] row_mask:0xf bank_mask:0xf bound_ctrl:1
	v_pk_fma_f32 v[72:73], v[66:67], v[148:149], v[72:73]
	v_cvt_pk_f32_fp8_e32 v[44:45], v100
	v_pk_fma_f32 v[72:73], v[44:45], v[150:151], v[72:73]
	v_add_f32_dpp v74, v74, v74 row_half_mirror row_mask:0xf bank_mask:0xf bound_ctrl:1
	v_cvt_pk_f32_fp8_sdwa v[46:47], v100 src0_sel:WORD_1
	v_pk_fma_f32 v[72:73], v[46:47], v[152:153], v[72:73]
	v_cvt_pk_f32_fp8_e32 v[64:65], v101
	v_add_f32_dpp v74, v74, v74 row_mirror row_mask:0xf bank_mask:0xf bound_ctrl:1
	v_pk_fma_f32 v[72:73], v[64:65], v[154:155], v[72:73]
	v_cvt_pk_f32_fp8_sdwa v[66:67], v101 src0_sel:WORD_1
	v_pk_fma_f32 v[72:73], v[66:67], v[156:157], v[72:73]
	v_add_f32_dpp v74, v74, v74 row_bcast:15 row_mask:0xa bank_mask:0xf
	v_cvt_pk_f32_fp8_e32 v[44:45], v102
	v_pk_fma_f32 v[72:73], v[44:45], v[158:159], v[72:73]
	v_cvt_pk_f32_fp8_sdwa v[46:47], v102 src0_sel:WORD_1
	v_add_f32_dpp v74, v74, v74 row_bcast:31 row_mask:0xc bank_mask:0xf
	v_pk_fma_f32 v[72:73], v[46:47], v[160:161], v[72:73]
	v_cvt_pk_f32_fp8_e32 v[64:65], v103
	v_readlane_b32 s48, v74, 63
	v_pk_fma_f32 v[72:73], v[64:65], v[162:163], v[72:73]
	v_cvt_pk_f32_fp8_sdwa v[66:67], v103 src0_sel:WORD_1
	v_pk_fma_f32 v[72:73], v[66:67], v[164:165], v[72:73]
	v_writelane_b32 v189, s48, 3
	s_nop 1
	v_readlane_b32 s100, v132, 11
	v_add_f32_e32 v72, v72, v73
	s_lshl_b32 s100, s100, 11
	s_add_u32 s100, s96, s100
	s_addc_u32 s101, s97, 0
	global_load_dwordx4 v[24:27], v254, s[100:101]
	global_load_dwordx4 v[28:31], v254, s[100:101] offset:1024
	s_waitcnt vmcnt(12)
	v_cvt_pk_f32_fp8_e32 v[44:45], v104
	v_pk_fma_f32 v[74:75], v[44:45], v[134:135], 0 op_sel_hi:[1,1,0]
	v_cvt_pk_f32_fp8_sdwa v[46:47], v104 src0_sel:WORD_1
	v_pk_fma_f32 v[74:75], v[46:47], v[136:137], v[74:75]
	v_cvt_pk_f32_fp8_e32 v[64:65], v105
	v_pk_fma_f32 v[74:75], v[64:65], v[138:139], v[74:75]
	v_cvt_pk_f32_fp8_sdwa v[66:67], v105 src0_sel:WORD_1
	v_pk_fma_f32 v[74:75], v[66:67], v[140:141], v[74:75]
	v_cvt_pk_f32_fp8_e32 v[44:45], v106
	v_pk_fma_f32 v[74:75], v[44:45], v[142:143], v[74:75]
	v_cvt_pk_f32_fp8_sdwa v[46:47], v106 src0_sel:WORD_1
	v_pk_fma_f32 v[74:75], v[46:47], v[144:145], v[74:75]
	v_add_f32_dpp v72, v72, v72 quad_perm:[1,0,3,2] row_mask:0xf bank_mask:0xf bound_ctrl:1
	v_cvt_pk_f32_fp8_e32 v[64:65], v107
	v_pk_fma_f32 v[74:75], v[64:65], v[146:147], v[74:75]
	v_cvt_pk_f32_fp8_sdwa v[66:67], v107 src0_sel:WORD_1
	v_add_f32_dpp v72, v72, v72 quad_perm:[2,3,0,1] row_mask:0xf bank_mask:0xf bound_ctrl:1
	v_pk_fma_f32 v[74:75], v[66:67], v[148:149], v[74:75]
	v_cvt_pk_f32_fp8_e32 v[44:45], v108
	v_pk_fma_f32 v[74:75], v[44:45], v[150:151], v[74:75]
	v_add_f32_dpp v72, v72, v72 row_half_mirror row_mask:0xf bank_mask:0xf bound_ctrl:1
	v_cvt_pk_f32_fp8_sdwa v[46:47], v108 src0_sel:WORD_1
	v_pk_fma_f32 v[74:75], v[46:47], v[152:153], v[74:75]
	v_cvt_pk_f32_fp8_e32 v[64:65], v109
	v_add_f32_dpp v72, v72, v72 row_mirror row_mask:0xf bank_mask:0xf bound_ctrl:1
	v_pk_fma_f32 v[74:75], v[64:65], v[154:155], v[74:75]
	v_cvt_pk_f32_fp8_sdwa v[66:67], v109 src0_sel:WORD_1
	v_pk_fma_f32 v[74:75], v[66:67], v[156:157], v[74:75]
	v_add_f32_dpp v72, v72, v72 row_bcast:15 row_mask:0xa bank_mask:0xf
	v_cvt_pk_f32_fp8_e32 v[44:45], v110
	v_pk_fma_f32 v[74:75], v[44:45], v[158:159], v[74:75]
	v_cvt_pk_f32_fp8_sdwa v[46:47], v110 src0_sel:WORD_1
	v_add_f32_dpp v72, v72, v72 row_bcast:31 row_mask:0xc bank_mask:0xf
	v_pk_fma_f32 v[74:75], v[46:47], v[160:161], v[74:75]
	v_cvt_pk_f32_fp8_e32 v[64:65], v111
	v_readlane_b32 s48, v72, 63
	v_pk_fma_f32 v[74:75], v[64:65], v[162:163], v[74:75]
	v_cvt_pk_f32_fp8_sdwa v[66:67], v111 src0_sel:WORD_1
	v_pk_fma_f32 v[74:75], v[66:67], v[164:165], v[74:75]
	v_writelane_b32 v189, s48, 4
	s_nop 1
	v_readlane_b32 s100, v132, 12
	v_add_f32_e32 v74, v74, v75
	s_lshl_b32 s100, s100, 11
	s_add_u32 s100, s96, s100
	s_addc_u32 s101, s97, 0
	global_load_dwordx4 v[96:99], v254, s[100:101]
	global_load_dwordx4 v[100:103], v254, s[100:101] offset:1024
	s_waitcnt vmcnt(12)
	v_cvt_pk_f32_fp8_e32 v[44:45], v80
	v_pk_fma_f32 v[72:73], v[44:45], v[134:135], 0 op_sel_hi:[1,1,0]
	v_cvt_pk_f32_fp8_sdwa v[46:47], v80 src0_sel:WORD_1
	v_pk_fma_f32 v[72:73], v[46:47], v[136:137], v[72:73]
	v_cvt_pk_f32_fp8_e32 v[64:65], v81
	v_pk_fma_f32 v[72:73], v[64:65], v[138:139], v[72:73]
	v_cvt_pk_f32_fp8_sdwa v[66:67], v81 src0_sel:WORD_1
	v_pk_fma_f32 v[72:73], v[66:67], v[140:141], v[72:73]
	v_cvt_pk_f32_fp8_e32 v[44:45], v82
	v_pk_fma_f32 v[72:73], v[44:45], v[142:143], v[72:73]
	v_cvt_pk_f32_fp8_sdwa v[46:47], v82 src0_sel:WORD_1
	v_pk_fma_f32 v[72:73], v[46:47], v[144:145], v[72:73]
	v_add_f32_dpp v74, v74, v74 quad_perm:[1,0,3,2] row_mask:0xf bank_mask:0xf bound_ctrl:1
	v_cvt_pk_f32_fp8_e32 v[64:65], v83
	v_pk_fma_f32 v[72:73], v[64:65], v[146:147], v[72:73]
	v_cvt_pk_f32_fp8_sdwa v[66:67], v83 src0_sel:WORD_1
	v_add_f32_dpp v74, v74, v74 quad_perm:[2,3,0,1] row_mask:0xf bank_mask:0xf bound_ctrl:1
	v_pk_fma_f32 v[72:73], v[66:67], v[148:149], v[72:73]
	v_cvt_pk_f32_fp8_e32 v[44:45], v84
	v_pk_fma_f32 v[72:73], v[44:45], v[150:151], v[72:73]
	v_add_f32_dpp v74, v74, v74 row_half_mirror row_mask:0xf bank_mask:0xf bound_ctrl:1
	v_cvt_pk_f32_fp8_sdwa v[46:47], v84 src0_sel:WORD_1
	v_pk_fma_f32 v[72:73], v[46:47], v[152:153], v[72:73]
	v_cvt_pk_f32_fp8_e32 v[64:65], v85
	v_add_f32_dpp v74, v74, v74 row_mirror row_mask:0xf bank_mask:0xf bound_ctrl:1
	v_pk_fma_f32 v[72:73], v[64:65], v[154:155], v[72:73]
	v_cvt_pk_f32_fp8_sdwa v[66:67], v85 src0_sel:WORD_1
	v_pk_fma_f32 v[72:73], v[66:67], v[156:157], v[72:73]
	v_add_f32_dpp v74, v74, v74 row_bcast:15 row_mask:0xa bank_mask:0xf
	v_cvt_pk_f32_fp8_e32 v[44:45], v86
	v_pk_fma_f32 v[72:73], v[44:45], v[158:159], v[72:73]
	v_cvt_pk_f32_fp8_sdwa v[46:47], v86 src0_sel:WORD_1
	v_add_f32_dpp v74, v74, v74 row_bcast:31 row_mask:0xc bank_mask:0xf
	v_pk_fma_f32 v[72:73], v[46:47], v[160:161], v[72:73]
	v_cvt_pk_f32_fp8_e32 v[64:65], v87
	v_readlane_b32 s48, v74, 63
	v_pk_fma_f32 v[72:73], v[64:65], v[162:163], v[72:73]
	v_cvt_pk_f32_fp8_sdwa v[66:67], v87 src0_sel:WORD_1
	v_pk_fma_f32 v[72:73], v[66:67], v[164:165], v[72:73]
	v_writelane_b32 v189, s48, 5
	s_nop 1
	v_readlane_b32 s100, v132, 13
	v_add_f32_e32 v72, v72, v73
	s_lshl_b32 s100, s100, 11
	s_add_u32 s100, s96, s100
	s_addc_u32 s101, s97, 0
	global_load_dwordx4 v[104:107], v254, s[100:101]
	global_load_dwordx4 v[108:111], v254, s[100:101] offset:1024
	s_waitcnt vmcnt(12)
	v_cvt_pk_f32_fp8_e32 v[44:45], v88
	v_pk_fma_f32 v[74:75], v[44:45], v[134:135], 0 op_sel_hi:[1,1,0]
	v_cvt_pk_f32_fp8_sdwa v[46:47], v88 src0_sel:WORD_1
	v_pk_fma_f32 v[74:75], v[46:47], v[136:137], v[74:75]
	v_cvt_pk_f32_fp8_e32 v[64:65], v89
	v_pk_fma_f32 v[74:75], v[64:65], v[138:139], v[74:75]
	v_cvt_pk_f32_fp8_sdwa v[66:67], v89 src0_sel:WORD_1
	v_pk_fma_f32 v[74:75], v[66:67], v[140:141], v[74:75]
	v_cvt_pk_f32_fp8_e32 v[44:45], v90
	v_pk_fma_f32 v[74:75], v[44:45], v[142:143], v[74:75]
	v_cvt_pk_f32_fp8_sdwa v[46:47], v90 src0_sel:WORD_1
	v_pk_fma_f32 v[74:75], v[46:47], v[144:145], v[74:75]
	v_add_f32_dpp v72, v72, v72 quad_perm:[1,0,3,2] row_mask:0xf bank_mask:0xf bound_ctrl:1
	v_cvt_pk_f32_fp8_e32 v[64:65], v91
	v_pk_fma_f32 v[74:75], v[64:65], v[146:147], v[74:75]
	v_cvt_pk_f32_fp8_sdwa v[66:67], v91 src0_sel:WORD_1
	v_add_f32_dpp v72, v72, v72 quad_perm:[2,3,0,1] row_mask:0xf bank_mask:0xf bound_ctrl:1
	v_pk_fma_f32 v[74:75], v[66:67], v[148:149], v[74:75]
	v_cvt_pk_f32_fp8_e32 v[44:45], v92
	v_pk_fma_f32 v[74:75], v[44:45], v[150:151], v[74:75]
	v_add_f32_dpp v72, v72, v72 row_half_mirror row_mask:0xf bank_mask:0xf bound_ctrl:1
	v_cvt_pk_f32_fp8_sdwa v[46:47], v92 src0_sel:WORD_1
	v_pk_fma_f32 v[74:75], v[46:47], v[152:153], v[74:75]
	v_cvt_pk_f32_fp8_e32 v[64:65], v93
	v_add_f32_dpp v72, v72, v72 row_mirror row_mask:0xf bank_mask:0xf bound_ctrl:1
	v_pk_fma_f32 v[74:75], v[64:65], v[154:155], v[74:75]
	v_cvt_pk_f32_fp8_sdwa v[66:67], v93 src0_sel:WORD_1
	v_pk_fma_f32 v[74:75], v[66:67], v[156:157], v[74:75]
	v_add_f32_dpp v72, v72, v72 row_bcast:15 row_mask:0xa bank_mask:0xf
	v_cvt_pk_f32_fp8_e32 v[44:45], v94
	v_pk_fma_f32 v[74:75], v[44:45], v[158:159], v[74:75]
	v_cvt_pk_f32_fp8_sdwa v[46:47], v94 src0_sel:WORD_1
	v_add_f32_dpp v72, v72, v72 row_bcast:31 row_mask:0xc bank_mask:0xf
	v_pk_fma_f32 v[74:75], v[46:47], v[160:161], v[74:75]
	v_cvt_pk_f32_fp8_e32 v[64:65], v95
	v_readlane_b32 s48, v72, 63
	v_pk_fma_f32 v[74:75], v[64:65], v[162:163], v[74:75]
	v_cvt_pk_f32_fp8_sdwa v[66:67], v95 src0_sel:WORD_1
	v_pk_fma_f32 v[74:75], v[66:67], v[164:165], v[74:75]
	v_writelane_b32 v189, s48, 6
	s_nop 1
	v_readlane_b32 s100, v132, 14
	v_add_f32_e32 v74, v74, v75
	s_lshl_b32 s100, s100, 11
	s_add_u32 s100, s96, s100
	s_addc_u32 s101, s97, 0
	global_load_dwordx4 v[80:83], v254, s[100:101]
	global_load_dwordx4 v[84:87], v254, s[100:101] offset:1024
	s_waitcnt vmcnt(12)
	v_cvt_pk_f32_fp8_e32 v[44:45], v0
	v_pk_fma_f32 v[72:73], v[44:45], v[134:135], 0 op_sel_hi:[1,1,0]
	v_cvt_pk_f32_fp8_sdwa v[46:47], v0 src0_sel:WORD_1
	v_pk_fma_f32 v[72:73], v[46:47], v[136:137], v[72:73]
	v_cvt_pk_f32_fp8_e32 v[64:65], v1
	v_pk_fma_f32 v[72:73], v[64:65], v[138:139], v[72:73]
	v_cvt_pk_f32_fp8_sdwa v[66:67], v1 src0_sel:WORD_1
	v_pk_fma_f32 v[72:73], v[66:67], v[140:141], v[72:73]
	v_cvt_pk_f32_fp8_e32 v[44:45], v2
	v_pk_fma_f32 v[72:73], v[44:45], v[142:143], v[72:73]
	v_cvt_pk_f32_fp8_sdwa v[46:47], v2 src0_sel:WORD_1
	v_pk_fma_f32 v[72:73], v[46:47], v[144:145], v[72:73]
	v_add_f32_dpp v74, v74, v74 quad_perm:[1,0,3,2] row_mask:0xf bank_mask:0xf bound_ctrl:1
	v_cvt_pk_f32_fp8_e32 v[64:65], v3
	v_pk_fma_f32 v[72:73], v[64:65], v[146:147], v[72:73]
	v_cvt_pk_f32_fp8_sdwa v[66:67], v3 src0_sel:WORD_1
	v_add_f32_dpp v74, v74, v74 quad_perm:[2,3,0,1] row_mask:0xf bank_mask:0xf bound_ctrl:1
	v_pk_fma_f32 v[72:73], v[66:67], v[148:149], v[72:73]
	v_cvt_pk_f32_fp8_e32 v[44:45], v4
	v_pk_fma_f32 v[72:73], v[44:45], v[150:151], v[72:73]
	v_add_f32_dpp v74, v74, v74 row_half_mirror row_mask:0xf bank_mask:0xf bound_ctrl:1
	v_cvt_pk_f32_fp8_sdwa v[46:47], v4 src0_sel:WORD_1
	v_pk_fma_f32 v[72:73], v[46:47], v[152:153], v[72:73]
	v_cvt_pk_f32_fp8_e32 v[64:65], v5
	v_add_f32_dpp v74, v74, v74 row_mirror row_mask:0xf bank_mask:0xf bound_ctrl:1
	v_pk_fma_f32 v[72:73], v[64:65], v[154:155], v[72:73]
	v_cvt_pk_f32_fp8_sdwa v[66:67], v5 src0_sel:WORD_1
	v_pk_fma_f32 v[72:73], v[66:67], v[156:157], v[72:73]
	v_add_f32_dpp v74, v74, v74 row_bcast:15 row_mask:0xa bank_mask:0xf
	v_cvt_pk_f32_fp8_e32 v[44:45], v6
	v_pk_fma_f32 v[72:73], v[44:45], v[158:159], v[72:73]
	v_cvt_pk_f32_fp8_sdwa v[46:47], v6 src0_sel:WORD_1
	v_add_f32_dpp v74, v74, v74 row_bcast:31 row_mask:0xc bank_mask:0xf
	v_pk_fma_f32 v[72:73], v[46:47], v[160:161], v[72:73]
	v_cvt_pk_f32_fp8_e32 v[64:65], v7
	v_readlane_b32 s48, v74, 63
	v_pk_fma_f32 v[72:73], v[64:65], v[162:163], v[72:73]
	v_cvt_pk_f32_fp8_sdwa v[66:67], v7 src0_sel:WORD_1
	v_pk_fma_f32 v[72:73], v[66:67], v[164:165], v[72:73]
	v_writelane_b32 v189, s48, 7
	s_nop 1
	v_readlane_b32 s100, v132, 15
	v_add_f32_e32 v72, v72, v73
	s_lshl_b32 s100, s100, 11
	s_add_u32 s100, s96, s100
	s_addc_u32 s101, s97, 0
	global_load_dwordx4 v[88:91], v254, s[100:101]
	global_load_dwordx4 v[92:95], v254, s[100:101] offset:1024
	s_waitcnt vmcnt(12)
	v_cvt_pk_f32_fp8_e32 v[44:45], v8
	v_pk_fma_f32 v[74:75], v[44:45], v[134:135], 0 op_sel_hi:[1,1,0]
	v_cvt_pk_f32_fp8_sdwa v[46:47], v8 src0_sel:WORD_1
	v_pk_fma_f32 v[74:75], v[46:47], v[136:137], v[74:75]
	v_cvt_pk_f32_fp8_e32 v[64:65], v9
	v_pk_fma_f32 v[74:75], v[64:65], v[138:139], v[74:75]
	v_cvt_pk_f32_fp8_sdwa v[66:67], v9 src0_sel:WORD_1
	v_pk_fma_f32 v[74:75], v[66:67], v[140:141], v[74:75]
	v_cvt_pk_f32_fp8_e32 v[44:45], v10
	v_pk_fma_f32 v[74:75], v[44:45], v[142:143], v[74:75]
	v_cvt_pk_f32_fp8_sdwa v[46:47], v10 src0_sel:WORD_1
	v_pk_fma_f32 v[74:75], v[46:47], v[144:145], v[74:75]
	v_add_f32_dpp v72, v72, v72 quad_perm:[1,0,3,2] row_mask:0xf bank_mask:0xf bound_ctrl:1
	v_cvt_pk_f32_fp8_e32 v[64:65], v11
	v_pk_fma_f32 v[74:75], v[64:65], v[146:147], v[74:75]
	v_cvt_pk_f32_fp8_sdwa v[66:67], v11 src0_sel:WORD_1
	v_add_f32_dpp v72, v72, v72 quad_perm:[2,3,0,1] row_mask:0xf bank_mask:0xf bound_ctrl:1
	v_pk_fma_f32 v[74:75], v[66:67], v[148:149], v[74:75]
	v_cvt_pk_f32_fp8_e32 v[44:45], v12
	v_pk_fma_f32 v[74:75], v[44:45], v[150:151], v[74:75]
	v_add_f32_dpp v72, v72, v72 row_half_mirror row_mask:0xf bank_mask:0xf bound_ctrl:1
	v_cvt_pk_f32_fp8_sdwa v[46:47], v12 src0_sel:WORD_1
	v_pk_fma_f32 v[74:75], v[46:47], v[152:153], v[74:75]
	v_cvt_pk_f32_fp8_e32 v[64:65], v13
	v_add_f32_dpp v72, v72, v72 row_mirror row_mask:0xf bank_mask:0xf bound_ctrl:1
	v_pk_fma_f32 v[74:75], v[64:65], v[154:155], v[74:75]
	v_cvt_pk_f32_fp8_sdwa v[66:67], v13 src0_sel:WORD_1
	v_pk_fma_f32 v[74:75], v[66:67], v[156:157], v[74:75]
	v_add_f32_dpp v72, v72, v72 row_bcast:15 row_mask:0xa bank_mask:0xf
	v_cvt_pk_f32_fp8_e32 v[44:45], v14
	v_pk_fma_f32 v[74:75], v[44:45], v[158:159], v[74:75]
	v_cvt_pk_f32_fp8_sdwa v[46:47], v14 src0_sel:WORD_1
	v_add_f32_dpp v72, v72, v72 row_bcast:31 row_mask:0xc bank_mask:0xf
	v_pk_fma_f32 v[74:75], v[46:47], v[160:161], v[74:75]
	v_cvt_pk_f32_fp8_e32 v[64:65], v15
	v_readlane_b32 s48, v72, 63
	v_pk_fma_f32 v[74:75], v[64:65], v[162:163], v[74:75]
	v_cvt_pk_f32_fp8_sdwa v[66:67], v15 src0_sel:WORD_1
	v_pk_fma_f32 v[74:75], v[66:67], v[164:165], v[74:75]
	v_writelane_b32 v189, s48, 8
	s_nop 1
	v_readlane_b32 s100, v132, 0
	v_add_f32_e32 v74, v74, v75
	s_lshl_b32 s100, s100, 11
	s_add_u32 s100, s98, s100
	s_addc_u32 s101, s99, 0
	global_load_dwordx4 v[192:195], v254, s[100:101]
	global_load_dwordx4 v[196:199], v254, s[100:101] offset:1024
	s_waitcnt vmcnt(12)
	v_cvt_pk_f32_fp8_e32 v[44:45], v16
	v_pk_fma_f32 v[72:73], v[44:45], v[134:135], 0 op_sel_hi:[1,1,0]
	v_cvt_pk_f32_fp8_sdwa v[46:47], v16 src0_sel:WORD_1
	v_pk_fma_f32 v[72:73], v[46:47], v[136:137], v[72:73]
	v_cvt_pk_f32_fp8_e32 v[64:65], v17
	v_pk_fma_f32 v[72:73], v[64:65], v[138:139], v[72:73]
	v_cvt_pk_f32_fp8_sdwa v[66:67], v17 src0_sel:WORD_1
	v_pk_fma_f32 v[72:73], v[66:67], v[140:141], v[72:73]
	v_cvt_pk_f32_fp8_e32 v[44:45], v18
	v_pk_fma_f32 v[72:73], v[44:45], v[142:143], v[72:73]
	v_cvt_pk_f32_fp8_sdwa v[46:47], v18 src0_sel:WORD_1
	v_pk_fma_f32 v[72:73], v[46:47], v[144:145], v[72:73]
	v_add_f32_dpp v74, v74, v74 quad_perm:[1,0,3,2] row_mask:0xf bank_mask:0xf bound_ctrl:1
	v_cvt_pk_f32_fp8_e32 v[64:65], v19
	v_pk_fma_f32 v[72:73], v[64:65], v[146:147], v[72:73]
	v_cvt_pk_f32_fp8_sdwa v[66:67], v19 src0_sel:WORD_1
	v_add_f32_dpp v74, v74, v74 quad_perm:[2,3,0,1] row_mask:0xf bank_mask:0xf bound_ctrl:1
	v_pk_fma_f32 v[72:73], v[66:67], v[148:149], v[72:73]
	v_cvt_pk_f32_fp8_e32 v[44:45], v20
	v_pk_fma_f32 v[72:73], v[44:45], v[150:151], v[72:73]
	v_add_f32_dpp v74, v74, v74 row_half_mirror row_mask:0xf bank_mask:0xf bound_ctrl:1
	v_cvt_pk_f32_fp8_sdwa v[46:47], v20 src0_sel:WORD_1
	v_pk_fma_f32 v[72:73], v[46:47], v[152:153], v[72:73]
	v_cvt_pk_f32_fp8_e32 v[64:65], v21
	v_add_f32_dpp v74, v74, v74 row_mirror row_mask:0xf bank_mask:0xf bound_ctrl:1
	v_pk_fma_f32 v[72:73], v[64:65], v[154:155], v[72:73]
	v_cvt_pk_f32_fp8_sdwa v[66:67], v21 src0_sel:WORD_1
	v_pk_fma_f32 v[72:73], v[66:67], v[156:157], v[72:73]
	v_add_f32_dpp v74, v74, v74 row_bcast:15 row_mask:0xa bank_mask:0xf
	v_cvt_pk_f32_fp8_e32 v[44:45], v22
	v_pk_fma_f32 v[72:73], v[44:45], v[158:159], v[72:73]
	v_cvt_pk_f32_fp8_sdwa v[46:47], v22 src0_sel:WORD_1
	v_add_f32_dpp v74, v74, v74 row_bcast:31 row_mask:0xc bank_mask:0xf
	v_pk_fma_f32 v[72:73], v[46:47], v[160:161], v[72:73]
	v_cvt_pk_f32_fp8_e32 v[64:65], v23
	v_readlane_b32 s48, v74, 63
	v_pk_fma_f32 v[72:73], v[64:65], v[162:163], v[72:73]
	v_cvt_pk_f32_fp8_sdwa v[66:67], v23 src0_sel:WORD_1
	v_pk_fma_f32 v[72:73], v[66:67], v[164:165], v[72:73]
	v_writelane_b32 v189, s48, 9
	s_nop 1
	v_readlane_b32 s100, v132, 1
	v_add_f32_e32 v72, v72, v73
	s_lshl_b32 s100, s100, 11
	s_add_u32 s100, s98, s100
	s_addc_u32 s101, s99, 0
	global_load_dwordx4 v[200:203], v254, s[100:101]
	global_load_dwordx4 v[204:207], v254, s[100:101] offset:1024
	s_waitcnt vmcnt(12)
	v_cvt_pk_f32_fp8_e32 v[44:45], v24
	v_pk_fma_f32 v[74:75], v[44:45], v[134:135], 0 op_sel_hi:[1,1,0]
	v_cvt_pk_f32_fp8_sdwa v[46:47], v24 src0_sel:WORD_1
	v_pk_fma_f32 v[74:75], v[46:47], v[136:137], v[74:75]
	v_cvt_pk_f32_fp8_e32 v[64:65], v25
	v_pk_fma_f32 v[74:75], v[64:65], v[138:139], v[74:75]
	v_cvt_pk_f32_fp8_sdwa v[66:67], v25 src0_sel:WORD_1
	v_pk_fma_f32 v[74:75], v[66:67], v[140:141], v[74:75]
	v_cvt_pk_f32_fp8_e32 v[44:45], v26
	v_pk_fma_f32 v[74:75], v[44:45], v[142:143], v[74:75]
	v_cvt_pk_f32_fp8_sdwa v[46:47], v26 src0_sel:WORD_1
	v_pk_fma_f32 v[74:75], v[46:47], v[144:145], v[74:75]
	v_add_f32_dpp v72, v72, v72 quad_perm:[1,0,3,2] row_mask:0xf bank_mask:0xf bound_ctrl:1
	v_cvt_pk_f32_fp8_e32 v[64:65], v27
	v_pk_fma_f32 v[74:75], v[64:65], v[146:147], v[74:75]
	v_cvt_pk_f32_fp8_sdwa v[66:67], v27 src0_sel:WORD_1
	v_add_f32_dpp v72, v72, v72 quad_perm:[2,3,0,1] row_mask:0xf bank_mask:0xf bound_ctrl:1
	v_pk_fma_f32 v[74:75], v[66:67], v[148:149], v[74:75]
	v_cvt_pk_f32_fp8_e32 v[44:45], v28
	v_pk_fma_f32 v[74:75], v[44:45], v[150:151], v[74:75]
	v_add_f32_dpp v72, v72, v72 row_half_mirror row_mask:0xf bank_mask:0xf bound_ctrl:1
	v_cvt_pk_f32_fp8_sdwa v[46:47], v28 src0_sel:WORD_1
	v_pk_fma_f32 v[74:75], v[46:47], v[152:153], v[74:75]
	v_cvt_pk_f32_fp8_e32 v[64:65], v29
	v_add_f32_dpp v72, v72, v72 row_mirror row_mask:0xf bank_mask:0xf bound_ctrl:1
	v_pk_fma_f32 v[74:75], v[64:65], v[154:155], v[74:75]
	v_cvt_pk_f32_fp8_sdwa v[66:67], v29 src0_sel:WORD_1
	v_pk_fma_f32 v[74:75], v[66:67], v[156:157], v[74:75]
	v_add_f32_dpp v72, v72, v72 row_bcast:15 row_mask:0xa bank_mask:0xf
	v_cvt_pk_f32_fp8_e32 v[44:45], v30
	v_pk_fma_f32 v[74:75], v[44:45], v[158:159], v[74:75]
	v_cvt_pk_f32_fp8_sdwa v[46:47], v30 src0_sel:WORD_1
	v_add_f32_dpp v72, v72, v72 row_bcast:31 row_mask:0xc bank_mask:0xf
	v_pk_fma_f32 v[74:75], v[46:47], v[160:161], v[74:75]
	v_cvt_pk_f32_fp8_e32 v[64:65], v31
	v_readlane_b32 s48, v72, 63
	v_pk_fma_f32 v[74:75], v[64:65], v[162:163], v[74:75]
	v_cvt_pk_f32_fp8_sdwa v[66:67], v31 src0_sel:WORD_1
	v_pk_fma_f32 v[74:75], v[66:67], v[164:165], v[74:75]
	v_writelane_b32 v189, s48, 10
	s_nop 1
	v_readlane_b32 s100, v132, 2
	v_add_f32_e32 v74, v74, v75
	s_lshl_b32 s100, s100, 11
	s_add_u32 s100, s98, s100
	s_addc_u32 s101, s99, 0
	global_load_dwordx4 v[208:211], v254, s[100:101]
	global_load_dwordx4 v[212:215], v254, s[100:101] offset:1024
	s_waitcnt vmcnt(12)
	v_cvt_pk_f32_fp8_e32 v[44:45], v96
	v_pk_fma_f32 v[72:73], v[44:45], v[134:135], 0 op_sel_hi:[1,1,0]
	v_cvt_pk_f32_fp8_sdwa v[46:47], v96 src0_sel:WORD_1
	v_pk_fma_f32 v[72:73], v[46:47], v[136:137], v[72:73]
	v_cvt_pk_f32_fp8_e32 v[64:65], v97
	v_pk_fma_f32 v[72:73], v[64:65], v[138:139], v[72:73]
	v_cvt_pk_f32_fp8_sdwa v[66:67], v97 src0_sel:WORD_1
	v_pk_fma_f32 v[72:73], v[66:67], v[140:141], v[72:73]
	v_cvt_pk_f32_fp8_e32 v[44:45], v98
	v_pk_fma_f32 v[72:73], v[44:45], v[142:143], v[72:73]
	v_cvt_pk_f32_fp8_sdwa v[46:47], v98 src0_sel:WORD_1
	v_pk_fma_f32 v[72:73], v[46:47], v[144:145], v[72:73]
	v_add_f32_dpp v74, v74, v74 quad_perm:[1,0,3,2] row_mask:0xf bank_mask:0xf bound_ctrl:1
	v_cvt_pk_f32_fp8_e32 v[64:65], v99
	v_pk_fma_f32 v[72:73], v[64:65], v[146:147], v[72:73]
	v_cvt_pk_f32_fp8_sdwa v[66:67], v99 src0_sel:WORD_1
	v_add_f32_dpp v74, v74, v74 quad_perm:[2,3,0,1] row_mask:0xf bank_mask:0xf bound_ctrl:1
	v_pk_fma_f32 v[72:73], v[66:67], v[148:149], v[72:73]
	v_cvt_pk_f32_fp8_e32 v[44:45], v100
	v_pk_fma_f32 v[72:73], v[44:45], v[150:151], v[72:73]
	v_add_f32_dpp v74, v74, v74 row_half_mirror row_mask:0xf bank_mask:0xf bound_ctrl:1
	v_cvt_pk_f32_fp8_sdwa v[46:47], v100 src0_sel:WORD_1
	v_pk_fma_f32 v[72:73], v[46:47], v[152:153], v[72:73]
	v_cvt_pk_f32_fp8_e32 v[64:65], v101
	v_add_f32_dpp v74, v74, v74 row_mirror row_mask:0xf bank_mask:0xf bound_ctrl:1
	v_pk_fma_f32 v[72:73], v[64:65], v[154:155], v[72:73]
	v_cvt_pk_f32_fp8_sdwa v[66:67], v101 src0_sel:WORD_1
	v_pk_fma_f32 v[72:73], v[66:67], v[156:157], v[72:73]
	v_add_f32_dpp v74, v74, v74 row_bcast:15 row_mask:0xa bank_mask:0xf
	v_cvt_pk_f32_fp8_e32 v[44:45], v102
	v_pk_fma_f32 v[72:73], v[44:45], v[158:159], v[72:73]
	v_cvt_pk_f32_fp8_sdwa v[46:47], v102 src0_sel:WORD_1
	v_add_f32_dpp v74, v74, v74 row_bcast:31 row_mask:0xc bank_mask:0xf
	v_pk_fma_f32 v[72:73], v[46:47], v[160:161], v[72:73]
	v_cvt_pk_f32_fp8_e32 v[64:65], v103
	v_readlane_b32 s48, v74, 63
	v_pk_fma_f32 v[72:73], v[64:65], v[162:163], v[72:73]
	v_cvt_pk_f32_fp8_sdwa v[66:67], v103 src0_sel:WORD_1
	v_pk_fma_f32 v[72:73], v[66:67], v[164:165], v[72:73]
	v_writelane_b32 v189, s48, 11
	s_nop 1
	v_readlane_b32 s100, v132, 3
	v_add_f32_e32 v72, v72, v73
	s_lshl_b32 s100, s100, 11
	s_add_u32 s100, s98, s100
	s_addc_u32 s101, s99, 0
	global_load_dwordx4 v[216:219], v254, s[100:101]
	global_load_dwordx4 v[220:223], v254, s[100:101] offset:1024
	s_waitcnt vmcnt(12)
	v_cvt_pk_f32_fp8_e32 v[44:45], v104
	v_pk_fma_f32 v[74:75], v[44:45], v[134:135], 0 op_sel_hi:[1,1,0]
	v_cvt_pk_f32_fp8_sdwa v[46:47], v104 src0_sel:WORD_1
	v_pk_fma_f32 v[74:75], v[46:47], v[136:137], v[74:75]
	v_cvt_pk_f32_fp8_e32 v[64:65], v105
	v_pk_fma_f32 v[74:75], v[64:65], v[138:139], v[74:75]
	v_cvt_pk_f32_fp8_sdwa v[66:67], v105 src0_sel:WORD_1
	v_pk_fma_f32 v[74:75], v[66:67], v[140:141], v[74:75]
	v_cvt_pk_f32_fp8_e32 v[44:45], v106
	v_pk_fma_f32 v[74:75], v[44:45], v[142:143], v[74:75]
	v_cvt_pk_f32_fp8_sdwa v[46:47], v106 src0_sel:WORD_1
	v_pk_fma_f32 v[74:75], v[46:47], v[144:145], v[74:75]
	v_add_f32_dpp v72, v72, v72 quad_perm:[1,0,3,2] row_mask:0xf bank_mask:0xf bound_ctrl:1
	v_cvt_pk_f32_fp8_e32 v[64:65], v107
	v_pk_fma_f32 v[74:75], v[64:65], v[146:147], v[74:75]
	v_cvt_pk_f32_fp8_sdwa v[66:67], v107 src0_sel:WORD_1
	v_add_f32_dpp v72, v72, v72 quad_perm:[2,3,0,1] row_mask:0xf bank_mask:0xf bound_ctrl:1
	v_pk_fma_f32 v[74:75], v[66:67], v[148:149], v[74:75]
	v_cvt_pk_f32_fp8_e32 v[44:45], v108
	v_pk_fma_f32 v[74:75], v[44:45], v[150:151], v[74:75]
	v_add_f32_dpp v72, v72, v72 row_half_mirror row_mask:0xf bank_mask:0xf bound_ctrl:1
	v_cvt_pk_f32_fp8_sdwa v[46:47], v108 src0_sel:WORD_1
	v_pk_fma_f32 v[74:75], v[46:47], v[152:153], v[74:75]
	v_cvt_pk_f32_fp8_e32 v[64:65], v109
	v_add_f32_dpp v72, v72, v72 row_mirror row_mask:0xf bank_mask:0xf bound_ctrl:1
	v_pk_fma_f32 v[74:75], v[64:65], v[154:155], v[74:75]
	v_cvt_pk_f32_fp8_sdwa v[66:67], v109 src0_sel:WORD_1
	v_pk_fma_f32 v[74:75], v[66:67], v[156:157], v[74:75]
	v_add_f32_dpp v72, v72, v72 row_bcast:15 row_mask:0xa bank_mask:0xf
	v_cvt_pk_f32_fp8_e32 v[44:45], v110
	v_pk_fma_f32 v[74:75], v[44:45], v[158:159], v[74:75]
	v_cvt_pk_f32_fp8_sdwa v[46:47], v110 src0_sel:WORD_1
	v_add_f32_dpp v72, v72, v72 row_bcast:31 row_mask:0xc bank_mask:0xf
	v_pk_fma_f32 v[74:75], v[46:47], v[160:161], v[74:75]
	v_cvt_pk_f32_fp8_e32 v[64:65], v111
	v_readlane_b32 s48, v72, 63
	v_pk_fma_f32 v[74:75], v[64:65], v[162:163], v[74:75]
	v_cvt_pk_f32_fp8_sdwa v[66:67], v111 src0_sel:WORD_1
	v_pk_fma_f32 v[74:75], v[66:67], v[164:165], v[74:75]
	v_writelane_b32 v189, s48, 12
	s_nop 1
	v_readlane_b32 s100, v132, 4
	v_add_f32_e32 v74, v74, v75
	s_lshl_b32 s100, s100, 11
	s_add_u32 s100, s98, s100
	s_addc_u32 s101, s99, 0
	global_load_dwordx4 v[224:227], v254, s[100:101]
	global_load_dwordx4 v[228:231], v254, s[100:101] offset:1024
	s_waitcnt vmcnt(12)
	v_cvt_pk_f32_fp8_e32 v[44:45], v80
	v_pk_fma_f32 v[72:73], v[44:45], v[134:135], 0 op_sel_hi:[1,1,0]
	v_cvt_pk_f32_fp8_sdwa v[46:47], v80 src0_sel:WORD_1
	v_pk_fma_f32 v[72:73], v[46:47], v[136:137], v[72:73]
	v_cvt_pk_f32_fp8_e32 v[64:65], v81
	v_pk_fma_f32 v[72:73], v[64:65], v[138:139], v[72:73]
	v_cvt_pk_f32_fp8_sdwa v[66:67], v81 src0_sel:WORD_1
	v_pk_fma_f32 v[72:73], v[66:67], v[140:141], v[72:73]
	v_cvt_pk_f32_fp8_e32 v[44:45], v82
	v_pk_fma_f32 v[72:73], v[44:45], v[142:143], v[72:73]
	v_cvt_pk_f32_fp8_sdwa v[46:47], v82 src0_sel:WORD_1
	v_pk_fma_f32 v[72:73], v[46:47], v[144:145], v[72:73]
	v_add_f32_dpp v74, v74, v74 quad_perm:[1,0,3,2] row_mask:0xf bank_mask:0xf bound_ctrl:1
	v_cvt_pk_f32_fp8_e32 v[64:65], v83
	v_pk_fma_f32 v[72:73], v[64:65], v[146:147], v[72:73]
	v_cvt_pk_f32_fp8_sdwa v[66:67], v83 src0_sel:WORD_1
	v_add_f32_dpp v74, v74, v74 quad_perm:[2,3,0,1] row_mask:0xf bank_mask:0xf bound_ctrl:1
	v_pk_fma_f32 v[72:73], v[66:67], v[148:149], v[72:73]
	v_cvt_pk_f32_fp8_e32 v[44:45], v84
	v_pk_fma_f32 v[72:73], v[44:45], v[150:151], v[72:73]
	v_add_f32_dpp v74, v74, v74 row_half_mirror row_mask:0xf bank_mask:0xf bound_ctrl:1
	v_cvt_pk_f32_fp8_sdwa v[46:47], v84 src0_sel:WORD_1
	v_pk_fma_f32 v[72:73], v[46:47], v[152:153], v[72:73]
	v_cvt_pk_f32_fp8_e32 v[64:65], v85
	v_add_f32_dpp v74, v74, v74 row_mirror row_mask:0xf bank_mask:0xf bound_ctrl:1
	v_pk_fma_f32 v[72:73], v[64:65], v[154:155], v[72:73]
	v_cvt_pk_f32_fp8_sdwa v[66:67], v85 src0_sel:WORD_1
	v_pk_fma_f32 v[72:73], v[66:67], v[156:157], v[72:73]
	v_add_f32_dpp v74, v74, v74 row_bcast:15 row_mask:0xa bank_mask:0xf
	v_cvt_pk_f32_fp8_e32 v[44:45], v86
	v_pk_fma_f32 v[72:73], v[44:45], v[158:159], v[72:73]
	v_cvt_pk_f32_fp8_sdwa v[46:47], v86 src0_sel:WORD_1
	v_add_f32_dpp v74, v74, v74 row_bcast:31 row_mask:0xc bank_mask:0xf
	v_pk_fma_f32 v[72:73], v[46:47], v[160:161], v[72:73]
	v_cvt_pk_f32_fp8_e32 v[64:65], v87
	v_readlane_b32 s48, v74, 63
	v_pk_fma_f32 v[72:73], v[64:65], v[162:163], v[72:73]
	v_cvt_pk_f32_fp8_sdwa v[66:67], v87 src0_sel:WORD_1
	v_pk_fma_f32 v[72:73], v[66:67], v[164:165], v[72:73]
	v_writelane_b32 v189, s48, 13
	s_nop 1
	v_readlane_b32 s100, v132, 5
	v_add_f32_e32 v72, v72, v73
	s_lshl_b32 s100, s100, 11
	s_add_u32 s100, s98, s100
	s_addc_u32 s101, s99, 0
	global_load_dwordx4 v[232:235], v254, s[100:101]
	global_load_dwordx4 v[236:239], v254, s[100:101] offset:1024
	s_waitcnt vmcnt(12)
	v_cvt_pk_f32_fp8_e32 v[44:45], v88
	v_pk_fma_f32 v[74:75], v[44:45], v[134:135], 0 op_sel_hi:[1,1,0]
	v_cvt_pk_f32_fp8_sdwa v[46:47], v88 src0_sel:WORD_1
	v_pk_fma_f32 v[74:75], v[46:47], v[136:137], v[74:75]
	v_cvt_pk_f32_fp8_e32 v[64:65], v89
	v_pk_fma_f32 v[74:75], v[64:65], v[138:139], v[74:75]
	v_cvt_pk_f32_fp8_sdwa v[66:67], v89 src0_sel:WORD_1
	v_pk_fma_f32 v[74:75], v[66:67], v[140:141], v[74:75]
	v_cvt_pk_f32_fp8_e32 v[44:45], v90
	v_pk_fma_f32 v[74:75], v[44:45], v[142:143], v[74:75]
	v_cvt_pk_f32_fp8_sdwa v[46:47], v90 src0_sel:WORD_1
	v_pk_fma_f32 v[74:75], v[46:47], v[144:145], v[74:75]
	v_add_f32_dpp v72, v72, v72 quad_perm:[1,0,3,2] row_mask:0xf bank_mask:0xf bound_ctrl:1
	v_cvt_pk_f32_fp8_e32 v[64:65], v91
	v_pk_fma_f32 v[74:75], v[64:65], v[146:147], v[74:75]
	v_cvt_pk_f32_fp8_sdwa v[66:67], v91 src0_sel:WORD_1
	v_add_f32_dpp v72, v72, v72 quad_perm:[2,3,0,1] row_mask:0xf bank_mask:0xf bound_ctrl:1
	v_pk_fma_f32 v[74:75], v[66:67], v[148:149], v[74:75]
	v_cvt_pk_f32_fp8_e32 v[44:45], v92
	v_pk_fma_f32 v[74:75], v[44:45], v[150:151], v[74:75]
	v_add_f32_dpp v72, v72, v72 row_half_mirror row_mask:0xf bank_mask:0xf bound_ctrl:1
	v_cvt_pk_f32_fp8_sdwa v[46:47], v92 src0_sel:WORD_1
	v_pk_fma_f32 v[74:75], v[46:47], v[152:153], v[74:75]
	v_cvt_pk_f32_fp8_e32 v[64:65], v93
	v_add_f32_dpp v72, v72, v72 row_mirror row_mask:0xf bank_mask:0xf bound_ctrl:1
	v_pk_fma_f32 v[74:75], v[64:65], v[154:155], v[74:75]
	v_cvt_pk_f32_fp8_sdwa v[66:67], v93 src0_sel:WORD_1
	v_pk_fma_f32 v[74:75], v[66:67], v[156:157], v[74:75]
	v_add_f32_dpp v72, v72, v72 row_bcast:15 row_mask:0xa bank_mask:0xf
	v_cvt_pk_f32_fp8_e32 v[44:45], v94
	v_pk_fma_f32 v[74:75], v[44:45], v[158:159], v[74:75]
	v_cvt_pk_f32_fp8_sdwa v[46:47], v94 src0_sel:WORD_1
	v_add_f32_dpp v72, v72, v72 row_bcast:31 row_mask:0xc bank_mask:0xf
	v_pk_fma_f32 v[74:75], v[46:47], v[160:161], v[74:75]
	v_cvt_pk_f32_fp8_e32 v[64:65], v95
	v_readlane_b32 s48, v72, 63
	v_pk_fma_f32 v[74:75], v[64:65], v[162:163], v[74:75]
	v_cvt_pk_f32_fp8_sdwa v[66:67], v95 src0_sel:WORD_1
	v_pk_fma_f32 v[74:75], v[66:67], v[164:165], v[74:75]
	v_writelane_b32 v189, s48, 14
	s_nop 1
	v_add_f32_e32 v74, v74, v75
	s_nop 0
	s_nop 0
	v_add_f32_dpp v74, v74, v74 quad_perm:[1,0,3,2] row_mask:0xf bank_mask:0xf bound_ctrl:1
	s_nop 0
	s_nop 0
	v_add_f32_dpp v74, v74, v74 quad_perm:[2,3,0,1] row_mask:0xf bank_mask:0xf bound_ctrl:1
	s_nop 0
	s_nop 0
	v_add_f32_dpp v74, v74, v74 row_half_mirror row_mask:0xf bank_mask:0xf bound_ctrl:1
	s_nop 0
	s_nop 0
	v_add_f32_dpp v74, v74, v74 row_mirror row_mask:0xf bank_mask:0xf bound_ctrl:1
	s_nop 0
	s_nop 0
	v_add_f32_dpp v74, v74, v74 row_bcast:15 row_mask:0xa bank_mask:0xf
	s_nop 0
	s_nop 0
	v_add_f32_dpp v74, v74, v74 row_bcast:31 row_mask:0xc bank_mask:0xf
	s_nop 0
	v_readlane_b32 s48, v74, 63
	v_mul_f32_e32 v74, v179, v188
	v_mul_f32_e32 v74, 0.5, v74
	v_writelane_b32 v189, s48, 15
	v_mul_f32_e32 v44, v187, v189
	v_mul_f32_e32 v45, 0x3f3504f3, v44
	v_fma_f32 v46, |v45|, s55, v183
	v_fma_f32 v46, |v45|, v46, s56
	v_fma_f32 v46, |v45|, v46, s57
	v_fma_f32 v46, |v45|, v46, s58
	v_fma_f32 v46, |v45|, v46, s59
	v_fma_f32 v46, |v45|, v46, s60
	v_fma_f32 v46, |v45|, v46, |v45|
	v_mul_f32_e32 v47, 0xbfb8aa3b, v46
	v_fma_f32 v64, v46, s61, -v47
	v_rndne_f32_e32 v65, v47
	v_fmac_f32_e32 v64, 0xb2a5705f, v46
	v_sub_f32_e32 v47, v47, v65
	v_add_f32_e32 v47, v47, v64
	v_exp_f32_e32 v47, v47
	v_cmp_nlt_f32_e32 vcc, s62, v46
	v_cvt_i32_f32_e32 v64, v65
	v_ldexp_f32 v47, v47, v64
	v_cndmask_b32_e32 v47, 0, v47, vcc
	v_cmp_ngt_f32_e32 vcc, s63, v46
	v_mul_f32_e32 v64, v45, v45
	v_fmamk_f32 v65, v64, 0xba1345e1, v112
	v_fmaak_f32 v65, v64, v65, 0xbcdac9b8
	v_cndmask_b32_e32 v46, v184, v47, vcc
	v_fmaak_f32 v65, v64, v65, 0x3de703be
	v_fmaak_f32 v65, v64, v65, 0xbec09330
	v_cmp_nlt_f32_e64 vcc, |v45|, 1.0
	v_fmaak_f32 v64, v64, v65, 0x3e0375d0
	v_sub_f32_e32 v66, 1.0, v46
	v_fma_f32 v67, |v45|, v64, |v45|
	v_cndmask_b32_e32 v66, v67, v66, vcc
	v_bfi_b32 v67, s64, v66, v45
	v_mul_f32_e32 v74, v44, v74
	v_add_f32_e32 v67, 1.0, v67
	v_mul_f32_e32 v74, v74, v67
	s_nop 1
	v_readlane_b32 s100, v132, 6
	v_readlane_b32 s48, v74, 0
	s_lshl_b32 s100, s100, 11
	s_add_u32 s100, s98, s100
	s_addc_u32 s101, s99, 0
	global_load_dwordx4 v[242:245], v254, s[100:101]
	global_load_dwordx4 v[246:249], v254, s[100:101] offset:1024
	s_waitcnt vmcnt(12)
	v_mov_b32_e32 v72, s48
	v_cvt_pk_f32_fp8_e32 v[44:45], v192
	v_cvt_pk_f32_fp8_sdwa v[46:47], v192 src0_sel:WORD_1
	v_cvt_pk_f32_fp8_e32 v[64:65], v193
	v_cvt_pk_f32_fp8_sdwa v[66:67], v193 src0_sel:WORD_1
	v_pk_fma_f32 v[68:69], v[72:73], v[44:45], 0 op_sel_hi:[0,1,0]
	v_pk_fma_f32 v[70:71], v[72:73], v[46:47], 0 op_sel_hi:[0,1,0]
	v_pk_fma_f32 v[60:61], v[72:73], v[64:65], 0 op_sel_hi:[0,1,0]
	v_pk_fma_f32 v[62:63], v[72:73], v[66:67], 0 op_sel_hi:[0,1,0]
	v_cvt_pk_f32_fp8_e32 v[44:45], v194
	v_cvt_pk_f32_fp8_sdwa v[46:47], v194 src0_sel:WORD_1
	v_cvt_pk_f32_fp8_e32 v[64:65], v195
	v_cvt_pk_f32_fp8_sdwa v[66:67], v195 src0_sel:WORD_1
	v_pk_fma_f32 v[56:57], v[72:73], v[44:45], 0 op_sel_hi:[0,1,0]
	v_pk_fma_f32 v[58:59], v[72:73], v[46:47], 0 op_sel_hi:[0,1,0]
	v_pk_fma_f32 v[52:53], v[72:73], v[64:65], 0 op_sel_hi:[0,1,0]
	v_pk_fma_f32 v[54:55], v[72:73], v[66:67], 0 op_sel_hi:[0,1,0]
	v_cvt_pk_f32_fp8_e32 v[44:45], v196
	v_cvt_pk_f32_fp8_sdwa v[46:47], v196 src0_sel:WORD_1
	v_cvt_pk_f32_fp8_e32 v[64:65], v197
	v_cvt_pk_f32_fp8_sdwa v[66:67], v197 src0_sel:WORD_1
	v_pk_fma_f32 v[48:49], v[72:73], v[44:45], 0 op_sel_hi:[0,1,0]
	v_pk_fma_f32 v[50:51], v[72:73], v[46:47], 0 op_sel_hi:[0,1,0]
	v_pk_fma_f32 v[40:41], v[72:73], v[64:65], 0 op_sel_hi:[0,1,0]
	v_pk_fma_f32 v[42:43], v[72:73], v[66:67], 0 op_sel_hi:[0,1,0]
	v_cvt_pk_f32_fp8_e32 v[44:45], v198
	v_cvt_pk_f32_fp8_sdwa v[46:47], v198 src0_sel:WORD_1
	v_cvt_pk_f32_fp8_e32 v[64:65], v199
	v_cvt_pk_f32_fp8_sdwa v[66:67], v199 src0_sel:WORD_1
	v_pk_fma_f32 v[36:37], v[72:73], v[44:45], 0 op_sel_hi:[0,1,0]
	v_pk_fma_f32 v[38:39], v[72:73], v[46:47], 0 op_sel_hi:[0,1,0]
	v_pk_fma_f32 v[32:33], v[72:73], v[64:65], 0 op_sel_hi:[0,1,0]
	v_pk_fma_f32 v[34:35], v[72:73], v[66:67], 0 op_sel_hi:[0,1,0]
	s_nop 1
	v_readlane_b32 s100, v132, 7
	v_readlane_b32 s48, v74, 1
	s_lshl_b32 s100, s100, 11
	s_add_u32 s100, s98, s100
	s_addc_u32 s101, s99, 0
	global_load_dwordx4 v[250:253], v254, s[100:101]
	global_load_dwordx4 v[76:79], v254, s[100:101] offset:1024
	s_waitcnt vmcnt(12)
	v_mov_b32_e32 v72, s48
	v_cvt_pk_f32_fp8_e32 v[44:45], v200
	v_cvt_pk_f32_fp8_sdwa v[46:47], v200 src0_sel:WORD_1
	v_cvt_pk_f32_fp8_e32 v[64:65], v201
	v_cvt_pk_f32_fp8_sdwa v[66:67], v201 src0_sel:WORD_1
	v_pk_fma_f32 v[68:69], v[72:73], v[44:45], v[68:69] op_sel_hi:[0,1,1]
	v_pk_fma_f32 v[70:71], v[72:73], v[46:47], v[70:71] op_sel_hi:[0,1,1]
	v_pk_fma_f32 v[60:61], v[72:73], v[64:65], v[60:61] op_sel_hi:[0,1,1]
	v_pk_fma_f32 v[62:63], v[72:73], v[66:67], v[62:63] op_sel_hi:[0,1,1]
	v_cvt_pk_f32_fp8_e32 v[44:45], v202
	v_cvt_pk_f32_fp8_sdwa v[46:47], v202 src0_sel:WORD_1
	v_cvt_pk_f32_fp8_e32 v[64:65], v203
	v_cvt_pk_f32_fp8_sdwa v[66:67], v203 src0_sel:WORD_1
	v_pk_fma_f32 v[56:57], v[72:73], v[44:45], v[56:57] op_sel_hi:[0,1,1]
	v_pk_fma_f32 v[58:59], v[72:73], v[46:47], v[58:59] op_sel_hi:[0,1,1]
	v_pk_fma_f32 v[52:53], v[72:73], v[64:65], v[52:53] op_sel_hi:[0,1,1]
	v_pk_fma_f32 v[54:55], v[72:73], v[66:67], v[54:55] op_sel_hi:[0,1,1]
	v_cvt_pk_f32_fp8_e32 v[44:45], v204
	v_cvt_pk_f32_fp8_sdwa v[46:47], v204 src0_sel:WORD_1
	v_cvt_pk_f32_fp8_e32 v[64:65], v205
	v_cvt_pk_f32_fp8_sdwa v[66:67], v205 src0_sel:WORD_1
	v_pk_fma_f32 v[48:49], v[72:73], v[44:45], v[48:49] op_sel_hi:[0,1,1]
	v_pk_fma_f32 v[50:51], v[72:73], v[46:47], v[50:51] op_sel_hi:[0,1,1]
	v_pk_fma_f32 v[40:41], v[72:73], v[64:65], v[40:41] op_sel_hi:[0,1,1]
	v_pk_fma_f32 v[42:43], v[72:73], v[66:67], v[42:43] op_sel_hi:[0,1,1]
	v_cvt_pk_f32_fp8_e32 v[44:45], v206
	v_cvt_pk_f32_fp8_sdwa v[46:47], v206 src0_sel:WORD_1
	v_cvt_pk_f32_fp8_e32 v[64:65], v207
	v_cvt_pk_f32_fp8_sdwa v[66:67], v207 src0_sel:WORD_1
	v_pk_fma_f32 v[36:37], v[72:73], v[44:45], v[36:37] op_sel_hi:[0,1,1]
	v_pk_fma_f32 v[38:39], v[72:73], v[46:47], v[38:39] op_sel_hi:[0,1,1]
	v_pk_fma_f32 v[32:33], v[72:73], v[64:65], v[32:33] op_sel_hi:[0,1,1]
	v_pk_fma_f32 v[34:35], v[72:73], v[66:67], v[34:35] op_sel_hi:[0,1,1]
	s_nop 1
	v_readlane_b32 s100, v132, 8
	v_readlane_b32 s48, v74, 2
	s_lshl_b32 s100, s100, 11
	s_add_u32 s100, s98, s100
	s_addc_u32 s101, s99, 0
	global_load_dwordx4 v[192:195], v254, s[100:101]
	global_load_dwordx4 v[196:199], v254, s[100:101] offset:1024
	s_waitcnt vmcnt(12)
	v_mov_b32_e32 v72, s48
	v_cvt_pk_f32_fp8_e32 v[44:45], v208
	v_cvt_pk_f32_fp8_sdwa v[46:47], v208 src0_sel:WORD_1
	v_cvt_pk_f32_fp8_e32 v[64:65], v209
	v_cvt_pk_f32_fp8_sdwa v[66:67], v209 src0_sel:WORD_1
	v_pk_fma_f32 v[68:69], v[72:73], v[44:45], v[68:69] op_sel_hi:[0,1,1]
	v_pk_fma_f32 v[70:71], v[72:73], v[46:47], v[70:71] op_sel_hi:[0,1,1]
	v_pk_fma_f32 v[60:61], v[72:73], v[64:65], v[60:61] op_sel_hi:[0,1,1]
	v_pk_fma_f32 v[62:63], v[72:73], v[66:67], v[62:63] op_sel_hi:[0,1,1]
	v_cvt_pk_f32_fp8_e32 v[44:45], v210
	v_cvt_pk_f32_fp8_sdwa v[46:47], v210 src0_sel:WORD_1
	v_cvt_pk_f32_fp8_e32 v[64:65], v211
	v_cvt_pk_f32_fp8_sdwa v[66:67], v211 src0_sel:WORD_1
	v_pk_fma_f32 v[56:57], v[72:73], v[44:45], v[56:57] op_sel_hi:[0,1,1]
	v_pk_fma_f32 v[58:59], v[72:73], v[46:47], v[58:59] op_sel_hi:[0,1,1]
	v_pk_fma_f32 v[52:53], v[72:73], v[64:65], v[52:53] op_sel_hi:[0,1,1]
	v_pk_fma_f32 v[54:55], v[72:73], v[66:67], v[54:55] op_sel_hi:[0,1,1]
	v_cvt_pk_f32_fp8_e32 v[44:45], v212
	v_cvt_pk_f32_fp8_sdwa v[46:47], v212 src0_sel:WORD_1
	v_cvt_pk_f32_fp8_e32 v[64:65], v213
	v_cvt_pk_f32_fp8_sdwa v[66:67], v213 src0_sel:WORD_1
	v_pk_fma_f32 v[48:49], v[72:73], v[44:45], v[48:49] op_sel_hi:[0,1,1]
	v_pk_fma_f32 v[50:51], v[72:73], v[46:47], v[50:51] op_sel_hi:[0,1,1]
	v_pk_fma_f32 v[40:41], v[72:73], v[64:65], v[40:41] op_sel_hi:[0,1,1]
	v_pk_fma_f32 v[42:43], v[72:73], v[66:67], v[42:43] op_sel_hi:[0,1,1]
	v_cvt_pk_f32_fp8_e32 v[44:45], v214
	v_cvt_pk_f32_fp8_sdwa v[46:47], v214 src0_sel:WORD_1
	v_cvt_pk_f32_fp8_e32 v[64:65], v215
	v_cvt_pk_f32_fp8_sdwa v[66:67], v215 src0_sel:WORD_1
	v_pk_fma_f32 v[36:37], v[72:73], v[44:45], v[36:37] op_sel_hi:[0,1,1]
	v_pk_fma_f32 v[38:39], v[72:73], v[46:47], v[38:39] op_sel_hi:[0,1,1]
	v_pk_fma_f32 v[32:33], v[72:73], v[64:65], v[32:33] op_sel_hi:[0,1,1]
	v_pk_fma_f32 v[34:35], v[72:73], v[66:67], v[34:35] op_sel_hi:[0,1,1]
	s_nop 1
	v_readlane_b32 s100, v132, 9
	v_readlane_b32 s48, v74, 3
	s_lshl_b32 s100, s100, 11
	s_add_u32 s100, s98, s100
	s_addc_u32 s101, s99, 0
	global_load_dwordx4 v[200:203], v254, s[100:101]
	global_load_dwordx4 v[204:207], v254, s[100:101] offset:1024
	s_waitcnt vmcnt(12)
	v_mov_b32_e32 v72, s48
	v_cvt_pk_f32_fp8_e32 v[44:45], v216
	v_cvt_pk_f32_fp8_sdwa v[46:47], v216 src0_sel:WORD_1
	v_cvt_pk_f32_fp8_e32 v[64:65], v217
	v_cvt_pk_f32_fp8_sdwa v[66:67], v217 src0_sel:WORD_1
	v_pk_fma_f32 v[68:69], v[72:73], v[44:45], v[68:69] op_sel_hi:[0,1,1]
	v_pk_fma_f32 v[70:71], v[72:73], v[46:47], v[70:71] op_sel_hi:[0,1,1]
	v_pk_fma_f32 v[60:61], v[72:73], v[64:65], v[60:61] op_sel_hi:[0,1,1]
	v_pk_fma_f32 v[62:63], v[72:73], v[66:67], v[62:63] op_sel_hi:[0,1,1]
	v_cvt_pk_f32_fp8_e32 v[44:45], v218
	v_cvt_pk_f32_fp8_sdwa v[46:47], v218 src0_sel:WORD_1
	v_cvt_pk_f32_fp8_e32 v[64:65], v219
	v_cvt_pk_f32_fp8_sdwa v[66:67], v219 src0_sel:WORD_1
	v_pk_fma_f32 v[56:57], v[72:73], v[44:45], v[56:57] op_sel_hi:[0,1,1]
	v_pk_fma_f32 v[58:59], v[72:73], v[46:47], v[58:59] op_sel_hi:[0,1,1]
	v_pk_fma_f32 v[52:53], v[72:73], v[64:65], v[52:53] op_sel_hi:[0,1,1]
	v_pk_fma_f32 v[54:55], v[72:73], v[66:67], v[54:55] op_sel_hi:[0,1,1]
	v_cvt_pk_f32_fp8_e32 v[44:45], v220
	v_cvt_pk_f32_fp8_sdwa v[46:47], v220 src0_sel:WORD_1
	v_cvt_pk_f32_fp8_e32 v[64:65], v221
	v_cvt_pk_f32_fp8_sdwa v[66:67], v221 src0_sel:WORD_1
	v_pk_fma_f32 v[48:49], v[72:73], v[44:45], v[48:49] op_sel_hi:[0,1,1]
	v_pk_fma_f32 v[50:51], v[72:73], v[46:47], v[50:51] op_sel_hi:[0,1,1]
	v_pk_fma_f32 v[40:41], v[72:73], v[64:65], v[40:41] op_sel_hi:[0,1,1]
	v_pk_fma_f32 v[42:43], v[72:73], v[66:67], v[42:43] op_sel_hi:[0,1,1]
	v_cvt_pk_f32_fp8_e32 v[44:45], v222
	v_cvt_pk_f32_fp8_sdwa v[46:47], v222 src0_sel:WORD_1
	v_cvt_pk_f32_fp8_e32 v[64:65], v223
	v_cvt_pk_f32_fp8_sdwa v[66:67], v223 src0_sel:WORD_1
	v_pk_fma_f32 v[36:37], v[72:73], v[44:45], v[36:37] op_sel_hi:[0,1,1]
	v_pk_fma_f32 v[38:39], v[72:73], v[46:47], v[38:39] op_sel_hi:[0,1,1]
	v_pk_fma_f32 v[32:33], v[72:73], v[64:65], v[32:33] op_sel_hi:[0,1,1]
	v_pk_fma_f32 v[34:35], v[72:73], v[66:67], v[34:35] op_sel_hi:[0,1,1]
	s_nop 1
	v_readlane_b32 s100, v132, 10
	v_readlane_b32 s48, v74, 4
	s_lshl_b32 s100, s100, 11
	s_add_u32 s100, s98, s100
	s_addc_u32 s101, s99, 0
	global_load_dwordx4 v[208:211], v254, s[100:101]
	global_load_dwordx4 v[212:215], v254, s[100:101] offset:1024
	s_waitcnt vmcnt(12)
	v_mov_b32_e32 v72, s48
	v_cvt_pk_f32_fp8_e32 v[44:45], v224
	v_cvt_pk_f32_fp8_sdwa v[46:47], v224 src0_sel:WORD_1
	v_cvt_pk_f32_fp8_e32 v[64:65], v225
	v_cvt_pk_f32_fp8_sdwa v[66:67], v225 src0_sel:WORD_1
	v_pk_fma_f32 v[68:69], v[72:73], v[44:45], v[68:69] op_sel_hi:[0,1,1]
	v_pk_fma_f32 v[70:71], v[72:73], v[46:47], v[70:71] op_sel_hi:[0,1,1]
	v_pk_fma_f32 v[60:61], v[72:73], v[64:65], v[60:61] op_sel_hi:[0,1,1]
	v_pk_fma_f32 v[62:63], v[72:73], v[66:67], v[62:63] op_sel_hi:[0,1,1]
	v_cvt_pk_f32_fp8_e32 v[44:45], v226
	v_cvt_pk_f32_fp8_sdwa v[46:47], v226 src0_sel:WORD_1
	v_cvt_pk_f32_fp8_e32 v[64:65], v227
	v_cvt_pk_f32_fp8_sdwa v[66:67], v227 src0_sel:WORD_1
	v_pk_fma_f32 v[56:57], v[72:73], v[44:45], v[56:57] op_sel_hi:[0,1,1]
	v_pk_fma_f32 v[58:59], v[72:73], v[46:47], v[58:59] op_sel_hi:[0,1,1]
	v_pk_fma_f32 v[52:53], v[72:73], v[64:65], v[52:53] op_sel_hi:[0,1,1]
	v_pk_fma_f32 v[54:55], v[72:73], v[66:67], v[54:55] op_sel_hi:[0,1,1]
	v_cvt_pk_f32_fp8_e32 v[44:45], v228
	v_cvt_pk_f32_fp8_sdwa v[46:47], v228 src0_sel:WORD_1
	v_cvt_pk_f32_fp8_e32 v[64:65], v229
	v_cvt_pk_f32_fp8_sdwa v[66:67], v229 src0_sel:WORD_1
	v_pk_fma_f32 v[48:49], v[72:73], v[44:45], v[48:49] op_sel_hi:[0,1,1]
	v_pk_fma_f32 v[50:51], v[72:73], v[46:47], v[50:51] op_sel_hi:[0,1,1]
	v_pk_fma_f32 v[40:41], v[72:73], v[64:65], v[40:41] op_sel_hi:[0,1,1]
	v_pk_fma_f32 v[42:43], v[72:73], v[66:67], v[42:43] op_sel_hi:[0,1,1]
	v_cvt_pk_f32_fp8_e32 v[44:45], v230
	v_cvt_pk_f32_fp8_sdwa v[46:47], v230 src0_sel:WORD_1
	v_cvt_pk_f32_fp8_e32 v[64:65], v231
	v_cvt_pk_f32_fp8_sdwa v[66:67], v231 src0_sel:WORD_1
	v_pk_fma_f32 v[36:37], v[72:73], v[44:45], v[36:37] op_sel_hi:[0,1,1]
	v_pk_fma_f32 v[38:39], v[72:73], v[46:47], v[38:39] op_sel_hi:[0,1,1]
	v_pk_fma_f32 v[32:33], v[72:73], v[64:65], v[32:33] op_sel_hi:[0,1,1]
	v_pk_fma_f32 v[34:35], v[72:73], v[66:67], v[34:35] op_sel_hi:[0,1,1]
	s_nop 1
	v_readlane_b32 s100, v132, 11
	v_readlane_b32 s48, v74, 5
	s_lshl_b32 s100, s100, 11
	s_add_u32 s100, s98, s100
	s_addc_u32 s101, s99, 0
	global_load_dwordx4 v[216:219], v254, s[100:101]
	global_load_dwordx4 v[220:223], v254, s[100:101] offset:1024
	s_waitcnt vmcnt(12)
	v_mov_b32_e32 v72, s48
	v_cvt_pk_f32_fp8_e32 v[44:45], v232
	v_cvt_pk_f32_fp8_sdwa v[46:47], v232 src0_sel:WORD_1
	v_cvt_pk_f32_fp8_e32 v[64:65], v233
	v_cvt_pk_f32_fp8_sdwa v[66:67], v233 src0_sel:WORD_1
	v_pk_fma_f32 v[68:69], v[72:73], v[44:45], v[68:69] op_sel_hi:[0,1,1]
	v_pk_fma_f32 v[70:71], v[72:73], v[46:47], v[70:71] op_sel_hi:[0,1,1]
	v_pk_fma_f32 v[60:61], v[72:73], v[64:65], v[60:61] op_sel_hi:[0,1,1]
	v_pk_fma_f32 v[62:63], v[72:73], v[66:67], v[62:63] op_sel_hi:[0,1,1]
	v_cvt_pk_f32_fp8_e32 v[44:45], v234
	v_cvt_pk_f32_fp8_sdwa v[46:47], v234 src0_sel:WORD_1
	v_cvt_pk_f32_fp8_e32 v[64:65], v235
	v_cvt_pk_f32_fp8_sdwa v[66:67], v235 src0_sel:WORD_1
	v_pk_fma_f32 v[56:57], v[72:73], v[44:45], v[56:57] op_sel_hi:[0,1,1]
	v_pk_fma_f32 v[58:59], v[72:73], v[46:47], v[58:59] op_sel_hi:[0,1,1]
	v_pk_fma_f32 v[52:53], v[72:73], v[64:65], v[52:53] op_sel_hi:[0,1,1]
	v_pk_fma_f32 v[54:55], v[72:73], v[66:67], v[54:55] op_sel_hi:[0,1,1]
	v_cvt_pk_f32_fp8_e32 v[44:45], v236
	v_cvt_pk_f32_fp8_sdwa v[46:47], v236 src0_sel:WORD_1
	v_cvt_pk_f32_fp8_e32 v[64:65], v237
	v_cvt_pk_f32_fp8_sdwa v[66:67], v237 src0_sel:WORD_1
	v_pk_fma_f32 v[48:49], v[72:73], v[44:45], v[48:49] op_sel_hi:[0,1,1]
	v_pk_fma_f32 v[50:51], v[72:73], v[46:47], v[50:51] op_sel_hi:[0,1,1]
	v_pk_fma_f32 v[40:41], v[72:73], v[64:65], v[40:41] op_sel_hi:[0,1,1]
	v_pk_fma_f32 v[42:43], v[72:73], v[66:67], v[42:43] op_sel_hi:[0,1,1]
	v_cvt_pk_f32_fp8_e32 v[44:45], v238
	v_cvt_pk_f32_fp8_sdwa v[46:47], v238 src0_sel:WORD_1
	v_cvt_pk_f32_fp8_e32 v[64:65], v239
	v_cvt_pk_f32_fp8_sdwa v[66:67], v239 src0_sel:WORD_1
	v_pk_fma_f32 v[36:37], v[72:73], v[44:45], v[36:37] op_sel_hi:[0,1,1]
	v_pk_fma_f32 v[38:39], v[72:73], v[46:47], v[38:39] op_sel_hi:[0,1,1]
	v_pk_fma_f32 v[32:33], v[72:73], v[64:65], v[32:33] op_sel_hi:[0,1,1]
	v_pk_fma_f32 v[34:35], v[72:73], v[66:67], v[34:35] op_sel_hi:[0,1,1]
	s_nop 1
	v_readlane_b32 s100, v132, 12
	v_readlane_b32 s48, v74, 6
	s_lshl_b32 s100, s100, 11
	s_add_u32 s100, s98, s100
	s_addc_u32 s101, s99, 0
	global_load_dwordx4 v[224:227], v254, s[100:101]
	global_load_dwordx4 v[228:231], v254, s[100:101] offset:1024
	s_waitcnt vmcnt(12)
	v_mov_b32_e32 v72, s48
	v_cvt_pk_f32_fp8_e32 v[44:45], v242
	v_cvt_pk_f32_fp8_sdwa v[46:47], v242 src0_sel:WORD_1
	v_cvt_pk_f32_fp8_e32 v[64:65], v243
	v_cvt_pk_f32_fp8_sdwa v[66:67], v243 src0_sel:WORD_1
	v_pk_fma_f32 v[68:69], v[72:73], v[44:45], v[68:69] op_sel_hi:[0,1,1]
	v_pk_fma_f32 v[70:71], v[72:73], v[46:47], v[70:71] op_sel_hi:[0,1,1]
	v_pk_fma_f32 v[60:61], v[72:73], v[64:65], v[60:61] op_sel_hi:[0,1,1]
	v_pk_fma_f32 v[62:63], v[72:73], v[66:67], v[62:63] op_sel_hi:[0,1,1]
	v_cvt_pk_f32_fp8_e32 v[44:45], v244
	v_cvt_pk_f32_fp8_sdwa v[46:47], v244 src0_sel:WORD_1
	v_cvt_pk_f32_fp8_e32 v[64:65], v245
	v_cvt_pk_f32_fp8_sdwa v[66:67], v245 src0_sel:WORD_1
	v_pk_fma_f32 v[56:57], v[72:73], v[44:45], v[56:57] op_sel_hi:[0,1,1]
	v_pk_fma_f32 v[58:59], v[72:73], v[46:47], v[58:59] op_sel_hi:[0,1,1]
	v_pk_fma_f32 v[52:53], v[72:73], v[64:65], v[52:53] op_sel_hi:[0,1,1]
	v_pk_fma_f32 v[54:55], v[72:73], v[66:67], v[54:55] op_sel_hi:[0,1,1]
	v_cvt_pk_f32_fp8_e32 v[44:45], v246
	v_cvt_pk_f32_fp8_sdwa v[46:47], v246 src0_sel:WORD_1
	v_cvt_pk_f32_fp8_e32 v[64:65], v247
	v_cvt_pk_f32_fp8_sdwa v[66:67], v247 src0_sel:WORD_1
	v_pk_fma_f32 v[48:49], v[72:73], v[44:45], v[48:49] op_sel_hi:[0,1,1]
	v_pk_fma_f32 v[50:51], v[72:73], v[46:47], v[50:51] op_sel_hi:[0,1,1]
	v_pk_fma_f32 v[40:41], v[72:73], v[64:65], v[40:41] op_sel_hi:[0,1,1]
	v_pk_fma_f32 v[42:43], v[72:73], v[66:67], v[42:43] op_sel_hi:[0,1,1]
	v_cvt_pk_f32_fp8_e32 v[44:45], v248
	v_cvt_pk_f32_fp8_sdwa v[46:47], v248 src0_sel:WORD_1
	v_cvt_pk_f32_fp8_e32 v[64:65], v249
	v_cvt_pk_f32_fp8_sdwa v[66:67], v249 src0_sel:WORD_1
	v_pk_fma_f32 v[36:37], v[72:73], v[44:45], v[36:37] op_sel_hi:[0,1,1]
	v_pk_fma_f32 v[38:39], v[72:73], v[46:47], v[38:39] op_sel_hi:[0,1,1]
	v_pk_fma_f32 v[32:33], v[72:73], v[64:65], v[32:33] op_sel_hi:[0,1,1]
	v_pk_fma_f32 v[34:35], v[72:73], v[66:67], v[34:35] op_sel_hi:[0,1,1]
	s_nop 1
	v_readlane_b32 s100, v132, 13
	v_readlane_b32 s48, v74, 7
	s_lshl_b32 s100, s100, 11
	s_add_u32 s100, s98, s100
	s_addc_u32 s101, s99, 0
	global_load_dwordx4 v[232:235], v254, s[100:101]
	global_load_dwordx4 v[236:239], v254, s[100:101] offset:1024
	s_waitcnt vmcnt(12)
	v_mov_b32_e32 v72, s48
	v_cvt_pk_f32_fp8_e32 v[44:45], v250
	v_cvt_pk_f32_fp8_sdwa v[46:47], v250 src0_sel:WORD_1
	v_cvt_pk_f32_fp8_e32 v[64:65], v251
	v_cvt_pk_f32_fp8_sdwa v[66:67], v251 src0_sel:WORD_1
	v_pk_fma_f32 v[68:69], v[72:73], v[44:45], v[68:69] op_sel_hi:[0,1,1]
	v_pk_fma_f32 v[70:71], v[72:73], v[46:47], v[70:71] op_sel_hi:[0,1,1]
	v_pk_fma_f32 v[60:61], v[72:73], v[64:65], v[60:61] op_sel_hi:[0,1,1]
	v_pk_fma_f32 v[62:63], v[72:73], v[66:67], v[62:63] op_sel_hi:[0,1,1]
	v_cvt_pk_f32_fp8_e32 v[44:45], v252
	v_cvt_pk_f32_fp8_sdwa v[46:47], v252 src0_sel:WORD_1
	v_cvt_pk_f32_fp8_e32 v[64:65], v253
	v_cvt_pk_f32_fp8_sdwa v[66:67], v253 src0_sel:WORD_1
	v_pk_fma_f32 v[56:57], v[72:73], v[44:45], v[56:57] op_sel_hi:[0,1,1]
	v_pk_fma_f32 v[58:59], v[72:73], v[46:47], v[58:59] op_sel_hi:[0,1,1]
	v_pk_fma_f32 v[52:53], v[72:73], v[64:65], v[52:53] op_sel_hi:[0,1,1]
	v_pk_fma_f32 v[54:55], v[72:73], v[66:67], v[54:55] op_sel_hi:[0,1,1]
	v_cvt_pk_f32_fp8_e32 v[44:45], v76
	v_cvt_pk_f32_fp8_sdwa v[46:47], v76 src0_sel:WORD_1
	v_cvt_pk_f32_fp8_e32 v[64:65], v77
	v_cvt_pk_f32_fp8_sdwa v[66:67], v77 src0_sel:WORD_1
	v_pk_fma_f32 v[48:49], v[72:73], v[44:45], v[48:49] op_sel_hi:[0,1,1]
	v_pk_fma_f32 v[50:51], v[72:73], v[46:47], v[50:51] op_sel_hi:[0,1,1]
	v_pk_fma_f32 v[40:41], v[72:73], v[64:65], v[40:41] op_sel_hi:[0,1,1]
	v_pk_fma_f32 v[42:43], v[72:73], v[66:67], v[42:43] op_sel_hi:[0,1,1]
	v_cvt_pk_f32_fp8_e32 v[44:45], v78
	v_cvt_pk_f32_fp8_sdwa v[46:47], v78 src0_sel:WORD_1
	v_cvt_pk_f32_fp8_e32 v[64:65], v79
	v_cvt_pk_f32_fp8_sdwa v[66:67], v79 src0_sel:WORD_1
	v_pk_fma_f32 v[36:37], v[72:73], v[44:45], v[36:37] op_sel_hi:[0,1,1]
	v_pk_fma_f32 v[38:39], v[72:73], v[46:47], v[38:39] op_sel_hi:[0,1,1]
	v_pk_fma_f32 v[32:33], v[72:73], v[64:65], v[32:33] op_sel_hi:[0,1,1]
	v_pk_fma_f32 v[34:35], v[72:73], v[66:67], v[34:35] op_sel_hi:[0,1,1]
	s_nop 1
	v_readlane_b32 s100, v132, 14
	v_readlane_b32 s48, v74, 8
	s_lshl_b32 s100, s100, 11
	s_add_u32 s100, s98, s100
	s_addc_u32 s101, s99, 0
	global_load_dwordx4 v[242:245], v254, s[100:101]
	global_load_dwordx4 v[246:249], v254, s[100:101] offset:1024
	s_waitcnt vmcnt(12)
	v_mov_b32_e32 v72, s48
	v_cvt_pk_f32_fp8_e32 v[44:45], v192
	v_cvt_pk_f32_fp8_sdwa v[46:47], v192 src0_sel:WORD_1
	v_cvt_pk_f32_fp8_e32 v[64:65], v193
	v_cvt_pk_f32_fp8_sdwa v[66:67], v193 src0_sel:WORD_1
	v_pk_fma_f32 v[68:69], v[72:73], v[44:45], v[68:69] op_sel_hi:[0,1,1]
	v_pk_fma_f32 v[70:71], v[72:73], v[46:47], v[70:71] op_sel_hi:[0,1,1]
	v_pk_fma_f32 v[60:61], v[72:73], v[64:65], v[60:61] op_sel_hi:[0,1,1]
	v_pk_fma_f32 v[62:63], v[72:73], v[66:67], v[62:63] op_sel_hi:[0,1,1]
	v_cvt_pk_f32_fp8_e32 v[44:45], v194
	v_cvt_pk_f32_fp8_sdwa v[46:47], v194 src0_sel:WORD_1
	v_cvt_pk_f32_fp8_e32 v[64:65], v195
	v_cvt_pk_f32_fp8_sdwa v[66:67], v195 src0_sel:WORD_1
	v_pk_fma_f32 v[56:57], v[72:73], v[44:45], v[56:57] op_sel_hi:[0,1,1]
	v_pk_fma_f32 v[58:59], v[72:73], v[46:47], v[58:59] op_sel_hi:[0,1,1]
	v_pk_fma_f32 v[52:53], v[72:73], v[64:65], v[52:53] op_sel_hi:[0,1,1]
	v_pk_fma_f32 v[54:55], v[72:73], v[66:67], v[54:55] op_sel_hi:[0,1,1]
	v_cvt_pk_f32_fp8_e32 v[44:45], v196
	v_cvt_pk_f32_fp8_sdwa v[46:47], v196 src0_sel:WORD_1
	v_cvt_pk_f32_fp8_e32 v[64:65], v197
	v_cvt_pk_f32_fp8_sdwa v[66:67], v197 src0_sel:WORD_1
	v_pk_fma_f32 v[48:49], v[72:73], v[44:45], v[48:49] op_sel_hi:[0,1,1]
	v_pk_fma_f32 v[50:51], v[72:73], v[46:47], v[50:51] op_sel_hi:[0,1,1]
	v_pk_fma_f32 v[40:41], v[72:73], v[64:65], v[40:41] op_sel_hi:[0,1,1]
	v_pk_fma_f32 v[42:43], v[72:73], v[66:67], v[42:43] op_sel_hi:[0,1,1]
	v_cvt_pk_f32_fp8_e32 v[44:45], v198
	v_cvt_pk_f32_fp8_sdwa v[46:47], v198 src0_sel:WORD_1
	v_cvt_pk_f32_fp8_e32 v[64:65], v199
	v_cvt_pk_f32_fp8_sdwa v[66:67], v199 src0_sel:WORD_1
	v_pk_fma_f32 v[36:37], v[72:73], v[44:45], v[36:37] op_sel_hi:[0,1,1]
	v_pk_fma_f32 v[38:39], v[72:73], v[46:47], v[38:39] op_sel_hi:[0,1,1]
	v_pk_fma_f32 v[32:33], v[72:73], v[64:65], v[32:33] op_sel_hi:[0,1,1]
	v_pk_fma_f32 v[34:35], v[72:73], v[66:67], v[34:35] op_sel_hi:[0,1,1]
	s_nop 1
	v_readlane_b32 s100, v132, 15
	v_readlane_b32 s48, v74, 9
	s_lshl_b32 s100, s100, 11
	s_add_u32 s100, s98, s100
	s_addc_u32 s101, s99, 0
	global_load_dwordx4 v[250:253], v254, s[100:101]
	global_load_dwordx4 v[76:79], v254, s[100:101] offset:1024
	s_waitcnt vmcnt(12)
	v_mov_b32_e32 v72, s48
	v_cvt_pk_f32_fp8_e32 v[44:45], v200
	v_cvt_pk_f32_fp8_sdwa v[46:47], v200 src0_sel:WORD_1
	v_cvt_pk_f32_fp8_e32 v[64:65], v201
	v_cvt_pk_f32_fp8_sdwa v[66:67], v201 src0_sel:WORD_1
	v_pk_fma_f32 v[68:69], v[72:73], v[44:45], v[68:69] op_sel_hi:[0,1,1]
	v_pk_fma_f32 v[70:71], v[72:73], v[46:47], v[70:71] op_sel_hi:[0,1,1]
	v_pk_fma_f32 v[60:61], v[72:73], v[64:65], v[60:61] op_sel_hi:[0,1,1]
	v_pk_fma_f32 v[62:63], v[72:73], v[66:67], v[62:63] op_sel_hi:[0,1,1]
	v_cvt_pk_f32_fp8_e32 v[44:45], v202
	v_cvt_pk_f32_fp8_sdwa v[46:47], v202 src0_sel:WORD_1
	v_cvt_pk_f32_fp8_e32 v[64:65], v203
	v_cvt_pk_f32_fp8_sdwa v[66:67], v203 src0_sel:WORD_1
	v_pk_fma_f32 v[56:57], v[72:73], v[44:45], v[56:57] op_sel_hi:[0,1,1]
	v_pk_fma_f32 v[58:59], v[72:73], v[46:47], v[58:59] op_sel_hi:[0,1,1]
	v_pk_fma_f32 v[52:53], v[72:73], v[64:65], v[52:53] op_sel_hi:[0,1,1]
	v_pk_fma_f32 v[54:55], v[72:73], v[66:67], v[54:55] op_sel_hi:[0,1,1]
	v_cvt_pk_f32_fp8_e32 v[44:45], v204
	v_cvt_pk_f32_fp8_sdwa v[46:47], v204 src0_sel:WORD_1
	v_cvt_pk_f32_fp8_e32 v[64:65], v205
	v_cvt_pk_f32_fp8_sdwa v[66:67], v205 src0_sel:WORD_1
	v_pk_fma_f32 v[48:49], v[72:73], v[44:45], v[48:49] op_sel_hi:[0,1,1]
	v_pk_fma_f32 v[50:51], v[72:73], v[46:47], v[50:51] op_sel_hi:[0,1,1]
	v_pk_fma_f32 v[40:41], v[72:73], v[64:65], v[40:41] op_sel_hi:[0,1,1]
	v_pk_fma_f32 v[42:43], v[72:73], v[66:67], v[42:43] op_sel_hi:[0,1,1]
	v_cvt_pk_f32_fp8_e32 v[44:45], v206
	v_cvt_pk_f32_fp8_sdwa v[46:47], v206 src0_sel:WORD_1
	v_cvt_pk_f32_fp8_e32 v[64:65], v207
	v_cvt_pk_f32_fp8_sdwa v[66:67], v207 src0_sel:WORD_1
	v_pk_fma_f32 v[36:37], v[72:73], v[44:45], v[36:37] op_sel_hi:[0,1,1]
	v_pk_fma_f32 v[38:39], v[72:73], v[46:47], v[38:39] op_sel_hi:[0,1,1]
	v_pk_fma_f32 v[32:33], v[72:73], v[64:65], v[32:33] op_sel_hi:[0,1,1]
	v_pk_fma_f32 v[34:35], v[72:73], v[66:67], v[34:35] op_sel_hi:[0,1,1]
	s_nop 1
	v_readlane_b32 s100, v133, 0
	v_readlane_b32 s48, v74, 10
	s_lshl_b32 s100, s100, 11
	s_add_u32 s100, s96, s100
	s_addc_u32 s101, s97, 0
	global_load_dwordx4 v[0:3], v254, s[100:101]
	global_load_dwordx4 v[4:7], v254, s[100:101] offset:1024
	s_waitcnt vmcnt(12)
	v_mov_b32_e32 v72, s48
	v_cvt_pk_f32_fp8_e32 v[44:45], v208
	v_cvt_pk_f32_fp8_sdwa v[46:47], v208 src0_sel:WORD_1
	v_cvt_pk_f32_fp8_e32 v[64:65], v209
	v_cvt_pk_f32_fp8_sdwa v[66:67], v209 src0_sel:WORD_1
	v_pk_fma_f32 v[68:69], v[72:73], v[44:45], v[68:69] op_sel_hi:[0,1,1]
	v_pk_fma_f32 v[70:71], v[72:73], v[46:47], v[70:71] op_sel_hi:[0,1,1]
	v_pk_fma_f32 v[60:61], v[72:73], v[64:65], v[60:61] op_sel_hi:[0,1,1]
	v_pk_fma_f32 v[62:63], v[72:73], v[66:67], v[62:63] op_sel_hi:[0,1,1]
	v_cvt_pk_f32_fp8_e32 v[44:45], v210
	v_cvt_pk_f32_fp8_sdwa v[46:47], v210 src0_sel:WORD_1
	v_cvt_pk_f32_fp8_e32 v[64:65], v211
	v_cvt_pk_f32_fp8_sdwa v[66:67], v211 src0_sel:WORD_1
	v_pk_fma_f32 v[56:57], v[72:73], v[44:45], v[56:57] op_sel_hi:[0,1,1]
	v_pk_fma_f32 v[58:59], v[72:73], v[46:47], v[58:59] op_sel_hi:[0,1,1]
	v_pk_fma_f32 v[52:53], v[72:73], v[64:65], v[52:53] op_sel_hi:[0,1,1]
	v_pk_fma_f32 v[54:55], v[72:73], v[66:67], v[54:55] op_sel_hi:[0,1,1]
	v_cvt_pk_f32_fp8_e32 v[44:45], v212
	v_cvt_pk_f32_fp8_sdwa v[46:47], v212 src0_sel:WORD_1
	v_cvt_pk_f32_fp8_e32 v[64:65], v213
	v_cvt_pk_f32_fp8_sdwa v[66:67], v213 src0_sel:WORD_1
	v_pk_fma_f32 v[48:49], v[72:73], v[44:45], v[48:49] op_sel_hi:[0,1,1]
	v_pk_fma_f32 v[50:51], v[72:73], v[46:47], v[50:51] op_sel_hi:[0,1,1]
	v_pk_fma_f32 v[40:41], v[72:73], v[64:65], v[40:41] op_sel_hi:[0,1,1]
	v_pk_fma_f32 v[42:43], v[72:73], v[66:67], v[42:43] op_sel_hi:[0,1,1]
	v_cvt_pk_f32_fp8_e32 v[44:45], v214
	v_cvt_pk_f32_fp8_sdwa v[46:47], v214 src0_sel:WORD_1
	v_cvt_pk_f32_fp8_e32 v[64:65], v215
	v_cvt_pk_f32_fp8_sdwa v[66:67], v215 src0_sel:WORD_1
	v_pk_fma_f32 v[36:37], v[72:73], v[44:45], v[36:37] op_sel_hi:[0,1,1]
	v_pk_fma_f32 v[38:39], v[72:73], v[46:47], v[38:39] op_sel_hi:[0,1,1]
	v_pk_fma_f32 v[32:33], v[72:73], v[64:65], v[32:33] op_sel_hi:[0,1,1]
	v_pk_fma_f32 v[34:35], v[72:73], v[66:67], v[34:35] op_sel_hi:[0,1,1]
	s_nop 1
	v_readlane_b32 s100, v133, 1
	v_readlane_b32 s48, v74, 11
	s_lshl_b32 s100, s100, 11
	s_add_u32 s100, s96, s100
	s_addc_u32 s101, s97, 0
	global_load_dwordx4 v[8:11], v254, s[100:101]
	global_load_dwordx4 v[12:15], v254, s[100:101] offset:1024
	s_waitcnt vmcnt(12)
	v_mov_b32_e32 v72, s48
	v_cvt_pk_f32_fp8_e32 v[44:45], v216
	v_cvt_pk_f32_fp8_sdwa v[46:47], v216 src0_sel:WORD_1
	v_cvt_pk_f32_fp8_e32 v[64:65], v217
	v_cvt_pk_f32_fp8_sdwa v[66:67], v217 src0_sel:WORD_1
	v_pk_fma_f32 v[68:69], v[72:73], v[44:45], v[68:69] op_sel_hi:[0,1,1]
	v_pk_fma_f32 v[70:71], v[72:73], v[46:47], v[70:71] op_sel_hi:[0,1,1]
	v_pk_fma_f32 v[60:61], v[72:73], v[64:65], v[60:61] op_sel_hi:[0,1,1]
	v_pk_fma_f32 v[62:63], v[72:73], v[66:67], v[62:63] op_sel_hi:[0,1,1]
	v_cvt_pk_f32_fp8_e32 v[44:45], v218
	v_cvt_pk_f32_fp8_sdwa v[46:47], v218 src0_sel:WORD_1
	v_cvt_pk_f32_fp8_e32 v[64:65], v219
	v_cvt_pk_f32_fp8_sdwa v[66:67], v219 src0_sel:WORD_1
	v_pk_fma_f32 v[56:57], v[72:73], v[44:45], v[56:57] op_sel_hi:[0,1,1]
	v_pk_fma_f32 v[58:59], v[72:73], v[46:47], v[58:59] op_sel_hi:[0,1,1]
	v_pk_fma_f32 v[52:53], v[72:73], v[64:65], v[52:53] op_sel_hi:[0,1,1]
	v_pk_fma_f32 v[54:55], v[72:73], v[66:67], v[54:55] op_sel_hi:[0,1,1]
	v_cvt_pk_f32_fp8_e32 v[44:45], v220
	v_cvt_pk_f32_fp8_sdwa v[46:47], v220 src0_sel:WORD_1
	v_cvt_pk_f32_fp8_e32 v[64:65], v221
	v_cvt_pk_f32_fp8_sdwa v[66:67], v221 src0_sel:WORD_1
	v_pk_fma_f32 v[48:49], v[72:73], v[44:45], v[48:49] op_sel_hi:[0,1,1]
	v_pk_fma_f32 v[50:51], v[72:73], v[46:47], v[50:51] op_sel_hi:[0,1,1]
	v_pk_fma_f32 v[40:41], v[72:73], v[64:65], v[40:41] op_sel_hi:[0,1,1]
	v_pk_fma_f32 v[42:43], v[72:73], v[66:67], v[42:43] op_sel_hi:[0,1,1]
	v_cvt_pk_f32_fp8_e32 v[44:45], v222
	v_cvt_pk_f32_fp8_sdwa v[46:47], v222 src0_sel:WORD_1
	v_cvt_pk_f32_fp8_e32 v[64:65], v223
	v_cvt_pk_f32_fp8_sdwa v[66:67], v223 src0_sel:WORD_1
	v_pk_fma_f32 v[36:37], v[72:73], v[44:45], v[36:37] op_sel_hi:[0,1,1]
	v_pk_fma_f32 v[38:39], v[72:73], v[46:47], v[38:39] op_sel_hi:[0,1,1]
	v_pk_fma_f32 v[32:33], v[72:73], v[64:65], v[32:33] op_sel_hi:[0,1,1]
	v_pk_fma_f32 v[34:35], v[72:73], v[66:67], v[34:35] op_sel_hi:[0,1,1]
	s_nop 1
	v_readlane_b32 s100, v133, 2
	v_readlane_b32 s48, v74, 12
	s_lshl_b32 s100, s100, 11
	s_add_u32 s100, s96, s100
	s_addc_u32 s101, s97, 0
	global_load_dwordx4 v[16:19], v254, s[100:101]
	global_load_dwordx4 v[20:23], v254, s[100:101] offset:1024
	s_waitcnt vmcnt(12)
	v_mov_b32_e32 v72, s48
	v_cvt_pk_f32_fp8_e32 v[44:45], v224
	v_cvt_pk_f32_fp8_sdwa v[46:47], v224 src0_sel:WORD_1
	v_cvt_pk_f32_fp8_e32 v[64:65], v225
	v_cvt_pk_f32_fp8_sdwa v[66:67], v225 src0_sel:WORD_1
	v_pk_fma_f32 v[68:69], v[72:73], v[44:45], v[68:69] op_sel_hi:[0,1,1]
	v_pk_fma_f32 v[70:71], v[72:73], v[46:47], v[70:71] op_sel_hi:[0,1,1]
	v_pk_fma_f32 v[60:61], v[72:73], v[64:65], v[60:61] op_sel_hi:[0,1,1]
	v_pk_fma_f32 v[62:63], v[72:73], v[66:67], v[62:63] op_sel_hi:[0,1,1]
	v_cvt_pk_f32_fp8_e32 v[44:45], v226
	v_cvt_pk_f32_fp8_sdwa v[46:47], v226 src0_sel:WORD_1
	v_cvt_pk_f32_fp8_e32 v[64:65], v227
	v_cvt_pk_f32_fp8_sdwa v[66:67], v227 src0_sel:WORD_1
	v_pk_fma_f32 v[56:57], v[72:73], v[44:45], v[56:57] op_sel_hi:[0,1,1]
	v_pk_fma_f32 v[58:59], v[72:73], v[46:47], v[58:59] op_sel_hi:[0,1,1]
	v_pk_fma_f32 v[52:53], v[72:73], v[64:65], v[52:53] op_sel_hi:[0,1,1]
	v_pk_fma_f32 v[54:55], v[72:73], v[66:67], v[54:55] op_sel_hi:[0,1,1]
	v_cvt_pk_f32_fp8_e32 v[44:45], v228
	v_cvt_pk_f32_fp8_sdwa v[46:47], v228 src0_sel:WORD_1
	v_cvt_pk_f32_fp8_e32 v[64:65], v229
	v_cvt_pk_f32_fp8_sdwa v[66:67], v229 src0_sel:WORD_1
	v_pk_fma_f32 v[48:49], v[72:73], v[44:45], v[48:49] op_sel_hi:[0,1,1]
	v_pk_fma_f32 v[50:51], v[72:73], v[46:47], v[50:51] op_sel_hi:[0,1,1]
	v_pk_fma_f32 v[40:41], v[72:73], v[64:65], v[40:41] op_sel_hi:[0,1,1]
	v_pk_fma_f32 v[42:43], v[72:73], v[66:67], v[42:43] op_sel_hi:[0,1,1]
	v_cvt_pk_f32_fp8_e32 v[44:45], v230
	v_cvt_pk_f32_fp8_sdwa v[46:47], v230 src0_sel:WORD_1
	v_cvt_pk_f32_fp8_e32 v[64:65], v231
	v_cvt_pk_f32_fp8_sdwa v[66:67], v231 src0_sel:WORD_1
	v_pk_fma_f32 v[36:37], v[72:73], v[44:45], v[36:37] op_sel_hi:[0,1,1]
	v_pk_fma_f32 v[38:39], v[72:73], v[46:47], v[38:39] op_sel_hi:[0,1,1]
	v_pk_fma_f32 v[32:33], v[72:73], v[64:65], v[32:33] op_sel_hi:[0,1,1]
	v_pk_fma_f32 v[34:35], v[72:73], v[66:67], v[34:35] op_sel_hi:[0,1,1]
	s_nop 1
	v_readlane_b32 s100, v133, 3
	v_readlane_b32 s48, v74, 13
	s_lshl_b32 s100, s100, 11
	s_add_u32 s100, s96, s100
	s_addc_u32 s101, s97, 0
	global_load_dwordx4 v[24:27], v254, s[100:101]
	global_load_dwordx4 v[28:31], v254, s[100:101] offset:1024
	s_waitcnt vmcnt(12)
	v_mov_b32_e32 v72, s48
	v_cvt_pk_f32_fp8_e32 v[44:45], v232
	v_cvt_pk_f32_fp8_sdwa v[46:47], v232 src0_sel:WORD_1
	v_cvt_pk_f32_fp8_e32 v[64:65], v233
	v_cvt_pk_f32_fp8_sdwa v[66:67], v233 src0_sel:WORD_1
	v_pk_fma_f32 v[68:69], v[72:73], v[44:45], v[68:69] op_sel_hi:[0,1,1]
	v_pk_fma_f32 v[70:71], v[72:73], v[46:47], v[70:71] op_sel_hi:[0,1,1]
	v_pk_fma_f32 v[60:61], v[72:73], v[64:65], v[60:61] op_sel_hi:[0,1,1]
	v_pk_fma_f32 v[62:63], v[72:73], v[66:67], v[62:63] op_sel_hi:[0,1,1]
	v_cvt_pk_f32_fp8_e32 v[44:45], v234
	v_cvt_pk_f32_fp8_sdwa v[46:47], v234 src0_sel:WORD_1
	v_cvt_pk_f32_fp8_e32 v[64:65], v235
	v_cvt_pk_f32_fp8_sdwa v[66:67], v235 src0_sel:WORD_1
	v_pk_fma_f32 v[56:57], v[72:73], v[44:45], v[56:57] op_sel_hi:[0,1,1]
	v_pk_fma_f32 v[58:59], v[72:73], v[46:47], v[58:59] op_sel_hi:[0,1,1]
	v_pk_fma_f32 v[52:53], v[72:73], v[64:65], v[52:53] op_sel_hi:[0,1,1]
	v_pk_fma_f32 v[54:55], v[72:73], v[66:67], v[54:55] op_sel_hi:[0,1,1]
	v_cvt_pk_f32_fp8_e32 v[44:45], v236
	v_cvt_pk_f32_fp8_sdwa v[46:47], v236 src0_sel:WORD_1
	v_cvt_pk_f32_fp8_e32 v[64:65], v237
	v_cvt_pk_f32_fp8_sdwa v[66:67], v237 src0_sel:WORD_1
	v_pk_fma_f32 v[48:49], v[72:73], v[44:45], v[48:49] op_sel_hi:[0,1,1]
	v_pk_fma_f32 v[50:51], v[72:73], v[46:47], v[50:51] op_sel_hi:[0,1,1]
	v_pk_fma_f32 v[40:41], v[72:73], v[64:65], v[40:41] op_sel_hi:[0,1,1]
	v_pk_fma_f32 v[42:43], v[72:73], v[66:67], v[42:43] op_sel_hi:[0,1,1]
	v_cvt_pk_f32_fp8_e32 v[44:45], v238
	v_cvt_pk_f32_fp8_sdwa v[46:47], v238 src0_sel:WORD_1
	v_cvt_pk_f32_fp8_e32 v[64:65], v239
	v_cvt_pk_f32_fp8_sdwa v[66:67], v239 src0_sel:WORD_1
	v_pk_fma_f32 v[36:37], v[72:73], v[44:45], v[36:37] op_sel_hi:[0,1,1]
	v_pk_fma_f32 v[38:39], v[72:73], v[46:47], v[38:39] op_sel_hi:[0,1,1]
	v_pk_fma_f32 v[32:33], v[72:73], v[64:65], v[32:33] op_sel_hi:[0,1,1]
	v_pk_fma_f32 v[34:35], v[72:73], v[66:67], v[34:35] op_sel_hi:[0,1,1]
	s_nop 1
	v_readlane_b32 s100, v133, 4
	v_readlane_b32 s48, v74, 14
	s_lshl_b32 s100, s100, 11
	s_add_u32 s100, s96, s100
	s_addc_u32 s101, s97, 0
	global_load_dwordx4 v[96:99], v254, s[100:101]
	global_load_dwordx4 v[100:103], v254, s[100:101] offset:1024
	s_waitcnt vmcnt(12)
	v_mov_b32_e32 v72, s48
	v_cvt_pk_f32_fp8_e32 v[44:45], v242
	v_cvt_pk_f32_fp8_sdwa v[46:47], v242 src0_sel:WORD_1
	v_cvt_pk_f32_fp8_e32 v[64:65], v243
	v_cvt_pk_f32_fp8_sdwa v[66:67], v243 src0_sel:WORD_1
	v_pk_fma_f32 v[68:69], v[72:73], v[44:45], v[68:69] op_sel_hi:[0,1,1]
	v_pk_fma_f32 v[70:71], v[72:73], v[46:47], v[70:71] op_sel_hi:[0,1,1]
	v_pk_fma_f32 v[60:61], v[72:73], v[64:65], v[60:61] op_sel_hi:[0,1,1]
	v_pk_fma_f32 v[62:63], v[72:73], v[66:67], v[62:63] op_sel_hi:[0,1,1]
	v_cvt_pk_f32_fp8_e32 v[44:45], v244
	v_cvt_pk_f32_fp8_sdwa v[46:47], v244 src0_sel:WORD_1
	v_cvt_pk_f32_fp8_e32 v[64:65], v245
	v_cvt_pk_f32_fp8_sdwa v[66:67], v245 src0_sel:WORD_1
	v_pk_fma_f32 v[56:57], v[72:73], v[44:45], v[56:57] op_sel_hi:[0,1,1]
	v_pk_fma_f32 v[58:59], v[72:73], v[46:47], v[58:59] op_sel_hi:[0,1,1]
	v_pk_fma_f32 v[52:53], v[72:73], v[64:65], v[52:53] op_sel_hi:[0,1,1]
	v_pk_fma_f32 v[54:55], v[72:73], v[66:67], v[54:55] op_sel_hi:[0,1,1]
	v_cvt_pk_f32_fp8_e32 v[44:45], v246
	v_cvt_pk_f32_fp8_sdwa v[46:47], v246 src0_sel:WORD_1
	v_cvt_pk_f32_fp8_e32 v[64:65], v247
	v_cvt_pk_f32_fp8_sdwa v[66:67], v247 src0_sel:WORD_1
	v_pk_fma_f32 v[48:49], v[72:73], v[44:45], v[48:49] op_sel_hi:[0,1,1]
	v_pk_fma_f32 v[50:51], v[72:73], v[46:47], v[50:51] op_sel_hi:[0,1,1]
	v_pk_fma_f32 v[40:41], v[72:73], v[64:65], v[40:41] op_sel_hi:[0,1,1]
	v_pk_fma_f32 v[42:43], v[72:73], v[66:67], v[42:43] op_sel_hi:[0,1,1]
	v_cvt_pk_f32_fp8_e32 v[44:45], v248
	v_cvt_pk_f32_fp8_sdwa v[46:47], v248 src0_sel:WORD_1
	v_cvt_pk_f32_fp8_e32 v[64:65], v249
	v_cvt_pk_f32_fp8_sdwa v[66:67], v249 src0_sel:WORD_1
	v_pk_fma_f32 v[36:37], v[72:73], v[44:45], v[36:37] op_sel_hi:[0,1,1]
	v_pk_fma_f32 v[38:39], v[72:73], v[46:47], v[38:39] op_sel_hi:[0,1,1]
	v_pk_fma_f32 v[32:33], v[72:73], v[64:65], v[32:33] op_sel_hi:[0,1,1]
	v_pk_fma_f32 v[34:35], v[72:73], v[66:67], v[34:35] op_sel_hi:[0,1,1]
	s_nop 1
	v_readlane_b32 s100, v133, 5
	v_readlane_b32 s48, v74, 15
	s_lshl_b32 s100, s100, 11
	s_add_u32 s100, s96, s100
	s_addc_u32 s101, s97, 0
	global_load_dwordx4 v[104:107], v254, s[100:101]
	global_load_dwordx4 v[108:111], v254, s[100:101] offset:1024
	s_waitcnt vmcnt(12)
	v_mov_b32_e32 v72, s48
	v_cvt_pk_f32_fp8_e32 v[44:45], v250
	v_cvt_pk_f32_fp8_sdwa v[46:47], v250 src0_sel:WORD_1
	v_cvt_pk_f32_fp8_e32 v[64:65], v251
	v_cvt_pk_f32_fp8_sdwa v[66:67], v251 src0_sel:WORD_1
	v_pk_fma_f32 v[68:69], v[72:73], v[44:45], v[68:69] op_sel_hi:[0,1,1]
	v_pk_fma_f32 v[70:71], v[72:73], v[46:47], v[70:71] op_sel_hi:[0,1,1]
	v_pk_fma_f32 v[60:61], v[72:73], v[64:65], v[60:61] op_sel_hi:[0,1,1]
	v_pk_fma_f32 v[62:63], v[72:73], v[66:67], v[62:63] op_sel_hi:[0,1,1]
	v_cvt_pk_f32_fp8_e32 v[44:45], v252
	v_cvt_pk_f32_fp8_sdwa v[46:47], v252 src0_sel:WORD_1
	v_cvt_pk_f32_fp8_e32 v[64:65], v253
	v_cvt_pk_f32_fp8_sdwa v[66:67], v253 src0_sel:WORD_1
	v_pk_fma_f32 v[56:57], v[72:73], v[44:45], v[56:57] op_sel_hi:[0,1,1]
	v_pk_fma_f32 v[58:59], v[72:73], v[46:47], v[58:59] op_sel_hi:[0,1,1]
	v_pk_fma_f32 v[52:53], v[72:73], v[64:65], v[52:53] op_sel_hi:[0,1,1]
	v_pk_fma_f32 v[54:55], v[72:73], v[66:67], v[54:55] op_sel_hi:[0,1,1]
	v_cvt_pk_f32_fp8_e32 v[44:45], v76
	v_cvt_pk_f32_fp8_sdwa v[46:47], v76 src0_sel:WORD_1
	v_cvt_pk_f32_fp8_e32 v[64:65], v77
	v_cvt_pk_f32_fp8_sdwa v[66:67], v77 src0_sel:WORD_1
	v_pk_fma_f32 v[48:49], v[72:73], v[44:45], v[48:49] op_sel_hi:[0,1,1]
	v_pk_fma_f32 v[50:51], v[72:73], v[46:47], v[50:51] op_sel_hi:[0,1,1]
	v_pk_fma_f32 v[40:41], v[72:73], v[64:65], v[40:41] op_sel_hi:[0,1,1]
	v_pk_fma_f32 v[42:43], v[72:73], v[66:67], v[42:43] op_sel_hi:[0,1,1]
	v_cvt_pk_f32_fp8_e32 v[44:45], v78
	v_cvt_pk_f32_fp8_sdwa v[46:47], v78 src0_sel:WORD_1
	v_cvt_pk_f32_fp8_e32 v[64:65], v79
	v_cvt_pk_f32_fp8_sdwa v[66:67], v79 src0_sel:WORD_1
	v_pk_fma_f32 v[36:37], v[72:73], v[44:45], v[36:37] op_sel_hi:[0,1,1]
	v_pk_fma_f32 v[38:39], v[72:73], v[46:47], v[38:39] op_sel_hi:[0,1,1]
	v_pk_fma_f32 v[32:33], v[72:73], v[64:65], v[32:33] op_sel_hi:[0,1,1]
	v_pk_fma_f32 v[34:35], v[72:73], v[66:67], v[34:35] op_sel_hi:[0,1,1]

.LBB0_2775:
	s_or_b64 exec, exec, s[42:43]
	s_add_u32 s48, s92, 0x3dc24000
	s_addc_u32 s49, s93, 0
	s_add_u32 s42, s92, 0x4d50000
	s_addc_u32 s43, s93, 0
	s_add_u32 s44, s92, 0x4d70000
	s_waitcnt lgkmcnt(1)
	v_max_u32_dpp v3, v2, v2 quad_perm:[1,0,3,2] row_mask:0xf bank_mask:0xf bound_ctrl:1
	s_addc_u32 s45, s93, 0
	s_add_u32 s46, s92, 0x5f64000
	v_max_u32_dpp v3, v3, v3 quad_perm:[2,3,0,1] row_mask:0xf bank_mask:0xf bound_ctrl:1
	s_addc_u32 s47, s93, 0
	s_add_u32 s50, s92, 0x14224000
	v_max_u32_dpp v3, v3, v3 row_half_mirror row_mask:0xf bank_mask:0xf bound_ctrl:1
	s_addc_u32 s51, s93, 0
	v_bitop3_b32 v1, v1, s54, v1 bitop3:0xc
	v_max_u32_dpp v3, v3, v3 row_mirror row_mask:0xf bank_mask:0xf bound_ctrl:1
	v_bitop3_b32 v0, v0, s54, v0 bitop3:0xc
	v_readlane_b32 s52, v3, 32
	v_readlane_b32 s53, v3, 48
	v_readlane_b32 s40, v3, 16
	s_max_u32 s52, s52, s53
	v_readlane_b32 s3, v3, 0
	v_mov_b32_e32 v3, s40
	s_waitcnt lgkmcnt(0)
	v_mov_b32_e32 v4, s52
	v_max3_u32 v3, s3, v3, v4
	v_cmp_ne_u32_e32 vcc, v2, v3
	v_cndmask_b32_e64 v3, 0, v3, s[6:7]
	v_lshlrev_b32_e32 v38, 4, v156
	v_cndmask_b32_e32 v2, 0, v2, vcc
	v_lshlrev_b32_e32 v166, 2, v162
	v_lshl_add_u64 v[36:37], s[86:87], 0, v[36:37]
	v_max_u32_dpp v4, v2, v2 quad_perm:[1,0,3,2] row_mask:0xf bank_mask:0xf bound_ctrl:1
	v_lshlrev_b32_e32 v167, 4, v190
	v_lshl_add_u64 v[120:121], v[36:37], 0, v[32:33]
	v_max_u32_dpp v4, v4, v4 quad_perm:[2,3,0,1] row_mask:0xf bank_mask:0xf bound_ctrl:1
	s_mov_b32 s55, 0x378e98ab
	s_mov_b32 s62, 0x42ce8ed0
	v_max_u32_dpp v4, v4, v4 row_half_mirror row_mask:0xf bank_mask:0xf bound_ctrl:1
	s_mov_b32 s63, 0xc2b17218
	v_mov_b32_e32 v169, 0x3ba10414
	v_max_u32_dpp v4, v4, v4 row_mirror row_mask:0xf bank_mask:0xf bound_ctrl:1
	s_brev_b32 s64, -2
	v_readlane_b32 s52, v4, 32
	v_readlane_b32 s53, v4, 48
	v_readlane_b32 s40, v4, 16
	s_max_u32 s52, s52, s53
	v_readlane_b32 s3, v4, 0
	v_mov_b32_e32 v4, s40
	v_mov_b32_e32 v5, s52
	v_max3_u32 v4, s3, v4, v5
	v_cmp_ne_u32_e32 vcc, v2, v4
	v_cndmask_b32_e64 v3, v3, v4, s[8:9]
	v_mov_b32_e32 v171, 0xb9c68948
	v_cndmask_b32_e32 v2, 0, v2, vcc
	v_mov_b32_e32 v172, 0x7f800000
	s_nop 0
	v_max_u32_dpp v4, v2, v2 quad_perm:[1,0,3,2] row_mask:0xf bank_mask:0xf bound_ctrl:1
	s_nop 1
	v_max_u32_dpp v4, v4, v4 quad_perm:[2,3,0,1] row_mask:0xf bank_mask:0xf bound_ctrl:1
	s_nop 1
	v_max_u32_dpp v4, v4, v4 row_half_mirror row_mask:0xf bank_mask:0xf bound_ctrl:1
	s_nop 1
	v_max_u32_dpp v4, v4, v4 row_mirror row_mask:0xf bank_mask:0xf bound_ctrl:1
	s_nop 0
	v_readlane_b32 s52, v4, 32
	v_readlane_b32 s53, v4, 48
	v_readlane_b32 s40, v4, 16
	s_max_u32 s52, s52, s53
	v_readlane_b32 s3, v4, 0
	v_mov_b32_e32 v4, s40
	v_mov_b32_e32 v5, s52
	v_max3_u32 v4, s3, v4, v5
	v_cmp_ne_u32_e32 vcc, v2, v4
	v_cndmask_b32_e64 v3, v3, v4, s[10:11]
	s_nop 0
	v_cndmask_b32_e32 v2, 0, v2, vcc
	s_nop 1
	v_max_u32_dpp v4, v2, v2 quad_perm:[1,0,3,2] row_mask:0xf bank_mask:0xf bound_ctrl:1
	s_nop 1
	v_max_u32_dpp v4, v4, v4 quad_perm:[2,3,0,1] row_mask:0xf bank_mask:0xf bound_ctrl:1
	s_nop 1
	v_max_u32_dpp v4, v4, v4 row_half_mirror row_mask:0xf bank_mask:0xf bound_ctrl:1
	s_nop 1
	v_max_u32_dpp v4, v4, v4 row_mirror row_mask:0xf bank_mask:0xf bound_ctrl:1
	s_nop 0
	v_readlane_b32 s52, v4, 32
	v_readlane_b32 s53, v4, 48
	v_readlane_b32 s40, v4, 16
	s_max_u32 s52, s52, s53
	v_readlane_b32 s3, v4, 0
	v_mov_b32_e32 v4, s40
	v_mov_b32_e32 v5, s52
	v_max3_u32 v4, s3, v4, v5
	v_cmp_ne_u32_e32 vcc, v2, v4
	v_cndmask_b32_e64 v3, v3, v4, s[12:13]
	s_nop 0
	v_cndmask_b32_e32 v2, 0, v2, vcc
	s_nop 1
	v_max_u32_dpp v4, v2, v2 quad_perm:[1,0,3,2] row_mask:0xf bank_mask:0xf bound_ctrl:1
	s_nop 1
	v_max_u32_dpp v4, v4, v4 quad_perm:[2,3,0,1] row_mask:0xf bank_mask:0xf bound_ctrl:1
	s_nop 1
	v_max_u32_dpp v4, v4, v4 row_half_mirror row_mask:0xf bank_mask:0xf bound_ctrl:1
	s_nop 1
	v_max_u32_dpp v4, v4, v4 row_mirror row_mask:0xf bank_mask:0xf bound_ctrl:1
	s_nop 0
	v_readlane_b32 s52, v4, 32
	v_readlane_b32 s53, v4, 48
	v_readlane_b32 s40, v4, 16
	s_max_u32 s52, s52, s53
	v_readlane_b32 s3, v4, 0
	v_mov_b32_e32 v4, s40
	v_mov_b32_e32 v5, s52
	v_max3_u32 v4, s3, v4, v5
	v_cmp_ne_u32_e32 vcc, v2, v4
	v_cndmask_b32_e64 v3, v3, v4, s[14:15]
	s_nop 0
	v_cndmask_b32_e32 v2, 0, v2, vcc
	s_nop 1
	v_max_u32_dpp v4, v2, v2 quad_perm:[1,0,3,2] row_mask:0xf bank_mask:0xf bound_ctrl:1
	s_nop 1
	v_max_u32_dpp v4, v4, v4 quad_perm:[2,3,0,1] row_mask:0xf bank_mask:0xf bound_ctrl:1
	s_nop 1
	v_max_u32_dpp v4, v4, v4 row_half_mirror row_mask:0xf bank_mask:0xf bound_ctrl:1
	s_nop 1
	v_max_u32_dpp v4, v4, v4 row_mirror row_mask:0xf bank_mask:0xf bound_ctrl:1
	s_nop 0
	v_readlane_b32 s52, v4, 32
	v_readlane_b32 s53, v4, 48
	v_readlane_b32 s40, v4, 16
	s_max_u32 s52, s52, s53
	v_readlane_b32 s3, v4, 0
	v_mov_b32_e32 v4, s40
	v_mov_b32_e32 v5, s52
	v_max3_u32 v4, s3, v4, v5
	v_cmp_ne_u32_e32 vcc, v2, v4
	v_cndmask_b32_e64 v3, v3, v4, s[16:17]
	s_nop 0
	v_cndmask_b32_e32 v2, 0, v2, vcc
	s_nop 1
	v_max_u32_dpp v4, v2, v2 quad_perm:[1,0,3,2] row_mask:0xf bank_mask:0xf bound_ctrl:1
	s_nop 1
	v_max_u32_dpp v4, v4, v4 quad_perm:[2,3,0,1] row_mask:0xf bank_mask:0xf bound_ctrl:1
	s_nop 1
	v_max_u32_dpp v4, v4, v4 row_half_mirror row_mask:0xf bank_mask:0xf bound_ctrl:1
	s_nop 1
	v_max_u32_dpp v4, v4, v4 row_mirror row_mask:0xf bank_mask:0xf bound_ctrl:1
	s_nop 0
	v_readlane_b32 s52, v4, 32
	v_readlane_b32 s53, v4, 48
	v_readlane_b32 s40, v4, 16
	s_max_u32 s52, s52, s53
	v_readlane_b32 s3, v4, 0
	v_mov_b32_e32 v4, s40
	v_mov_b32_e32 v5, s52
	v_max3_u32 v4, s3, v4, v5
	v_cmp_ne_u32_e32 vcc, v2, v4
	v_cndmask_b32_e64 v3, v3, v4, s[18:19]
	s_nop 0
	v_cndmask_b32_e32 v2, 0, v2, vcc
	s_nop 1
	v_max_u32_dpp v4, v2, v2 quad_perm:[1,0,3,2] row_mask:0xf bank_mask:0xf bound_ctrl:1
	s_nop 1
	v_max_u32_dpp v4, v4, v4 quad_perm:[2,3,0,1] row_mask:0xf bank_mask:0xf bound_ctrl:1
	s_nop 1
	v_max_u32_dpp v4, v4, v4 row_half_mirror row_mask:0xf bank_mask:0xf bound_ctrl:1
	s_nop 1
	v_max_u32_dpp v4, v4, v4 row_mirror row_mask:0xf bank_mask:0xf bound_ctrl:1
	s_nop 0
	v_readlane_b32 s52, v4, 32
	v_readlane_b32 s53, v4, 48
	v_readlane_b32 s40, v4, 16
	s_max_u32 s52, s52, s53
	v_readlane_b32 s3, v4, 0
	v_mov_b32_e32 v4, s40
	v_mov_b32_e32 v5, s52
	v_max3_u32 v4, s3, v4, v5
	v_cmp_ne_u32_e32 vcc, v2, v4
	v_cndmask_b32_e64 v3, v3, v4, s[20:21]
	s_nop 0
	v_cndmask_b32_e32 v2, 0, v2, vcc
	s_nop 1
	v_max_u32_dpp v4, v2, v2 quad_perm:[1,0,3,2] row_mask:0xf bank_mask:0xf bound_ctrl:1
	s_nop 1
	v_max_u32_dpp v4, v4, v4 quad_perm:[2,3,0,1] row_mask:0xf bank_mask:0xf bound_ctrl:1
	s_nop 1
	v_max_u32_dpp v4, v4, v4 row_half_mirror row_mask:0xf bank_mask:0xf bound_ctrl:1
	s_nop 1
	v_max_u32_dpp v4, v4, v4 row_mirror row_mask:0xf bank_mask:0xf bound_ctrl:1
	s_nop 0
	v_readlane_b32 s52, v4, 32
	v_readlane_b32 s53, v4, 48
	v_readlane_b32 s40, v4, 16
	s_max_u32 s52, s52, s53
	v_readlane_b32 s3, v4, 0
	v_mov_b32_e32 v4, s40
	v_mov_b32_e32 v5, s52
	v_max3_u32 v4, s3, v4, v5
	v_cmp_ne_u32_e32 vcc, v2, v4
	v_cndmask_b32_e64 v3, v3, v4, s[22:23]
	s_nop 0
	v_cndmask_b32_e32 v2, 0, v2, vcc
	s_nop 1
	v_max_u32_dpp v4, v2, v2 quad_perm:[1,0,3,2] row_mask:0xf bank_mask:0xf bound_ctrl:1
	s_nop 1
	v_max_u32_dpp v4, v4, v4 quad_perm:[2,3,0,1] row_mask:0xf bank_mask:0xf bound_ctrl:1
	s_nop 1
	v_max_u32_dpp v4, v4, v4 row_half_mirror row_mask:0xf bank_mask:0xf bound_ctrl:1
	s_nop 1
	v_max_u32_dpp v4, v4, v4 row_mirror row_mask:0xf bank_mask:0xf bound_ctrl:1
	s_nop 0
	v_readlane_b32 s52, v4, 32
	v_readlane_b32 s53, v4, 48
	v_readlane_b32 s40, v4, 16
	s_max_u32 s52, s52, s53
	v_readlane_b32 s3, v4, 0
	v_mov_b32_e32 v4, s40
	v_mov_b32_e32 v5, s52
	v_max3_u32 v4, s3, v4, v5
	v_cmp_ne_u32_e32 vcc, v2, v4
	v_cndmask_b32_e64 v3, v3, v4, s[24:25]
	s_nop 0
	v_cndmask_b32_e32 v2, 0, v2, vcc
	s_nop 1
	v_max_u32_dpp v4, v2, v2 quad_perm:[1,0,3,2] row_mask:0xf bank_mask:0xf bound_ctrl:1
	s_nop 1
	v_max_u32_dpp v4, v4, v4 quad_perm:[2,3,0,1] row_mask:0xf bank_mask:0xf bound_ctrl:1
	s_nop 1
	v_max_u32_dpp v4, v4, v4 row_half_mirror row_mask:0xf bank_mask:0xf bound_ctrl:1
	s_nop 1
	v_max_u32_dpp v4, v4, v4 row_mirror row_mask:0xf bank_mask:0xf bound_ctrl:1
	s_nop 0
	v_readlane_b32 s52, v4, 32
	v_readlane_b32 s53, v4, 48
	v_readlane_b32 s40, v4, 16
	s_max_u32 s52, s52, s53
	v_readlane_b32 s3, v4, 0
	v_mov_b32_e32 v4, s40
	v_mov_b32_e32 v5, s52
	v_max3_u32 v4, s3, v4, v5
	v_cmp_ne_u32_e32 vcc, v2, v4
	v_cndmask_b32_e64 v3, v3, v4, s[26:27]
	s_nop 0
	v_cndmask_b32_e32 v2, 0, v2, vcc
	s_nop 1
	v_max_u32_dpp v4, v2, v2 quad_perm:[1,0,3,2] row_mask:0xf bank_mask:0xf bound_ctrl:1
	s_nop 1
	v_max_u32_dpp v4, v4, v4 quad_perm:[2,3,0,1] row_mask:0xf bank_mask:0xf bound_ctrl:1
	s_nop 1
	v_max_u32_dpp v4, v4, v4 row_half_mirror row_mask:0xf bank_mask:0xf bound_ctrl:1
	s_nop 1
	v_max_u32_dpp v4, v4, v4 row_mirror row_mask:0xf bank_mask:0xf bound_ctrl:1
	s_nop 0
	v_readlane_b32 s52, v4, 32
	v_readlane_b32 s53, v4, 48
	v_readlane_b32 s40, v4, 16
	s_max_u32 s52, s52, s53
	v_readlane_b32 s3, v4, 0
	v_mov_b32_e32 v4, s40
	v_mov_b32_e32 v5, s52
	v_max3_u32 v4, s3, v4, v5
	v_cmp_ne_u32_e32 vcc, v2, v4
	v_cndmask_b32_e64 v3, v3, v4, s[28:29]
	s_nop 0
	v_cndmask_b32_e32 v2, 0, v2, vcc
	s_nop 1
	v_max_u32_dpp v4, v2, v2 quad_perm:[1,0,3,2] row_mask:0xf bank_mask:0xf bound_ctrl:1
	s_nop 1
	v_max_u32_dpp v4, v4, v4 quad_perm:[2,3,0,1] row_mask:0xf bank_mask:0xf bound_ctrl:1
	s_nop 1
	v_max_u32_dpp v4, v4, v4 row_half_mirror row_mask:0xf bank_mask:0xf bound_ctrl:1
	s_nop 1
	v_max_u32_dpp v4, v4, v4 row_mirror row_mask:0xf bank_mask:0xf bound_ctrl:1
	s_nop 0
	v_readlane_b32 s52, v4, 32
	v_readlane_b32 s53, v4, 48
	v_readlane_b32 s40, v4, 16
	s_max_u32 s52, s52, s53
	v_readlane_b32 s3, v4, 0
	v_mov_b32_e32 v4, s40
	v_mov_b32_e32 v5, s52
	v_max3_u32 v4, s3, v4, v5
	v_cmp_ne_u32_e32 vcc, v2, v4
	v_cndmask_b32_e64 v3, v3, v4, s[30:31]
	s_nop 0
	v_cndmask_b32_e32 v2, 0, v2, vcc
	s_nop 1
	v_max_u32_dpp v4, v2, v2 quad_perm:[1,0,3,2] row_mask:0xf bank_mask:0xf bound_ctrl:1
	s_nop 1
	v_max_u32_dpp v4, v4, v4 quad_perm:[2,3,0,1] row_mask:0xf bank_mask:0xf bound_ctrl:1
	s_nop 1
	v_max_u32_dpp v4, v4, v4 row_half_mirror row_mask:0xf bank_mask:0xf bound_ctrl:1
	s_nop 1
	v_max_u32_dpp v4, v4, v4 row_mirror row_mask:0xf bank_mask:0xf bound_ctrl:1
	s_nop 0
	v_readlane_b32 s52, v4, 32
	v_readlane_b32 s53, v4, 48
	v_readlane_b32 s40, v4, 16
	s_max_u32 s52, s52, s53
	v_readlane_b32 s3, v4, 0
	v_mov_b32_e32 v4, s40
	v_mov_b32_e32 v5, s52
	v_max3_u32 v4, s3, v4, v5
	v_cmp_ne_u32_e32 vcc, v2, v4
	v_cndmask_b32_e64 v3, v3, v4, s[34:35]
	s_nop 0
	v_cndmask_b32_e32 v2, 0, v2, vcc
	s_nop 1
	v_max_u32_dpp v4, v2, v2 quad_perm:[1,0,3,2] row_mask:0xf bank_mask:0xf bound_ctrl:1
	s_nop 1
	v_max_u32_dpp v4, v4, v4 quad_perm:[2,3,0,1] row_mask:0xf bank_mask:0xf bound_ctrl:1
	s_nop 1
	v_max_u32_dpp v4, v4, v4 row_half_mirror row_mask:0xf bank_mask:0xf bound_ctrl:1
	s_nop 1
	v_max_u32_dpp v4, v4, v4 row_mirror row_mask:0xf bank_mask:0xf bound_ctrl:1
	s_nop 0
	v_readlane_b32 s52, v4, 32
	v_readlane_b32 s53, v4, 48
	v_readlane_b32 s40, v4, 16
	s_max_u32 s52, s52, s53
	v_readlane_b32 s3, v4, 0
	v_mov_b32_e32 v4, s40
	v_mov_b32_e32 v5, s52
	v_max3_u32 v4, s3, v4, v5
	v_cmp_ne_u32_e32 vcc, v2, v4
	v_cndmask_b32_e64 v3, v3, v4, s[36:37]
	s_nop 0
	v_cndmask_b32_e32 v2, 0, v2, vcc
	s_nop 1
	v_max_u32_dpp v2, v2, v2 quad_perm:[1,0,3,2] row_mask:0xf bank_mask:0xf bound_ctrl:1
	s_nop 1
	v_max_u32_dpp v2, v2, v2 quad_perm:[2,3,0,1] row_mask:0xf bank_mask:0xf bound_ctrl:1
	s_nop 1
	v_max_u32_dpp v2, v2, v2 row_half_mirror row_mask:0xf bank_mask:0xf bound_ctrl:1
	s_nop 1
	v_max_u32_dpp v2, v2, v2 row_mirror row_mask:0xf bank_mask:0xf bound_ctrl:1
	s_nop 0
	v_readlane_b32 s52, v2, 32
	v_readlane_b32 s53, v2, 48
	v_readlane_b32 s40, v2, 16
	s_max_u32 s52, s52, s53
	v_readlane_b32 s3, v2, 0
	v_mov_b32_e32 v2, s40
	v_mov_b32_e32 v4, s52
	v_max3_u32 v2, s3, v2, v4
	v_cndmask_b32_e64 v35, v3, v2, s[38:39]
	v_and_or_b32 v2, v35, 63, v162
	v_lshlrev_b32_e32 v2, 2, v2
	v_xor_b32_e32 v2, 0xfc, v2
	ds_bpermute_b32 v3, v2, v161
	ds_bpermute_b32 v2, v2, v157
	s_mov_b32 s53, s41
	v_cmp_lt_i32_e32 vcc, -1, v35
	s_waitcnt lgkmcnt(1)
	v_and_or_b32 v3, v3, 63, v162
	s_waitcnt lgkmcnt(0)
	v_and_or_b32 v2, v2, 63, v162
	v_lshlrev_b32_e32 v3, 2, v3
	v_lshlrev_b32_e32 v2, 2, v2
	ds_bpermute_b32 v0, v3, v0
	ds_bpermute_b32 v1, v2, v1
	v_cndmask_b32_e64 v39, v159, -1, vcc
	v_bitop3_b32 v35, v39, v35, s33 bitop3:0x78
	ds_bpermute_b32 v39, v166, v35
	s_waitcnt lgkmcnt(1)
	v_lshl_add_u32 v0, v0, 7, v1
	v_and_or_b32 v1, v190, 15, v162
	v_and_b32_e32 v0, 0x3fff, v0
	v_lshlrev_b32_e32 v165, 2, v1
	ds_bpermute_b32 v122, v165, v0
	s_waitcnt lgkmcnt(1)
	v_sub_f32_e32 v35, v35, v39
	v_mul_f32_e32 v35, 0x3fb8aa3b, v35
	v_exp_f32_e32 v35, v35
	s_waitcnt lgkmcnt(0)
	v_readlane_b32 s40, v122, 1
	s_lshl_b64 s[56:57], s[40:41], 11
	s_add_u32 s58, s50, s56
	s_addc_u32 s59, s51, s57
	v_readlane_b32 s52, v122, 0
	s_add_u32 s56, s48, s56
	s_addc_u32 s57, s49, s57
	s_lshl_b64 s[52:53], s[52:53], 11
	s_add_u32 s56, s50, s52
	s_addc_u32 s57, s51, s53
	s_add_u32 s52, s48, s52
	s_addc_u32 s53, s49, s53
	v_cndmask_b32_e64 v35, 0, v35, s[4:5]
	s_mov_b32 s56, 0x3b7cd369
	s_mov_b32 s57, 0xbcc618b2
	v_add_f32_dpp v39, v35, v35 quad_perm:[1,0,3,2] row_mask:0xf bank_mask:0xf bound_ctrl:1
	s_mov_b32 s58, 0x3dda74e4
	s_mov_b32 s59, 0x3f228afd
	v_add_f32_dpp v39, v39, v39 quad_perm:[2,3,0,1] row_mask:0xf bank_mask:0xf bound_ctrl:1
	s_nop 1
	v_add_f32_dpp v39, v39, v39 row_half_mirror row_mask:0xf bank_mask:0xf bound_ctrl:1
	s_nop 1
	v_add_f32_dpp v39, v39, v39 row_mirror row_mask:0xf bank_mask:0xf bound_ctrl:1
	s_nop 0
	v_readlane_b32 s3, v39, 16
	v_readlane_b32 s40, v39, 48
	v_readlane_b32 s52, v39, 0
	v_readlane_b32 s53, v39, 32
	v_mov_b32_e32 v40, s3
	v_mov_b32_e32 v41, s40
	v_pk_add_f32 v[40:41], s[52:53], v[40:41]
	s_nop 0
	v_add_f32_e32 v39, v40, v41
	v_div_scale_f32 v40, s[52:53], v39, v39, v35
	v_rcp_f32_e32 v41, v40
	s_nop 0
	v_fma_f32 v42, -v40, v41, 1.0
	v_fmac_f32_e32 v41, v42, v41
	v_div_scale_f32 v42, vcc, v35, v39, v35
	v_mul_f32_e32 v43, v42, v41
	v_fma_f32 v44, -v40, v43, v42
	v_fmac_f32_e32 v43, v44, v41
	v_fma_f32 v40, -v40, v43, v42
	v_div_fmas_f32 v40, v40, v41, v43
	v_div_fixup_f32 v35, v40, v39, v35
	ds_bpermute_b32 v173, v165, v35
	v_mov_b32_e32 v39, v33
	v_lshl_add_u64 v[114:115], s[48:49], 0, v[38:39]
	v_lshl_add_u64 v[116:117], s[50:51], 0, v[38:39]
	s_mov_b64 s[96:97], s[48:49]
	s_mov_b64 s[98:99], s[50:51]
	v_readlane_b32 s100, v122, 0
	s_nop 0
	s_lshl_b32 s100, s100, 11
	s_add_u32 s100, s96, s100
	s_addc_u32 s101, s97, 0
	global_load_dwordx4 v[0:3], v38, s[100:101]
	global_load_dwordx4 v[4:7], v38, s[100:101] offset:1024
	v_readlane_b32 s100, v122, 1
	s_nop 0
	s_lshl_b32 s100, s100, 11
	s_add_u32 s100, s96, s100
	s_addc_u32 s101, s97, 0
	global_load_dwordx4 v[8:11], v38, s[100:101]
	global_load_dwordx4 v[16:19], v38, s[100:101] offset:1024
	v_readlane_b32 s100, v122, 2
	s_nop 0
	s_lshl_b32 s100, s100, 11
	s_add_u32 s100, s96, s100
	s_addc_u32 s101, s97, 0
	global_load_dwordx4 v[80:83], v38, s[100:101]
	global_load_dwordx4 v[84:87], v38, s[100:101] offset:1024
	v_readlane_b32 s100, v122, 3
	s_nop 0
	s_lshl_b32 s100, s100, 11
	s_add_u32 s100, s96, s100
	s_addc_u32 s101, s97, 0
	global_load_dwordx4 v[88:91], v38, s[100:101]
	global_load_dwordx4 v[92:95], v38, s[100:101] offset:1024
	v_readlane_b32 s100, v122, 4
	s_nop 0
	s_lshl_b32 s100, s100, 11
	s_add_u32 s100, s96, s100
	s_addc_u32 s101, s97, 0
	global_load_dwordx4 v[96:99], v38, s[100:101]
	global_load_dwordx4 v[100:103], v38, s[100:101] offset:1024
	v_readlane_b32 s100, v122, 5
	s_nop 0
	s_lshl_b32 s100, s100, 11
	s_add_u32 s100, s96, s100
	s_addc_u32 s101, s97, 0
	global_load_dwordx4 v[104:107], v38, s[100:101]
	global_load_dwordx4 v[108:111], v38, s[100:101] offset:1024
	v_lshlrev_b32_e32 v38, 13, v34
	v_lshlrev_b32_e32 v34, 2, v190
	v_lshlrev_b32_e32 v42, 6, v156
	v_lshlrev_b32_e32 v40, 5, v156
	v_mov_b32_e32 v41, v33
	v_ashrrev_i32_e32 v35, 31, v34
	v_lshl_add_u64 v[112:113], s[60:61], 0, v[40:41]
	v_add_u32_e32 v168, 0x2800, v34
	v_lshl_add_u64 v[118:119], v[34:35], 2, s[90:91]
	s_mov_b32 s60, 0x3e03c728
	s_mov_b32 s61, 0xbfb8aa3b
	v_add_u32_e32 v170, v42, v38
	s_branch .LBB0_2777

.LBB0_2779:
	s_or_b64 exec, exec, s[48:49]
	s_waitcnt lgkmcnt(1)
	v_max_u32_dpp v36, v35, v35 quad_perm:[1,0,3,2] row_mask:0xf bank_mask:0xf bound_ctrl:1
	v_bitop3_b32 v32, v32, s54, v32 bitop3:0xc
	v_ashrrev_i32_e32 v123, 31, v122
	v_max_u32_dpp v36, v36, v36 quad_perm:[2,3,0,1] row_mask:0xf bank_mask:0xf bound_ctrl:1
	s_mov_b32 s70, 0
	s_mov_b32 s71, 5
	v_max_u32_dpp v36, v36, v36 row_half_mirror row_mask:0xf bank_mask:0xf bound_ctrl:1
	v_mov_b32_e32 v58, v34
	v_mov_b32_e32 v59, v34
	v_max_u32_dpp v36, v36, v36 row_mirror row_mask:0xf bank_mask:0xf bound_ctrl:1
	v_mov_b32_e32 v57, v34
	v_readlane_b32 s48, v36, 32
	v_readlane_b32 s49, v36, 48
	v_readlane_b32 s40, v36, 16
	s_max_u32 s48, s48, s49
	v_readlane_b32 s3, v36, 0
	v_mov_b32_e32 v36, s40
	s_waitcnt lgkmcnt(0)
	v_mov_b32_e32 v37, s48
	v_max3_u32 v36, s3, v36, v37
	v_cmp_ne_u32_e32 vcc, v35, v36
	v_cndmask_b32_e64 v36, 0, v36, s[6:7]
	v_mov_b32_e32 v62, v34
	v_cndmask_b32_e32 v35, 0, v35, vcc
	v_mov_b32_e32 v63, v34
	v_mov_b32_e32 v60, v34
	v_max_u32_dpp v37, v35, v35 quad_perm:[1,0,3,2] row_mask:0xf bank_mask:0xf bound_ctrl:1
	v_mov_b32_e32 v61, v34
	s_nop 0
	v_max_u32_dpp v37, v37, v37 quad_perm:[2,3,0,1] row_mask:0xf bank_mask:0xf bound_ctrl:1
	s_nop 1
	v_max_u32_dpp v37, v37, v37 row_half_mirror row_mask:0xf bank_mask:0xf bound_ctrl:1
	s_nop 1
	v_max_u32_dpp v37, v37, v37 row_mirror row_mask:0xf bank_mask:0xf bound_ctrl:1
	s_nop 0
	v_readlane_b32 s48, v37, 32
	v_readlane_b32 s49, v37, 48
	v_readlane_b32 s40, v37, 16
	s_max_u32 s48, s48, s49
	v_readlane_b32 s3, v37, 0
	v_mov_b32_e32 v37, s40
	v_mov_b32_e32 v38, s48
	v_max3_u32 v37, s3, v37, v38
	v_cmp_ne_u32_e32 vcc, v35, v37
	v_cndmask_b32_e64 v36, v36, v37, s[8:9]
	s_nop 0
	v_cndmask_b32_e32 v35, 0, v35, vcc
	s_nop 1
	v_max_u32_dpp v37, v35, v35 quad_perm:[1,0,3,2] row_mask:0xf bank_mask:0xf bound_ctrl:1
	s_nop 1
	v_max_u32_dpp v37, v37, v37 quad_perm:[2,3,0,1] row_mask:0xf bank_mask:0xf bound_ctrl:1
	s_nop 1
	v_max_u32_dpp v37, v37, v37 row_half_mirror row_mask:0xf bank_mask:0xf bound_ctrl:1
	s_nop 1
	v_max_u32_dpp v37, v37, v37 row_mirror row_mask:0xf bank_mask:0xf bound_ctrl:1
	s_nop 0
	v_readlane_b32 s48, v37, 32
	v_readlane_b32 s49, v37, 48
	v_readlane_b32 s40, v37, 16
	s_max_u32 s48, s48, s49
	v_readlane_b32 s3, v37, 0
	v_mov_b32_e32 v37, s40
	v_mov_b32_e32 v38, s48
	v_max3_u32 v37, s3, v37, v38
	v_cmp_ne_u32_e32 vcc, v35, v37
	v_cndmask_b32_e64 v36, v36, v37, s[10:11]
	s_nop 0
	v_cndmask_b32_e32 v35, 0, v35, vcc
	s_nop 1
	v_max_u32_dpp v37, v35, v35 quad_perm:[1,0,3,2] row_mask:0xf bank_mask:0xf bound_ctrl:1
	s_nop 1
	v_max_u32_dpp v37, v37, v37 quad_perm:[2,3,0,1] row_mask:0xf bank_mask:0xf bound_ctrl:1
	s_nop 1
	v_max_u32_dpp v37, v37, v37 row_half_mirror row_mask:0xf bank_mask:0xf bound_ctrl:1
	s_nop 1
	v_max_u32_dpp v37, v37, v37 row_mirror row_mask:0xf bank_mask:0xf bound_ctrl:1
	s_nop 0
	v_readlane_b32 s48, v37, 32
	v_readlane_b32 s49, v37, 48
	v_readlane_b32 s40, v37, 16
	s_max_u32 s48, s48, s49
	v_readlane_b32 s3, v37, 0
	v_mov_b32_e32 v37, s40
	v_mov_b32_e32 v38, s48
	v_max3_u32 v37, s3, v37, v38
	v_cmp_ne_u32_e32 vcc, v35, v37
	v_cndmask_b32_e64 v36, v36, v37, s[12:13]
	s_nop 0
	v_cndmask_b32_e32 v35, 0, v35, vcc
	s_nop 1
	v_max_u32_dpp v37, v35, v35 quad_perm:[1,0,3,2] row_mask:0xf bank_mask:0xf bound_ctrl:1
	s_nop 1
	v_max_u32_dpp v37, v37, v37 quad_perm:[2,3,0,1] row_mask:0xf bank_mask:0xf bound_ctrl:1
	s_nop 1
	v_max_u32_dpp v37, v37, v37 row_half_mirror row_mask:0xf bank_mask:0xf bound_ctrl:1
	s_nop 1
	v_max_u32_dpp v37, v37, v37 row_mirror row_mask:0xf bank_mask:0xf bound_ctrl:1
	s_nop 0
	v_readlane_b32 s48, v37, 32
	v_readlane_b32 s49, v37, 48
	v_readlane_b32 s40, v37, 16
	s_max_u32 s48, s48, s49
	v_readlane_b32 s3, v37, 0
	v_mov_b32_e32 v37, s40
	v_mov_b32_e32 v38, s48
	v_max3_u32 v37, s3, v37, v38
	v_cmp_ne_u32_e32 vcc, v35, v37
	v_cndmask_b32_e64 v36, v36, v37, s[14:15]
	s_nop 0
	v_cndmask_b32_e32 v35, 0, v35, vcc
	s_nop 1
	v_max_u32_dpp v37, v35, v35 quad_perm:[1,0,3,2] row_mask:0xf bank_mask:0xf bound_ctrl:1
	s_nop 1
	v_max_u32_dpp v37, v37, v37 quad_perm:[2,3,0,1] row_mask:0xf bank_mask:0xf bound_ctrl:1
	s_nop 1
	v_max_u32_dpp v37, v37, v37 row_half_mirror row_mask:0xf bank_mask:0xf bound_ctrl:1
	s_nop 1
	v_max_u32_dpp v37, v37, v37 row_mirror row_mask:0xf bank_mask:0xf bound_ctrl:1
	s_nop 0
	v_readlane_b32 s48, v37, 32
	v_readlane_b32 s49, v37, 48
	v_readlane_b32 s40, v37, 16
	s_max_u32 s48, s48, s49
	v_readlane_b32 s3, v37, 0
	v_mov_b32_e32 v37, s40
	v_mov_b32_e32 v38, s48
	v_max3_u32 v37, s3, v37, v38
	v_cmp_ne_u32_e32 vcc, v35, v37
	v_cndmask_b32_e64 v36, v36, v37, s[16:17]
	s_nop 0
	v_cndmask_b32_e32 v35, 0, v35, vcc
	s_nop 1
	v_max_u32_dpp v37, v35, v35 quad_perm:[1,0,3,2] row_mask:0xf bank_mask:0xf bound_ctrl:1
	s_nop 1
	v_max_u32_dpp v37, v37, v37 quad_perm:[2,3,0,1] row_mask:0xf bank_mask:0xf bound_ctrl:1
	s_nop 1
	v_max_u32_dpp v37, v37, v37 row_half_mirror row_mask:0xf bank_mask:0xf bound_ctrl:1
	s_nop 1
	v_max_u32_dpp v37, v37, v37 row_mirror row_mask:0xf bank_mask:0xf bound_ctrl:1
	s_nop 0
	v_readlane_b32 s48, v37, 32
	v_readlane_b32 s49, v37, 48
	v_readlane_b32 s40, v37, 16
	s_max_u32 s48, s48, s49
	v_readlane_b32 s3, v37, 0
	v_mov_b32_e32 v37, s40
	v_mov_b32_e32 v38, s48
	v_max3_u32 v37, s3, v37, v38
	v_cmp_ne_u32_e32 vcc, v35, v37
	v_cndmask_b32_e64 v36, v36, v37, s[18:19]
	s_nop 0
	v_cndmask_b32_e32 v35, 0, v35, vcc
	s_nop 1
	v_max_u32_dpp v37, v35, v35 quad_perm:[1,0,3,2] row_mask:0xf bank_mask:0xf bound_ctrl:1
	s_nop 1
	v_max_u32_dpp v37, v37, v37 quad_perm:[2,3,0,1] row_mask:0xf bank_mask:0xf bound_ctrl:1
	s_nop 1
	v_max_u32_dpp v37, v37, v37 row_half_mirror row_mask:0xf bank_mask:0xf bound_ctrl:1
	s_nop 1
	v_max_u32_dpp v37, v37, v37 row_mirror row_mask:0xf bank_mask:0xf bound_ctrl:1
	s_nop 0
	v_readlane_b32 s48, v37, 32
	v_readlane_b32 s49, v37, 48
	v_readlane_b32 s40, v37, 16
	s_max_u32 s48, s48, s49
	v_readlane_b32 s3, v37, 0
	v_mov_b32_e32 v37, s40
	v_mov_b32_e32 v38, s48
	v_max3_u32 v37, s3, v37, v38
	v_cmp_ne_u32_e32 vcc, v35, v37
	v_cndmask_b32_e64 v36, v36, v37, s[20:21]
	s_nop 0
	v_cndmask_b32_e32 v35, 0, v35, vcc
	s_nop 1
	v_max_u32_dpp v37, v35, v35 quad_perm:[1,0,3,2] row_mask:0xf bank_mask:0xf bound_ctrl:1
	s_nop 1
	v_max_u32_dpp v37, v37, v37 quad_perm:[2,3,0,1] row_mask:0xf bank_mask:0xf bound_ctrl:1
	s_nop 1
	v_max_u32_dpp v37, v37, v37 row_half_mirror row_mask:0xf bank_mask:0xf bound_ctrl:1
	s_nop 1
	v_max_u32_dpp v37, v37, v37 row_mirror row_mask:0xf bank_mask:0xf bound_ctrl:1
	s_nop 0
	v_readlane_b32 s48, v37, 32
	v_readlane_b32 s49, v37, 48
	v_readlane_b32 s40, v37, 16
	s_max_u32 s48, s48, s49
	v_readlane_b32 s3, v37, 0
	v_mov_b32_e32 v37, s40
	v_mov_b32_e32 v38, s48
	v_max3_u32 v37, s3, v37, v38
	v_cmp_ne_u32_e32 vcc, v35, v37
	v_cndmask_b32_e64 v36, v36, v37, s[22:23]
	s_nop 0
	v_cndmask_b32_e32 v35, 0, v35, vcc
	s_nop 1
	v_max_u32_dpp v37, v35, v35 quad_perm:[1,0,3,2] row_mask:0xf bank_mask:0xf bound_ctrl:1
	s_nop 1
	v_max_u32_dpp v37, v37, v37 quad_perm:[2,3,0,1] row_mask:0xf bank_mask:0xf bound_ctrl:1
	s_nop 1
	v_max_u32_dpp v37, v37, v37 row_half_mirror row_mask:0xf bank_mask:0xf bound_ctrl:1
	s_nop 1
	v_max_u32_dpp v37, v37, v37 row_mirror row_mask:0xf bank_mask:0xf bound_ctrl:1
	s_nop 0
	v_readlane_b32 s48, v37, 32
	v_readlane_b32 s49, v37, 48
	v_readlane_b32 s40, v37, 16
	s_max_u32 s48, s48, s49
	v_readlane_b32 s3, v37, 0
	v_mov_b32_e32 v37, s40
	v_mov_b32_e32 v38, s48
	v_max3_u32 v37, s3, v37, v38
	v_cmp_ne_u32_e32 vcc, v35, v37
	v_cndmask_b32_e64 v36, v36, v37, s[24:25]
	s_nop 0
	v_cndmask_b32_e32 v35, 0, v35, vcc
	s_nop 1
	v_max_u32_dpp v37, v35, v35 quad_perm:[1,0,3,2] row_mask:0xf bank_mask:0xf bound_ctrl:1
	s_nop 1
	v_max_u32_dpp v37, v37, v37 quad_perm:[2,3,0,1] row_mask:0xf bank_mask:0xf bound_ctrl:1
	s_nop 1
	v_max_u32_dpp v37, v37, v37 row_half_mirror row_mask:0xf bank_mask:0xf bound_ctrl:1
	s_nop 1
	v_max_u32_dpp v37, v37, v37 row_mirror row_mask:0xf bank_mask:0xf bound_ctrl:1
	s_nop 0
	v_readlane_b32 s48, v37, 32
	v_readlane_b32 s49, v37, 48
	v_readlane_b32 s40, v37, 16
	s_max_u32 s48, s48, s49
	v_readlane_b32 s3, v37, 0
	v_mov_b32_e32 v37, s40
	v_mov_b32_e32 v38, s48
	v_max3_u32 v37, s3, v37, v38
	v_cmp_ne_u32_e32 vcc, v35, v37
	v_cndmask_b32_e64 v36, v36, v37, s[26:27]
	s_nop 0
	v_cndmask_b32_e32 v35, 0, v35, vcc
	s_nop 1
	v_max_u32_dpp v37, v35, v35 quad_perm:[1,0,3,2] row_mask:0xf bank_mask:0xf bound_ctrl:1
	s_nop 1
	v_max_u32_dpp v37, v37, v37 quad_perm:[2,3,0,1] row_mask:0xf bank_mask:0xf bound_ctrl:1
	s_nop 1
	v_max_u32_dpp v37, v37, v37 row_half_mirror row_mask:0xf bank_mask:0xf bound_ctrl:1
	s_nop 1
	v_max_u32_dpp v37, v37, v37 row_mirror row_mask:0xf bank_mask:0xf bound_ctrl:1
	s_nop 0
	v_readlane_b32 s48, v37, 32
	v_readlane_b32 s49, v37, 48
	v_readlane_b32 s40, v37, 16
	s_max_u32 s48, s48, s49
	v_readlane_b32 s3, v37, 0
	v_mov_b32_e32 v37, s40
	v_mov_b32_e32 v38, s48
	v_max3_u32 v37, s3, v37, v38
	v_cmp_ne_u32_e32 vcc, v35, v37
	v_cndmask_b32_e64 v36, v36, v37, s[28:29]
	s_nop 0
	v_cndmask_b32_e32 v35, 0, v35, vcc
	s_nop 1
	v_max_u32_dpp v37, v35, v35 quad_perm:[1,0,3,2] row_mask:0xf bank_mask:0xf bound_ctrl:1
	s_nop 1
	v_max_u32_dpp v37, v37, v37 quad_perm:[2,3,0,1] row_mask:0xf bank_mask:0xf bound_ctrl:1
	s_nop 1
	v_max_u32_dpp v37, v37, v37 row_half_mirror row_mask:0xf bank_mask:0xf bound_ctrl:1
	s_nop 1
	v_max_u32_dpp v37, v37, v37 row_mirror row_mask:0xf bank_mask:0xf bound_ctrl:1
	s_nop 0
	v_readlane_b32 s48, v37, 32
	v_readlane_b32 s49, v37, 48
	v_readlane_b32 s40, v37, 16
	s_max_u32 s48, s48, s49
	v_readlane_b32 s3, v37, 0
	v_mov_b32_e32 v37, s40
	v_mov_b32_e32 v38, s48
	v_max3_u32 v37, s3, v37, v38
	v_cmp_ne_u32_e32 vcc, v35, v37
	v_cndmask_b32_e64 v44, v36, v37, s[30:31]
	s_ashr_i32 s3, s2, 31
	v_cndmask_b32_e32 v35, 0, v35, vcc
	s_lshl_b64 s[48:49], s[2:3], 12
	v_lshl_add_u64 v[48:49], v[112:113], 0, s[48:49]
	v_max_u32_dpp v36, v35, v35 quad_perm:[1,0,3,2] row_mask:0xf bank_mask:0xf bound_ctrl:1
	s_nop 1
	v_max_u32_dpp v45, v36, v36 quad_perm:[2,3,0,1] row_mask:0xf bank_mask:0xf bound_ctrl:1
	global_load_dwordx4 v[36:39], v[48:49], off offset:16
	global_load_dwordx4 v[40:43], v[48:49], off
	v_max_u32_dpp v45, v45, v45 row_half_mirror row_mask:0xf bank_mask:0xf bound_ctrl:1
	s_waitcnt vmcnt(1)
	v_lshlrev_b32_e32 v132, 16, v36
	v_max_u32_dpp v45, v45, v45 row_mirror row_mask:0xf bank_mask:0xf bound_ctrl:1
	s_waitcnt vmcnt(0)
	v_lshlrev_b32_e32 v124, 16, v40
	v_readlane_b32 s49, v45, 32
	v_readlane_b32 s50, v45, 48
	v_readlane_b32 s48, v45, 16
	s_max_u32 s49, s49, s50
	v_readlane_b32 s40, v45, 0
	v_mov_b32_e32 v45, s48
	v_mov_b32_e32 v46, s49
	v_max3_u32 v45, s40, v45, v46
	v_cmp_ne_u32_e32 vcc, v35, v45
	v_cndmask_b32_e64 v52, v44, v45, s[34:35]
	global_load_dwordx4 v[44:47], v[48:49], off offset:2064
	s_nop 0
	global_load_dwordx4 v[48:51], v[48:49], off offset:2048
	v_cndmask_b32_e32 v35, 0, v35, vcc
	v_and_b32_e32 v125, 0xffff0000, v40
	v_lshlrev_b32_e32 v126, 16, v41
	v_max_u32_dpp v53, v35, v35 quad_perm:[1,0,3,2] row_mask:0xf bank_mask:0xf bound_ctrl:1
	v_and_b32_e32 v127, 0xffff0000, v41
	v_lshlrev_b32_e32 v128, 16, v42
	v_max_u32_dpp v53, v53, v53 quad_perm:[2,3,0,1] row_mask:0xf bank_mask:0xf bound_ctrl:1
	v_and_b32_e32 v129, 0xffff0000, v42
	v_lshlrev_b32_e32 v130, 16, v43
	v_max_u32_dpp v53, v53, v53 row_half_mirror row_mask:0xf bank_mask:0xf bound_ctrl:1
	v_and_b32_e32 v131, 0xffff0000, v43
	v_and_b32_e32 v133, 0xffff0000, v36
	v_max_u32_dpp v53, v53, v53 row_mirror row_mask:0xf bank_mask:0xf bound_ctrl:1
	v_lshlrev_b32_e32 v134, 16, v37
	v_readlane_b32 s49, v53, 32
	v_readlane_b32 s50, v53, 48
	v_readlane_b32 s48, v53, 16
	s_max_u32 s49, s49, s50
	v_readlane_b32 s40, v53, 0
	v_mov_b32_e32 v53, s48
	v_mov_b32_e32 v54, s49
	v_max3_u32 v53, s40, v53, v54
	v_cmp_ne_u32_e32 vcc, v35, v53
	v_cndmask_b32_e64 v52, v52, v53, s[36:37]
	v_bitop3_b32 v54, v33, s54, v33 bitop3:0xc
	v_cndmask_b32_e32 v35, 0, v35, vcc
	v_and_b32_e32 v135, 0xffff0000, v37
	v_lshlrev_b32_e32 v136, 16, v38
	v_max_u32_dpp v35, v35, v35 quad_perm:[1,0,3,2] row_mask:0xf bank_mask:0xf bound_ctrl:1
	v_and_b32_e32 v137, 0xffff0000, v38
	v_lshlrev_b32_e32 v138, 16, v39
	v_max_u32_dpp v35, v35, v35 quad_perm:[2,3,0,1] row_mask:0xf bank_mask:0xf bound_ctrl:1
	v_and_b32_e32 v139, 0xffff0000, v39
	v_mov_b32_e32 v38, v34
	v_max_u32_dpp v35, v35, v35 row_half_mirror row_mask:0xf bank_mask:0xf bound_ctrl:1
	v_mov_b32_e32 v39, v34
	v_mov_b32_e32 v36, v34
	v_max_u32_dpp v35, v35, v35 row_mirror row_mask:0xf bank_mask:0xf bound_ctrl:1
	v_mov_b32_e32 v37, v34
	v_readlane_b32 s49, v35, 32
	v_readlane_b32 s50, v35, 48
	v_readlane_b32 s48, v35, 16
	s_max_u32 s49, s49, s50
	v_readlane_b32 s40, v35, 0
	v_mov_b32_e32 v35, s48
	v_mov_b32_e32 v53, s49
	v_max3_u32 v35, s40, v35, v53
	v_cndmask_b32_e64 v35, v52, v35, s[38:39]
	v_and_or_b32 v33, v35, 63, v162
	v_lshlrev_b32_e32 v33, 2, v33
	v_xor_b32_e32 v33, 0xfc, v33
	v_cmp_lt_i32_e32 vcc, -1, v35
	ds_bpermute_b32 v52, v33, v161
	ds_bpermute_b32 v33, v33, v157
	v_cndmask_b32_e64 v53, v159, -1, vcc
	v_bitop3_b32 v35, v53, v35, s33 bitop3:0x78
	ds_bpermute_b32 v53, v166, v35
	s_waitcnt lgkmcnt(2)
	v_and_or_b32 v52, v52, 63, v162
	v_lshlrev_b32_e32 v52, 2, v52
	ds_bpermute_b32 v55, v52, v32
	s_waitcnt lgkmcnt(2)
	v_and_or_b32 v56, v33, 63, v162
	s_waitcnt lgkmcnt(1)
	v_sub_f32_e32 v32, v35, v53
	v_mul_f32_e32 v32, 0x3fb8aa3b, v32
	v_exp_f32_e32 v35, v32
	v_lshlrev_b64 v[32:33], 2, v[122:123]
	v_lshl_add_u64 v[52:53], s[42:43], 0, v[32:33]
	v_lshl_add_u64 v[32:33], s[44:45], 0, v[32:33]
	global_load_dword v175, v[52:53], off
	global_load_dword v176, v[32:33], off
	v_lshlrev_b32_e32 v32, 2, v56
	ds_bpermute_b32 v32, v32, v54
	v_cndmask_b32_e64 v123, 0, v35, s[4:5]
	v_mov_b32_e32 v35, v34
	v_mov_b32_e32 v42, v34
	v_add_f32_dpp v33, v123, v123 quad_perm:[1,0,3,2] row_mask:0xf bank_mask:0xf bound_ctrl:1
	s_waitcnt lgkmcnt(0)
	v_lshl_add_u32 v32, v55, 7, v32
	v_and_b32_e32 v32, 0x3fff, v32
	ds_bpermute_b32 v174, v165, v32
	v_add_f32_dpp v33, v33, v33 quad_perm:[2,3,0,1] row_mask:0xf bank_mask:0xf bound_ctrl:1
	s_waitcnt vmcnt(3)
	v_lshlrev_b32_e32 v148, 16, v44
	s_waitcnt vmcnt(2)
	v_lshlrev_b32_e32 v140, 16, v48
	v_add_f32_dpp v33, v33, v33 row_half_mirror row_mask:0xf bank_mask:0xf bound_ctrl:1
	v_and_b32_e32 v141, 0xffff0000, v48
	v_lshlrev_b32_e32 v142, 16, v49
	v_add_f32_dpp v33, v33, v33 row_mirror row_mask:0xf bank_mask:0xf bound_ctrl:1
	v_and_b32_e32 v143, 0xffff0000, v49
	v_readlane_b32 s66, v33, 0
	v_readlane_b32 s68, v33, 16
	v_readlane_b32 s67, v33, 32
	v_readlane_b32 s69, v33, 48
	v_lshlrev_b32_e32 v144, 16, v50
	v_and_b32_e32 v145, 0xffff0000, v50
	v_lshlrev_b32_e32 v146, 16, v51
	v_and_b32_e32 v147, 0xffff0000, v51
	v_and_b32_e32 v149, 0xffff0000, v44
	v_lshlrev_b32_e32 v150, 16, v45
	v_and_b32_e32 v151, 0xffff0000, v45
	v_lshlrev_b32_e32 v152, 16, v46
	v_and_b32_e32 v153, 0xffff0000, v46
	v_lshlrev_b32_e32 v154, 16, v47
	v_and_b32_e32 v155, 0xffff0000, v47
	v_mov_b32_e32 v32, v34
	v_mov_b32_e32 v33, v34
	v_mov_b32_e32 v43, v34
	v_mov_b32_e32 v40, v34
	v_mov_b32_e32 v41, v34
	v_mov_b32_e32 v46, v34
	v_mov_b32_e32 v47, v34
	v_mov_b32_e32 v44, v34
	v_mov_b32_e32 v45, v34
	v_mov_b32_e32 v50, v34
	v_mov_b32_e32 v51, v34
	v_mov_b32_e32 v48, v34
	v_mov_b32_e32 v49, v34
	v_mov_b32_e32 v54, v34
	v_mov_b32_e32 v55, v34
	v_mov_b32_e32 v52, v34
	v_mov_b32_e32 v53, v34
	v_mov_b32_e32 v56, v34
	s_waitcnt vmcnt(0) lgkmcnt(0)
	v_subrev_u32_e32 v178, s96, v114
	s_nop 1
	v_readlane_b32 s100, v122, 6
	s_nop 0
	s_lshl_b32 s100, s100, 11
	s_add_u32 s100, s96, s100
	s_addc_u32 s101, s97, 0
	global_load_dwordx4 v[12:15], v178, s[100:101]
	global_load_dwordx4 v[20:23], v178, s[100:101] offset:1024
	s_waitcnt vmcnt(12)
	v_cvt_pk_f32_fp8_e32 v[64:65], v0
	v_pk_fma_f32 v[72:73], v[64:65], v[124:125], 0 op_sel_hi:[1,1,0]
	v_cvt_pk_f32_fp8_sdwa v[66:67], v0 src0_sel:WORD_1
	v_pk_fma_f32 v[72:73], v[66:67], v[126:127], v[72:73]
	v_cvt_pk_f32_fp8_e32 v[68:69], v1
	v_pk_fma_f32 v[72:73], v[68:69], v[128:129], v[72:73]
	v_cvt_pk_f32_fp8_sdwa v[70:71], v1 src0_sel:WORD_1
	v_pk_fma_f32 v[72:73], v[70:71], v[130:131], v[72:73]
	v_cvt_pk_f32_fp8_e32 v[64:65], v2
	v_pk_fma_f32 v[72:73], v[64:65], v[132:133], v[72:73]
	v_cvt_pk_f32_fp8_sdwa v[66:67], v2 src0_sel:WORD_1
	v_pk_fma_f32 v[72:73], v[66:67], v[134:135], v[72:73]
	v_cvt_pk_f32_fp8_e32 v[68:69], v3
	v_pk_fma_f32 v[72:73], v[68:69], v[136:137], v[72:73]
	v_cvt_pk_f32_fp8_sdwa v[70:71], v3 src0_sel:WORD_1
	v_pk_fma_f32 v[72:73], v[70:71], v[138:139], v[72:73]
	v_cvt_pk_f32_fp8_e32 v[64:65], v4
	v_pk_fma_f32 v[72:73], v[64:65], v[140:141], v[72:73]
	v_cvt_pk_f32_fp8_sdwa v[66:67], v4 src0_sel:WORD_1
	v_pk_fma_f32 v[72:73], v[66:67], v[142:143], v[72:73]
	v_cvt_pk_f32_fp8_e32 v[68:69], v5
	v_pk_fma_f32 v[72:73], v[68:69], v[144:145], v[72:73]
	v_cvt_pk_f32_fp8_sdwa v[70:71], v5 src0_sel:WORD_1
	v_pk_fma_f32 v[72:73], v[70:71], v[146:147], v[72:73]
	v_cvt_pk_f32_fp8_e32 v[64:65], v6
	v_pk_fma_f32 v[72:73], v[64:65], v[148:149], v[72:73]
	v_cvt_pk_f32_fp8_sdwa v[66:67], v6 src0_sel:WORD_1
	v_pk_fma_f32 v[72:73], v[66:67], v[150:151], v[72:73]
	v_cvt_pk_f32_fp8_e32 v[68:69], v7
	v_pk_fma_f32 v[72:73], v[68:69], v[152:153], v[72:73]
	v_cvt_pk_f32_fp8_sdwa v[70:71], v7 src0_sel:WORD_1
	v_pk_fma_f32 v[72:73], v[70:71], v[154:155], v[72:73]
	s_nop 1
	v_readlane_b32 s100, v122, 7
	v_add_f32_e32 v72, v72, v73
	s_lshl_b32 s100, s100, 11
	s_add_u32 s100, s96, s100
	s_addc_u32 s101, s97, 0
	global_load_dwordx4 v[24:27], v178, s[100:101]
	global_load_dwordx4 v[28:31], v178, s[100:101] offset:1024
	s_waitcnt vmcnt(12)
	v_cvt_pk_f32_fp8_e32 v[64:65], v8
	v_pk_fma_f32 v[74:75], v[64:65], v[124:125], 0 op_sel_hi:[1,1,0]
	v_cvt_pk_f32_fp8_sdwa v[66:67], v8 src0_sel:WORD_1
	v_pk_fma_f32 v[74:75], v[66:67], v[126:127], v[74:75]
	v_cvt_pk_f32_fp8_e32 v[68:69], v9
	v_pk_fma_f32 v[74:75], v[68:69], v[128:129], v[74:75]
	v_cvt_pk_f32_fp8_sdwa v[70:71], v9 src0_sel:WORD_1
	v_pk_fma_f32 v[74:75], v[70:71], v[130:131], v[74:75]
	v_cvt_pk_f32_fp8_e32 v[64:65], v10
	v_pk_fma_f32 v[74:75], v[64:65], v[132:133], v[74:75]
	v_cvt_pk_f32_fp8_sdwa v[66:67], v10 src0_sel:WORD_1
	v_pk_fma_f32 v[74:75], v[66:67], v[134:135], v[74:75]
	v_add_f32_dpp v72, v72, v72 quad_perm:[1,0,3,2] row_mask:0xf bank_mask:0xf bound_ctrl:1
	v_cvt_pk_f32_fp8_e32 v[68:69], v11
	v_pk_fma_f32 v[74:75], v[68:69], v[136:137], v[74:75]
	v_cvt_pk_f32_fp8_sdwa v[70:71], v11 src0_sel:WORD_1
	v_add_f32_dpp v72, v72, v72 quad_perm:[2,3,0,1] row_mask:0xf bank_mask:0xf bound_ctrl:1
	v_pk_fma_f32 v[74:75], v[70:71], v[138:139], v[74:75]
	v_cvt_pk_f32_fp8_e32 v[64:65], v16
	v_pk_fma_f32 v[74:75], v[64:65], v[140:141], v[74:75]
	v_add_f32_dpp v72, v72, v72 row_half_mirror row_mask:0xf bank_mask:0xf bound_ctrl:1
	v_cvt_pk_f32_fp8_sdwa v[66:67], v16 src0_sel:WORD_1
	v_pk_fma_f32 v[74:75], v[66:67], v[142:143], v[74:75]
	v_cvt_pk_f32_fp8_e32 v[68:69], v17
	v_add_f32_dpp v72, v72, v72 row_mirror row_mask:0xf bank_mask:0xf bound_ctrl:1
	v_pk_fma_f32 v[74:75], v[68:69], v[144:145], v[74:75]
	v_cvt_pk_f32_fp8_sdwa v[70:71], v17 src0_sel:WORD_1
	v_pk_fma_f32 v[74:75], v[70:71], v[146:147], v[74:75]
	v_add_f32_dpp v72, v72, v72 row_bcast:15 row_mask:0xa bank_mask:0xf
	v_cvt_pk_f32_fp8_e32 v[64:65], v18
	v_pk_fma_f32 v[74:75], v[64:65], v[148:149], v[74:75]
	v_cvt_pk_f32_fp8_sdwa v[66:67], v18 src0_sel:WORD_1
	v_add_f32_dpp v72, v72, v72 row_bcast:31 row_mask:0xc bank_mask:0xf
	v_pk_fma_f32 v[74:75], v[66:67], v[150:151], v[74:75]
	v_cvt_pk_f32_fp8_e32 v[68:69], v19
	v_readlane_b32 s50, v72, 63
	v_pk_fma_f32 v[74:75], v[68:69], v[152:153], v[74:75]
	v_cvt_pk_f32_fp8_sdwa v[70:71], v19 src0_sel:WORD_1
	v_pk_fma_f32 v[74:75], v[70:71], v[154:155], v[74:75]
	v_writelane_b32 v177, s50, 0
	s_nop 1
	v_readlane_b32 s100, v122, 8
	v_add_f32_e32 v74, v74, v75
	s_lshl_b32 s100, s100, 11
	s_add_u32 s100, s96, s100
	s_addc_u32 s101, s97, 0
	global_load_dwordx4 v[0:3], v178, s[100:101]
	global_load_dwordx4 v[4:7], v178, s[100:101] offset:1024
	s_waitcnt vmcnt(12)
	v_cvt_pk_f32_fp8_e32 v[64:65], v80
	v_pk_fma_f32 v[72:73], v[64:65], v[124:125], 0 op_sel_hi:[1,1,0]
	v_cvt_pk_f32_fp8_sdwa v[66:67], v80 src0_sel:WORD_1
	v_pk_fma_f32 v[72:73], v[66:67], v[126:127], v[72:73]
	v_cvt_pk_f32_fp8_e32 v[68:69], v81
	v_pk_fma_f32 v[72:73], v[68:69], v[128:129], v[72:73]
	v_cvt_pk_f32_fp8_sdwa v[70:71], v81 src0_sel:WORD_1
	v_pk_fma_f32 v[72:73], v[70:71], v[130:131], v[72:73]
	v_cvt_pk_f32_fp8_e32 v[64:65], v82
	v_pk_fma_f32 v[72:73], v[64:65], v[132:133], v[72:73]
	v_cvt_pk_f32_fp8_sdwa v[66:67], v82 src0_sel:WORD_1
	v_pk_fma_f32 v[72:73], v[66:67], v[134:135], v[72:73]
	v_add_f32_dpp v74, v74, v74 quad_perm:[1,0,3,2] row_mask:0xf bank_mask:0xf bound_ctrl:1
	v_cvt_pk_f32_fp8_e32 v[68:69], v83
	v_pk_fma_f32 v[72:73], v[68:69], v[136:137], v[72:73]
	v_cvt_pk_f32_fp8_sdwa v[70:71], v83 src0_sel:WORD_1
	v_add_f32_dpp v74, v74, v74 quad_perm:[2,3,0,1] row_mask:0xf bank_mask:0xf bound_ctrl:1
	v_pk_fma_f32 v[72:73], v[70:71], v[138:139], v[72:73]
	v_cvt_pk_f32_fp8_e32 v[64:65], v84
	v_pk_fma_f32 v[72:73], v[64:65], v[140:141], v[72:73]
	v_add_f32_dpp v74, v74, v74 row_half_mirror row_mask:0xf bank_mask:0xf bound_ctrl:1
	v_cvt_pk_f32_fp8_sdwa v[66:67], v84 src0_sel:WORD_1
	v_pk_fma_f32 v[72:73], v[66:67], v[142:143], v[72:73]
	v_cvt_pk_f32_fp8_e32 v[68:69], v85
	v_add_f32_dpp v74, v74, v74 row_mirror row_mask:0xf bank_mask:0xf bound_ctrl:1
	v_pk_fma_f32 v[72:73], v[68:69], v[144:145], v[72:73]
	v_cvt_pk_f32_fp8_sdwa v[70:71], v85 src0_sel:WORD_1
	v_pk_fma_f32 v[72:73], v[70:71], v[146:147], v[72:73]
	v_add_f32_dpp v74, v74, v74 row_bcast:15 row_mask:0xa bank_mask:0xf
	v_cvt_pk_f32_fp8_e32 v[64:65], v86
	v_pk_fma_f32 v[72:73], v[64:65], v[148:149], v[72:73]
	v_cvt_pk_f32_fp8_sdwa v[66:67], v86 src0_sel:WORD_1
	v_add_f32_dpp v74, v74, v74 row_bcast:31 row_mask:0xc bank_mask:0xf
	v_pk_fma_f32 v[72:73], v[66:67], v[150:151], v[72:73]
	v_cvt_pk_f32_fp8_e32 v[68:69], v87
	v_readlane_b32 s50, v74, 63
	v_pk_fma_f32 v[72:73], v[68:69], v[152:153], v[72:73]
	v_cvt_pk_f32_fp8_sdwa v[70:71], v87 src0_sel:WORD_1
	v_pk_fma_f32 v[72:73], v[70:71], v[154:155], v[72:73]
	v_writelane_b32 v177, s50, 1
	s_nop 1
	v_readlane_b32 s100, v122, 9
	v_add_f32_e32 v72, v72, v73
	s_lshl_b32 s100, s100, 11
	s_add_u32 s100, s96, s100
	s_addc_u32 s101, s97, 0
	global_load_dwordx4 v[8:11], v178, s[100:101]
	global_load_dwordx4 v[16:19], v178, s[100:101] offset:1024
	s_waitcnt vmcnt(12)
	v_cvt_pk_f32_fp8_e32 v[64:65], v88
	v_pk_fma_f32 v[74:75], v[64:65], v[124:125], 0 op_sel_hi:[1,1,0]
	v_cvt_pk_f32_fp8_sdwa v[66:67], v88 src0_sel:WORD_1
	v_pk_fma_f32 v[74:75], v[66:67], v[126:127], v[74:75]
	v_cvt_pk_f32_fp8_e32 v[68:69], v89
	v_pk_fma_f32 v[74:75], v[68:69], v[128:129], v[74:75]
	v_cvt_pk_f32_fp8_sdwa v[70:71], v89 src0_sel:WORD_1
	v_pk_fma_f32 v[74:75], v[70:71], v[130:131], v[74:75]
	v_cvt_pk_f32_fp8_e32 v[64:65], v90
	v_pk_fma_f32 v[74:75], v[64:65], v[132:133], v[74:75]
	v_cvt_pk_f32_fp8_sdwa v[66:67], v90 src0_sel:WORD_1
	v_pk_fma_f32 v[74:75], v[66:67], v[134:135], v[74:75]
	v_add_f32_dpp v72, v72, v72 quad_perm:[1,0,3,2] row_mask:0xf bank_mask:0xf bound_ctrl:1
	v_cvt_pk_f32_fp8_e32 v[68:69], v91
	v_pk_fma_f32 v[74:75], v[68:69], v[136:137], v[74:75]
	v_cvt_pk_f32_fp8_sdwa v[70:71], v91 src0_sel:WORD_1
	v_add_f32_dpp v72, v72, v72 quad_perm:[2,3,0,1] row_mask:0xf bank_mask:0xf bound_ctrl:1
	v_pk_fma_f32 v[74:75], v[70:71], v[138:139], v[74:75]
	v_cvt_pk_f32_fp8_e32 v[64:65], v92
	v_pk_fma_f32 v[74:75], v[64:65], v[140:141], v[74:75]
	v_add_f32_dpp v72, v72, v72 row_half_mirror row_mask:0xf bank_mask:0xf bound_ctrl:1
	v_cvt_pk_f32_fp8_sdwa v[66:67], v92 src0_sel:WORD_1
	v_pk_fma_f32 v[74:75], v[66:67], v[142:143], v[74:75]
	v_cvt_pk_f32_fp8_e32 v[68:69], v93
	v_add_f32_dpp v72, v72, v72 row_mirror row_mask:0xf bank_mask:0xf bound_ctrl:1
	v_pk_fma_f32 v[74:75], v[68:69], v[144:145], v[74:75]
	v_cvt_pk_f32_fp8_sdwa v[70:71], v93 src0_sel:WORD_1
	v_pk_fma_f32 v[74:75], v[70:71], v[146:147], v[74:75]
	v_add_f32_dpp v72, v72, v72 row_bcast:15 row_mask:0xa bank_mask:0xf
	v_cvt_pk_f32_fp8_e32 v[64:65], v94
	v_pk_fma_f32 v[74:75], v[64:65], v[148:149], v[74:75]
	v_cvt_pk_f32_fp8_sdwa v[66:67], v94 src0_sel:WORD_1
	v_add_f32_dpp v72, v72, v72 row_bcast:31 row_mask:0xc bank_mask:0xf
	v_pk_fma_f32 v[74:75], v[66:67], v[150:151], v[74:75]
	v_cvt_pk_f32_fp8_e32 v[68:69], v95
	v_readlane_b32 s50, v72, 63
	v_pk_fma_f32 v[74:75], v[68:69], v[152:153], v[74:75]
	v_cvt_pk_f32_fp8_sdwa v[70:71], v95 src0_sel:WORD_1
	v_pk_fma_f32 v[74:75], v[70:71], v[154:155], v[74:75]
	v_writelane_b32 v177, s50, 2
	s_nop 1
	v_readlane_b32 s100, v122, 10
	v_add_f32_e32 v74, v74, v75
	s_lshl_b32 s100, s100, 11
	s_add_u32 s100, s96, s100
	s_addc_u32 s101, s97, 0
	global_load_dwordx4 v[80:83], v178, s[100:101]
	global_load_dwordx4 v[84:87], v178, s[100:101] offset:1024
	s_waitcnt vmcnt(12)
	v_cvt_pk_f32_fp8_e32 v[64:65], v96
	v_pk_fma_f32 v[72:73], v[64:65], v[124:125], 0 op_sel_hi:[1,1,0]
	v_cvt_pk_f32_fp8_sdwa v[66:67], v96 src0_sel:WORD_1
	v_pk_fma_f32 v[72:73], v[66:67], v[126:127], v[72:73]
	v_cvt_pk_f32_fp8_e32 v[68:69], v97
	v_pk_fma_f32 v[72:73], v[68:69], v[128:129], v[72:73]
	v_cvt_pk_f32_fp8_sdwa v[70:71], v97 src0_sel:WORD_1
	v_pk_fma_f32 v[72:73], v[70:71], v[130:131], v[72:73]
	v_cvt_pk_f32_fp8_e32 v[64:65], v98
	v_pk_fma_f32 v[72:73], v[64:65], v[132:133], v[72:73]
	v_cvt_pk_f32_fp8_sdwa v[66:67], v98 src0_sel:WORD_1
	v_pk_fma_f32 v[72:73], v[66:67], v[134:135], v[72:73]
	v_add_f32_dpp v74, v74, v74 quad_perm:[1,0,3,2] row_mask:0xf bank_mask:0xf bound_ctrl:1
	v_cvt_pk_f32_fp8_e32 v[68:69], v99
	v_pk_fma_f32 v[72:73], v[68:69], v[136:137], v[72:73]
	v_cvt_pk_f32_fp8_sdwa v[70:71], v99 src0_sel:WORD_1
	v_add_f32_dpp v74, v74, v74 quad_perm:[2,3,0,1] row_mask:0xf bank_mask:0xf bound_ctrl:1
	v_pk_fma_f32 v[72:73], v[70:71], v[138:139], v[72:73]
	v_cvt_pk_f32_fp8_e32 v[64:65], v100
	v_pk_fma_f32 v[72:73], v[64:65], v[140:141], v[72:73]
	v_add_f32_dpp v74, v74, v74 row_half_mirror row_mask:0xf bank_mask:0xf bound_ctrl:1
	v_cvt_pk_f32_fp8_sdwa v[66:67], v100 src0_sel:WORD_1
	v_pk_fma_f32 v[72:73], v[66:67], v[142:143], v[72:73]
	v_cvt_pk_f32_fp8_e32 v[68:69], v101
	v_add_f32_dpp v74, v74, v74 row_mirror row_mask:0xf bank_mask:0xf bound_ctrl:1
	v_pk_fma_f32 v[72:73], v[68:69], v[144:145], v[72:73]
	v_cvt_pk_f32_fp8_sdwa v[70:71], v101 src0_sel:WORD_1
	v_pk_fma_f32 v[72:73], v[70:71], v[146:147], v[72:73]
	v_add_f32_dpp v74, v74, v74 row_bcast:15 row_mask:0xa bank_mask:0xf
	v_cvt_pk_f32_fp8_e32 v[64:65], v102
	v_pk_fma_f32 v[72:73], v[64:65], v[148:149], v[72:73]
	v_cvt_pk_f32_fp8_sdwa v[66:67], v102 src0_sel:WORD_1
	v_add_f32_dpp v74, v74, v74 row_bcast:31 row_mask:0xc bank_mask:0xf
	v_pk_fma_f32 v[72:73], v[66:67], v[150:151], v[72:73]
	v_cvt_pk_f32_fp8_e32 v[68:69], v103
	v_readlane_b32 s50, v74, 63
	v_pk_fma_f32 v[72:73], v[68:69], v[152:153], v[72:73]
	v_cvt_pk_f32_fp8_sdwa v[70:71], v103 src0_sel:WORD_1
	v_pk_fma_f32 v[72:73], v[70:71], v[154:155], v[72:73]
	v_writelane_b32 v177, s50, 3
	s_nop 1
	v_readlane_b32 s100, v122, 11
	v_add_f32_e32 v72, v72, v73
	s_lshl_b32 s100, s100, 11
	s_add_u32 s100, s96, s100
	s_addc_u32 s101, s97, 0
	global_load_dwordx4 v[88:91], v178, s[100:101]
	global_load_dwordx4 v[92:95], v178, s[100:101] offset:1024
	s_waitcnt vmcnt(12)
	v_cvt_pk_f32_fp8_e32 v[64:65], v104
	v_pk_fma_f32 v[74:75], v[64:65], v[124:125], 0 op_sel_hi:[1,1,0]
	v_cvt_pk_f32_fp8_sdwa v[66:67], v104 src0_sel:WORD_1
	v_pk_fma_f32 v[74:75], v[66:67], v[126:127], v[74:75]
	v_cvt_pk_f32_fp8_e32 v[68:69], v105
	v_pk_fma_f32 v[74:75], v[68:69], v[128:129], v[74:75]
	v_cvt_pk_f32_fp8_sdwa v[70:71], v105 src0_sel:WORD_1
	v_pk_fma_f32 v[74:75], v[70:71], v[130:131], v[74:75]
	v_cvt_pk_f32_fp8_e32 v[64:65], v106
	v_pk_fma_f32 v[74:75], v[64:65], v[132:133], v[74:75]
	v_cvt_pk_f32_fp8_sdwa v[66:67], v106 src0_sel:WORD_1
	v_pk_fma_f32 v[74:75], v[66:67], v[134:135], v[74:75]
	v_add_f32_dpp v72, v72, v72 quad_perm:[1,0,3,2] row_mask:0xf bank_mask:0xf bound_ctrl:1
	v_cvt_pk_f32_fp8_e32 v[68:69], v107
	v_pk_fma_f32 v[74:75], v[68:69], v[136:137], v[74:75]
	v_cvt_pk_f32_fp8_sdwa v[70:71], v107 src0_sel:WORD_1
	v_add_f32_dpp v72, v72, v72 quad_perm:[2,3,0,1] row_mask:0xf bank_mask:0xf bound_ctrl:1
	v_pk_fma_f32 v[74:75], v[70:71], v[138:139], v[74:75]
	v_cvt_pk_f32_fp8_e32 v[64:65], v108
	v_pk_fma_f32 v[74:75], v[64:65], v[140:141], v[74:75]
	v_add_f32_dpp v72, v72, v72 row_half_mirror row_mask:0xf bank_mask:0xf bound_ctrl:1
	v_cvt_pk_f32_fp8_sdwa v[66:67], v108 src0_sel:WORD_1
	v_pk_fma_f32 v[74:75], v[66:67], v[142:143], v[74:75]
	v_cvt_pk_f32_fp8_e32 v[68:69], v109
	v_add_f32_dpp v72, v72, v72 row_mirror row_mask:0xf bank_mask:0xf bound_ctrl:1
	v_pk_fma_f32 v[74:75], v[68:69], v[144:145], v[74:75]
	v_cvt_pk_f32_fp8_sdwa v[70:71], v109 src0_sel:WORD_1
	v_pk_fma_f32 v[74:75], v[70:71], v[146:147], v[74:75]
	v_add_f32_dpp v72, v72, v72 row_bcast:15 row_mask:0xa bank_mask:0xf
	v_cvt_pk_f32_fp8_e32 v[64:65], v110
	v_pk_fma_f32 v[74:75], v[64:65], v[148:149], v[74:75]
	v_cvt_pk_f32_fp8_sdwa v[66:67], v110 src0_sel:WORD_1
	v_add_f32_dpp v72, v72, v72 row_bcast:31 row_mask:0xc bank_mask:0xf
	v_pk_fma_f32 v[74:75], v[66:67], v[150:151], v[74:75]
	v_cvt_pk_f32_fp8_e32 v[68:69], v111
	v_readlane_b32 s50, v72, 63
	v_pk_fma_f32 v[74:75], v[68:69], v[152:153], v[74:75]
	v_cvt_pk_f32_fp8_sdwa v[70:71], v111 src0_sel:WORD_1
	v_pk_fma_f32 v[74:75], v[70:71], v[154:155], v[74:75]
	v_writelane_b32 v177, s50, 4
	s_nop 1
	v_readlane_b32 s100, v122, 12
	v_add_f32_e32 v74, v74, v75
	s_lshl_b32 s100, s100, 11
	s_add_u32 s100, s96, s100
	s_addc_u32 s101, s97, 0
	global_load_dwordx4 v[96:99], v178, s[100:101]
	global_load_dwordx4 v[100:103], v178, s[100:101] offset:1024
	s_waitcnt vmcnt(12)
	v_cvt_pk_f32_fp8_e32 v[64:65], v12
	v_pk_fma_f32 v[72:73], v[64:65], v[124:125], 0 op_sel_hi:[1,1,0]
	v_cvt_pk_f32_fp8_sdwa v[66:67], v12 src0_sel:WORD_1
	v_pk_fma_f32 v[72:73], v[66:67], v[126:127], v[72:73]
	v_cvt_pk_f32_fp8_e32 v[68:69], v13
	v_pk_fma_f32 v[72:73], v[68:69], v[128:129], v[72:73]
	v_cvt_pk_f32_fp8_sdwa v[70:71], v13 src0_sel:WORD_1
	v_pk_fma_f32 v[72:73], v[70:71], v[130:131], v[72:73]
	v_cvt_pk_f32_fp8_e32 v[64:65], v14
	v_pk_fma_f32 v[72:73], v[64:65], v[132:133], v[72:73]
	v_cvt_pk_f32_fp8_sdwa v[66:67], v14 src0_sel:WORD_1
	v_pk_fma_f32 v[72:73], v[66:67], v[134:135], v[72:73]
	v_add_f32_dpp v74, v74, v74 quad_perm:[1,0,3,2] row_mask:0xf bank_mask:0xf bound_ctrl:1
	v_cvt_pk_f32_fp8_e32 v[68:69], v15
	v_pk_fma_f32 v[72:73], v[68:69], v[136:137], v[72:73]
	v_cvt_pk_f32_fp8_sdwa v[70:71], v15 src0_sel:WORD_1
	v_add_f32_dpp v74, v74, v74 quad_perm:[2,3,0,1] row_mask:0xf bank_mask:0xf bound_ctrl:1
	v_pk_fma_f32 v[72:73], v[70:71], v[138:139], v[72:73]
	v_cvt_pk_f32_fp8_e32 v[64:65], v20
	v_pk_fma_f32 v[72:73], v[64:65], v[140:141], v[72:73]
	v_add_f32_dpp v74, v74, v74 row_half_mirror row_mask:0xf bank_mask:0xf bound_ctrl:1
	v_cvt_pk_f32_fp8_sdwa v[66:67], v20 src0_sel:WORD_1
	v_pk_fma_f32 v[72:73], v[66:67], v[142:143], v[72:73]
	v_cvt_pk_f32_fp8_e32 v[68:69], v21
	v_add_f32_dpp v74, v74, v74 row_mirror row_mask:0xf bank_mask:0xf bound_ctrl:1
	v_pk_fma_f32 v[72:73], v[68:69], v[144:145], v[72:73]
	v_cvt_pk_f32_fp8_sdwa v[70:71], v21 src0_sel:WORD_1
	v_pk_fma_f32 v[72:73], v[70:71], v[146:147], v[72:73]
	v_add_f32_dpp v74, v74, v74 row_bcast:15 row_mask:0xa bank_mask:0xf
	v_cvt_pk_f32_fp8_e32 v[64:65], v22
	v_pk_fma_f32 v[72:73], v[64:65], v[148:149], v[72:73]
	v_cvt_pk_f32_fp8_sdwa v[66:67], v22 src0_sel:WORD_1
	v_add_f32_dpp v74, v74, v74 row_bcast:31 row_mask:0xc bank_mask:0xf
	v_pk_fma_f32 v[72:73], v[66:67], v[150:151], v[72:73]
	v_cvt_pk_f32_fp8_e32 v[68:69], v23
	v_readlane_b32 s50, v74, 63
	v_pk_fma_f32 v[72:73], v[68:69], v[152:153], v[72:73]
	v_cvt_pk_f32_fp8_sdwa v[70:71], v23 src0_sel:WORD_1
	v_pk_fma_f32 v[72:73], v[70:71], v[154:155], v[72:73]
	v_writelane_b32 v177, s50, 5
	s_nop 1
	v_readlane_b32 s100, v122, 13
	v_add_f32_e32 v72, v72, v73
	s_lshl_b32 s100, s100, 11
	s_add_u32 s100, s96, s100
	s_addc_u32 s101, s97, 0
	global_load_dwordx4 v[104:107], v178, s[100:101]
	global_load_dwordx4 v[108:111], v178, s[100:101] offset:1024
	s_waitcnt vmcnt(12)
	v_cvt_pk_f32_fp8_e32 v[64:65], v24
	v_pk_fma_f32 v[74:75], v[64:65], v[124:125], 0 op_sel_hi:[1,1,0]
	v_cvt_pk_f32_fp8_sdwa v[66:67], v24 src0_sel:WORD_1
	v_pk_fma_f32 v[74:75], v[66:67], v[126:127], v[74:75]
	v_cvt_pk_f32_fp8_e32 v[68:69], v25
	v_pk_fma_f32 v[74:75], v[68:69], v[128:129], v[74:75]
	v_cvt_pk_f32_fp8_sdwa v[70:71], v25 src0_sel:WORD_1
	v_pk_fma_f32 v[74:75], v[70:71], v[130:131], v[74:75]
	v_cvt_pk_f32_fp8_e32 v[64:65], v26
	v_pk_fma_f32 v[74:75], v[64:65], v[132:133], v[74:75]
	v_cvt_pk_f32_fp8_sdwa v[66:67], v26 src0_sel:WORD_1
	v_pk_fma_f32 v[74:75], v[66:67], v[134:135], v[74:75]
	v_add_f32_dpp v72, v72, v72 quad_perm:[1,0,3,2] row_mask:0xf bank_mask:0xf bound_ctrl:1
	v_cvt_pk_f32_fp8_e32 v[68:69], v27
	v_pk_fma_f32 v[74:75], v[68:69], v[136:137], v[74:75]
	v_cvt_pk_f32_fp8_sdwa v[70:71], v27 src0_sel:WORD_1
	v_add_f32_dpp v72, v72, v72 quad_perm:[2,3,0,1] row_mask:0xf bank_mask:0xf bound_ctrl:1
	v_pk_fma_f32 v[74:75], v[70:71], v[138:139], v[74:75]
	v_cvt_pk_f32_fp8_e32 v[64:65], v28
	v_pk_fma_f32 v[74:75], v[64:65], v[140:141], v[74:75]
	v_add_f32_dpp v72, v72, v72 row_half_mirror row_mask:0xf bank_mask:0xf bound_ctrl:1
	v_cvt_pk_f32_fp8_sdwa v[66:67], v28 src0_sel:WORD_1
	v_pk_fma_f32 v[74:75], v[66:67], v[142:143], v[74:75]
	v_cvt_pk_f32_fp8_e32 v[68:69], v29
	v_add_f32_dpp v72, v72, v72 row_mirror row_mask:0xf bank_mask:0xf bound_ctrl:1
	v_pk_fma_f32 v[74:75], v[68:69], v[144:145], v[74:75]
	v_cvt_pk_f32_fp8_sdwa v[70:71], v29 src0_sel:WORD_1
	v_pk_fma_f32 v[74:75], v[70:71], v[146:147], v[74:75]
	v_add_f32_dpp v72, v72, v72 row_bcast:15 row_mask:0xa bank_mask:0xf
	v_cvt_pk_f32_fp8_e32 v[64:65], v30
	v_pk_fma_f32 v[74:75], v[64:65], v[148:149], v[74:75]
	v_cvt_pk_f32_fp8_sdwa v[66:67], v30 src0_sel:WORD_1
	v_add_f32_dpp v72, v72, v72 row_bcast:31 row_mask:0xc bank_mask:0xf
	v_pk_fma_f32 v[74:75], v[66:67], v[150:151], v[74:75]
	v_cvt_pk_f32_fp8_e32 v[68:69], v31
	v_readlane_b32 s50, v72, 63
	v_pk_fma_f32 v[74:75], v[68:69], v[152:153], v[74:75]
	v_cvt_pk_f32_fp8_sdwa v[70:71], v31 src0_sel:WORD_1
	v_pk_fma_f32 v[74:75], v[70:71], v[154:155], v[74:75]
	v_writelane_b32 v177, s50, 6
	s_nop 1
	v_readlane_b32 s100, v122, 14
	v_add_f32_e32 v74, v74, v75
	s_lshl_b32 s100, s100, 11
	s_add_u32 s100, s96, s100
	s_addc_u32 s101, s97, 0
	global_load_dwordx4 v[12:15], v178, s[100:101]
	global_load_dwordx4 v[20:23], v178, s[100:101] offset:1024
	s_waitcnt vmcnt(12)
	v_cvt_pk_f32_fp8_e32 v[64:65], v0
	v_pk_fma_f32 v[72:73], v[64:65], v[124:125], 0 op_sel_hi:[1,1,0]
	v_cvt_pk_f32_fp8_sdwa v[66:67], v0 src0_sel:WORD_1
	v_pk_fma_f32 v[72:73], v[66:67], v[126:127], v[72:73]
	v_cvt_pk_f32_fp8_e32 v[68:69], v1
	v_pk_fma_f32 v[72:73], v[68:69], v[128:129], v[72:73]
	v_cvt_pk_f32_fp8_sdwa v[70:71], v1 src0_sel:WORD_1
	v_pk_fma_f32 v[72:73], v[70:71], v[130:131], v[72:73]
	v_cvt_pk_f32_fp8_e32 v[64:65], v2
	v_pk_fma_f32 v[72:73], v[64:65], v[132:133], v[72:73]
	v_cvt_pk_f32_fp8_sdwa v[66:67], v2 src0_sel:WORD_1
	v_pk_fma_f32 v[72:73], v[66:67], v[134:135], v[72:73]
	v_add_f32_dpp v74, v74, v74 quad_perm:[1,0,3,2] row_mask:0xf bank_mask:0xf bound_ctrl:1
	v_cvt_pk_f32_fp8_e32 v[68:69], v3
	v_pk_fma_f32 v[72:73], v[68:69], v[136:137], v[72:73]
	v_cvt_pk_f32_fp8_sdwa v[70:71], v3 src0_sel:WORD_1
	v_add_f32_dpp v74, v74, v74 quad_perm:[2,3,0,1] row_mask:0xf bank_mask:0xf bound_ctrl:1
	v_pk_fma_f32 v[72:73], v[70:71], v[138:139], v[72:73]
	v_cvt_pk_f32_fp8_e32 v[64:65], v4
	v_pk_fma_f32 v[72:73], v[64:65], v[140:141], v[72:73]
	v_add_f32_dpp v74, v74, v74 row_half_mirror row_mask:0xf bank_mask:0xf bound_ctrl:1
	v_cvt_pk_f32_fp8_sdwa v[66:67], v4 src0_sel:WORD_1
	v_pk_fma_f32 v[72:73], v[66:67], v[142:143], v[72:73]
	v_cvt_pk_f32_fp8_e32 v[68:69], v5
	v_add_f32_dpp v74, v74, v74 row_mirror row_mask:0xf bank_mask:0xf bound_ctrl:1
	v_pk_fma_f32 v[72:73], v[68:69], v[144:145], v[72:73]
	v_cvt_pk_f32_fp8_sdwa v[70:71], v5 src0_sel:WORD_1
	v_pk_fma_f32 v[72:73], v[70:71], v[146:147], v[72:73]
	v_add_f32_dpp v74, v74, v74 row_bcast:15 row_mask:0xa bank_mask:0xf
	v_cvt_pk_f32_fp8_e32 v[64:65], v6
	v_pk_fma_f32 v[72:73], v[64:65], v[148:149], v[72:73]
	v_cvt_pk_f32_fp8_sdwa v[66:67], v6 src0_sel:WORD_1
	v_add_f32_dpp v74, v74, v74 row_bcast:31 row_mask:0xc bank_mask:0xf
	v_pk_fma_f32 v[72:73], v[66:67], v[150:151], v[72:73]
	v_cvt_pk_f32_fp8_e32 v[68:69], v7
	v_readlane_b32 s50, v74, 63
	v_pk_fma_f32 v[72:73], v[68:69], v[152:153], v[72:73]
	v_cvt_pk_f32_fp8_sdwa v[70:71], v7 src0_sel:WORD_1
	v_pk_fma_f32 v[72:73], v[70:71], v[154:155], v[72:73]
	v_writelane_b32 v177, s50, 7
	s_nop 1
	v_readlane_b32 s100, v122, 15
	v_add_f32_e32 v72, v72, v73
	s_lshl_b32 s100, s100, 11
	s_add_u32 s100, s96, s100
	s_addc_u32 s101, s97, 0
	global_load_dwordx4 v[24:27], v178, s[100:101]
	global_load_dwordx4 v[28:31], v178, s[100:101] offset:1024
	s_waitcnt vmcnt(12)
	v_cvt_pk_f32_fp8_e32 v[64:65], v8
	v_pk_fma_f32 v[74:75], v[64:65], v[124:125], 0 op_sel_hi:[1,1,0]
	v_cvt_pk_f32_fp8_sdwa v[66:67], v8 src0_sel:WORD_1
	v_pk_fma_f32 v[74:75], v[66:67], v[126:127], v[74:75]
	v_cvt_pk_f32_fp8_e32 v[68:69], v9
	v_pk_fma_f32 v[74:75], v[68:69], v[128:129], v[74:75]
	v_cvt_pk_f32_fp8_sdwa v[70:71], v9 src0_sel:WORD_1
	v_pk_fma_f32 v[74:75], v[70:71], v[130:131], v[74:75]
	v_cvt_pk_f32_fp8_e32 v[64:65], v10
	v_pk_fma_f32 v[74:75], v[64:65], v[132:133], v[74:75]
	v_cvt_pk_f32_fp8_sdwa v[66:67], v10 src0_sel:WORD_1
	v_pk_fma_f32 v[74:75], v[66:67], v[134:135], v[74:75]
	v_add_f32_dpp v72, v72, v72 quad_perm:[1,0,3,2] row_mask:0xf bank_mask:0xf bound_ctrl:1
	v_cvt_pk_f32_fp8_e32 v[68:69], v11
	v_pk_fma_f32 v[74:75], v[68:69], v[136:137], v[74:75]
	v_cvt_pk_f32_fp8_sdwa v[70:71], v11 src0_sel:WORD_1
	v_add_f32_dpp v72, v72, v72 quad_perm:[2,3,0,1] row_mask:0xf bank_mask:0xf bound_ctrl:1
	v_pk_fma_f32 v[74:75], v[70:71], v[138:139], v[74:75]
	v_cvt_pk_f32_fp8_e32 v[64:65], v16
	v_pk_fma_f32 v[74:75], v[64:65], v[140:141], v[74:75]
	v_add_f32_dpp v72, v72, v72 row_half_mirror row_mask:0xf bank_mask:0xf bound_ctrl:1
	v_cvt_pk_f32_fp8_sdwa v[66:67], v16 src0_sel:WORD_1
	v_pk_fma_f32 v[74:75], v[66:67], v[142:143], v[74:75]
	v_cvt_pk_f32_fp8_e32 v[68:69], v17
	v_add_f32_dpp v72, v72, v72 row_mirror row_mask:0xf bank_mask:0xf bound_ctrl:1
	v_pk_fma_f32 v[74:75], v[68:69], v[144:145], v[74:75]
	v_cvt_pk_f32_fp8_sdwa v[70:71], v17 src0_sel:WORD_1
	v_pk_fma_f32 v[74:75], v[70:71], v[146:147], v[74:75]
	v_add_f32_dpp v72, v72, v72 row_bcast:15 row_mask:0xa bank_mask:0xf
	v_cvt_pk_f32_fp8_e32 v[64:65], v18
	v_pk_fma_f32 v[74:75], v[64:65], v[148:149], v[74:75]
	v_cvt_pk_f32_fp8_sdwa v[66:67], v18 src0_sel:WORD_1
	v_add_f32_dpp v72, v72, v72 row_bcast:31 row_mask:0xc bank_mask:0xf
	v_pk_fma_f32 v[74:75], v[66:67], v[150:151], v[74:75]
	v_cvt_pk_f32_fp8_e32 v[68:69], v19
	v_readlane_b32 s50, v72, 63
	v_pk_fma_f32 v[74:75], v[68:69], v[152:153], v[74:75]
	v_cvt_pk_f32_fp8_sdwa v[70:71], v19 src0_sel:WORD_1
	v_pk_fma_f32 v[74:75], v[70:71], v[154:155], v[74:75]
	v_writelane_b32 v177, s50, 8
	s_nop 1
	v_readlane_b32 s100, v122, 0
	v_add_f32_e32 v74, v74, v75
	s_lshl_b32 s100, s100, 11
	s_add_u32 s100, s98, s100
	s_addc_u32 s101, s99, 0
	global_load_dwordx4 v[192:195], v178, s[100:101]
	global_load_dwordx4 v[196:199], v178, s[100:101] offset:1024
	s_waitcnt vmcnt(12)
	v_cvt_pk_f32_fp8_e32 v[64:65], v80
	v_pk_fma_f32 v[72:73], v[64:65], v[124:125], 0 op_sel_hi:[1,1,0]
	v_cvt_pk_f32_fp8_sdwa v[66:67], v80 src0_sel:WORD_1
	v_pk_fma_f32 v[72:73], v[66:67], v[126:127], v[72:73]
	v_cvt_pk_f32_fp8_e32 v[68:69], v81
	v_pk_fma_f32 v[72:73], v[68:69], v[128:129], v[72:73]
	v_cvt_pk_f32_fp8_sdwa v[70:71], v81 src0_sel:WORD_1
	v_pk_fma_f32 v[72:73], v[70:71], v[130:131], v[72:73]
	v_cvt_pk_f32_fp8_e32 v[64:65], v82
	v_pk_fma_f32 v[72:73], v[64:65], v[132:133], v[72:73]
	v_cvt_pk_f32_fp8_sdwa v[66:67], v82 src0_sel:WORD_1
	v_pk_fma_f32 v[72:73], v[66:67], v[134:135], v[72:73]
	v_add_f32_dpp v74, v74, v74 quad_perm:[1,0,3,2] row_mask:0xf bank_mask:0xf bound_ctrl:1
	v_cvt_pk_f32_fp8_e32 v[68:69], v83
	v_pk_fma_f32 v[72:73], v[68:69], v[136:137], v[72:73]
	v_cvt_pk_f32_fp8_sdwa v[70:71], v83 src0_sel:WORD_1
	v_add_f32_dpp v74, v74, v74 quad_perm:[2,3,0,1] row_mask:0xf bank_mask:0xf bound_ctrl:1
	v_pk_fma_f32 v[72:73], v[70:71], v[138:139], v[72:73]
	v_cvt_pk_f32_fp8_e32 v[64:65], v84
	v_pk_fma_f32 v[72:73], v[64:65], v[140:141], v[72:73]
	v_add_f32_dpp v74, v74, v74 row_half_mirror row_mask:0xf bank_mask:0xf bound_ctrl:1
	v_cvt_pk_f32_fp8_sdwa v[66:67], v84 src0_sel:WORD_1
	v_pk_fma_f32 v[72:73], v[66:67], v[142:143], v[72:73]
	v_cvt_pk_f32_fp8_e32 v[68:69], v85
	v_add_f32_dpp v74, v74, v74 row_mirror row_mask:0xf bank_mask:0xf bound_ctrl:1
	v_pk_fma_f32 v[72:73], v[68:69], v[144:145], v[72:73]
	v_cvt_pk_f32_fp8_sdwa v[70:71], v85 src0_sel:WORD_1
	v_pk_fma_f32 v[72:73], v[70:71], v[146:147], v[72:73]
	v_add_f32_dpp v74, v74, v74 row_bcast:15 row_mask:0xa bank_mask:0xf
	v_cvt_pk_f32_fp8_e32 v[64:65], v86
	v_pk_fma_f32 v[72:73], v[64:65], v[148:149], v[72:73]
	v_cvt_pk_f32_fp8_sdwa v[66:67], v86 src0_sel:WORD_1
	v_add_f32_dpp v74, v74, v74 row_bcast:31 row_mask:0xc bank_mask:0xf
	v_pk_fma_f32 v[72:73], v[66:67], v[150:151], v[72:73]
	v_cvt_pk_f32_fp8_e32 v[68:69], v87
	v_readlane_b32 s50, v74, 63
	v_pk_fma_f32 v[72:73], v[68:69], v[152:153], v[72:73]
	v_cvt_pk_f32_fp8_sdwa v[70:71], v87 src0_sel:WORD_1
	v_pk_fma_f32 v[72:73], v[70:71], v[154:155], v[72:73]
	v_writelane_b32 v177, s50, 9
	s_nop 1
	v_readlane_b32 s100, v122, 1
	v_add_f32_e32 v72, v72, v73
	s_lshl_b32 s100, s100, 11
	s_add_u32 s100, s98, s100
	s_addc_u32 s101, s99, 0
	global_load_dwordx4 v[200:203], v178, s[100:101]
	global_load_dwordx4 v[204:207], v178, s[100:101] offset:1024
	s_waitcnt vmcnt(12)
	v_cvt_pk_f32_fp8_e32 v[64:65], v88
	v_pk_fma_f32 v[74:75], v[64:65], v[124:125], 0 op_sel_hi:[1,1,0]
	v_cvt_pk_f32_fp8_sdwa v[66:67], v88 src0_sel:WORD_1
	v_pk_fma_f32 v[74:75], v[66:67], v[126:127], v[74:75]
	v_cvt_pk_f32_fp8_e32 v[68:69], v89
	v_pk_fma_f32 v[74:75], v[68:69], v[128:129], v[74:75]
	v_cvt_pk_f32_fp8_sdwa v[70:71], v89 src0_sel:WORD_1
	v_pk_fma_f32 v[74:75], v[70:71], v[130:131], v[74:75]
	v_cvt_pk_f32_fp8_e32 v[64:65], v90
	v_pk_fma_f32 v[74:75], v[64:65], v[132:133], v[74:75]
	v_cvt_pk_f32_fp8_sdwa v[66:67], v90 src0_sel:WORD_1
	v_pk_fma_f32 v[74:75], v[66:67], v[134:135], v[74:75]
	v_add_f32_dpp v72, v72, v72 quad_perm:[1,0,3,2] row_mask:0xf bank_mask:0xf bound_ctrl:1
	v_cvt_pk_f32_fp8_e32 v[68:69], v91
	v_pk_fma_f32 v[74:75], v[68:69], v[136:137], v[74:75]
	v_cvt_pk_f32_fp8_sdwa v[70:71], v91 src0_sel:WORD_1
	v_add_f32_dpp v72, v72, v72 quad_perm:[2,3,0,1] row_mask:0xf bank_mask:0xf bound_ctrl:1
	v_pk_fma_f32 v[74:75], v[70:71], v[138:139], v[74:75]
	v_cvt_pk_f32_fp8_e32 v[64:65], v92
	v_pk_fma_f32 v[74:75], v[64:65], v[140:141], v[74:75]
	v_add_f32_dpp v72, v72, v72 row_half_mirror row_mask:0xf bank_mask:0xf bound_ctrl:1
	v_cvt_pk_f32_fp8_sdwa v[66:67], v92 src0_sel:WORD_1
	v_pk_fma_f32 v[74:75], v[66:67], v[142:143], v[74:75]
	v_cvt_pk_f32_fp8_e32 v[68:69], v93
	v_add_f32_dpp v72, v72, v72 row_mirror row_mask:0xf bank_mask:0xf bound_ctrl:1
	v_pk_fma_f32 v[74:75], v[68:69], v[144:145], v[74:75]
	v_cvt_pk_f32_fp8_sdwa v[70:71], v93 src0_sel:WORD_1
	v_pk_fma_f32 v[74:75], v[70:71], v[146:147], v[74:75]
	v_add_f32_dpp v72, v72, v72 row_bcast:15 row_mask:0xa bank_mask:0xf
	v_cvt_pk_f32_fp8_e32 v[64:65], v94
	v_pk_fma_f32 v[74:75], v[64:65], v[148:149], v[74:75]
	v_cvt_pk_f32_fp8_sdwa v[66:67], v94 src0_sel:WORD_1
	v_add_f32_dpp v72, v72, v72 row_bcast:31 row_mask:0xc bank_mask:0xf
	v_pk_fma_f32 v[74:75], v[66:67], v[150:151], v[74:75]
	v_cvt_pk_f32_fp8_e32 v[68:69], v95
	v_readlane_b32 s50, v72, 63
	v_pk_fma_f32 v[74:75], v[68:69], v[152:153], v[74:75]
	v_cvt_pk_f32_fp8_sdwa v[70:71], v95 src0_sel:WORD_1
	v_pk_fma_f32 v[74:75], v[70:71], v[154:155], v[74:75]
	v_writelane_b32 v177, s50, 10
	s_nop 1
	v_readlane_b32 s100, v122, 2
	v_add_f32_e32 v74, v74, v75
	s_lshl_b32 s100, s100, 11
	s_add_u32 s100, s98, s100
	s_addc_u32 s101, s99, 0
	global_load_dwordx4 v[208:211], v178, s[100:101]
	global_load_dwordx4 v[212:215], v178, s[100:101] offset:1024
	s_waitcnt vmcnt(12)
	v_cvt_pk_f32_fp8_e32 v[64:65], v96
	v_pk_fma_f32 v[72:73], v[64:65], v[124:125], 0 op_sel_hi:[1,1,0]
	v_cvt_pk_f32_fp8_sdwa v[66:67], v96 src0_sel:WORD_1
	v_pk_fma_f32 v[72:73], v[66:67], v[126:127], v[72:73]
	v_cvt_pk_f32_fp8_e32 v[68:69], v97
	v_pk_fma_f32 v[72:73], v[68:69], v[128:129], v[72:73]
	v_cvt_pk_f32_fp8_sdwa v[70:71], v97 src0_sel:WORD_1
	v_pk_fma_f32 v[72:73], v[70:71], v[130:131], v[72:73]
	v_cvt_pk_f32_fp8_e32 v[64:65], v98
	v_pk_fma_f32 v[72:73], v[64:65], v[132:133], v[72:73]
	v_cvt_pk_f32_fp8_sdwa v[66:67], v98 src0_sel:WORD_1
	v_pk_fma_f32 v[72:73], v[66:67], v[134:135], v[72:73]
	v_add_f32_dpp v74, v74, v74 quad_perm:[1,0,3,2] row_mask:0xf bank_mask:0xf bound_ctrl:1
	v_cvt_pk_f32_fp8_e32 v[68:69], v99
	v_pk_fma_f32 v[72:73], v[68:69], v[136:137], v[72:73]
	v_cvt_pk_f32_fp8_sdwa v[70:71], v99 src0_sel:WORD_1
	v_add_f32_dpp v74, v74, v74 quad_perm:[2,3,0,1] row_mask:0xf bank_mask:0xf bound_ctrl:1
	v_pk_fma_f32 v[72:73], v[70:71], v[138:139], v[72:73]
	v_cvt_pk_f32_fp8_e32 v[64:65], v100
	v_pk_fma_f32 v[72:73], v[64:65], v[140:141], v[72:73]
	v_add_f32_dpp v74, v74, v74 row_half_mirror row_mask:0xf bank_mask:0xf bound_ctrl:1
	v_cvt_pk_f32_fp8_sdwa v[66:67], v100 src0_sel:WORD_1
	v_pk_fma_f32 v[72:73], v[66:67], v[142:143], v[72:73]
	v_cvt_pk_f32_fp8_e32 v[68:69], v101
	v_add_f32_dpp v74, v74, v74 row_mirror row_mask:0xf bank_mask:0xf bound_ctrl:1
	v_pk_fma_f32 v[72:73], v[68:69], v[144:145], v[72:73]
	v_cvt_pk_f32_fp8_sdwa v[70:71], v101 src0_sel:WORD_1
	v_pk_fma_f32 v[72:73], v[70:71], v[146:147], v[72:73]
	v_add_f32_dpp v74, v74, v74 row_bcast:15 row_mask:0xa bank_mask:0xf
	v_cvt_pk_f32_fp8_e32 v[64:65], v102
	v_pk_fma_f32 v[72:73], v[64:65], v[148:149], v[72:73]
	v_cvt_pk_f32_fp8_sdwa v[66:67], v102 src0_sel:WORD_1
	v_add_f32_dpp v74, v74, v74 row_bcast:31 row_mask:0xc bank_mask:0xf
	v_pk_fma_f32 v[72:73], v[66:67], v[150:151], v[72:73]
	v_cvt_pk_f32_fp8_e32 v[68:69], v103
	v_readlane_b32 s50, v74, 63
	v_pk_fma_f32 v[72:73], v[68:69], v[152:153], v[72:73]
	v_cvt_pk_f32_fp8_sdwa v[70:71], v103 src0_sel:WORD_1
	v_pk_fma_f32 v[72:73], v[70:71], v[154:155], v[72:73]
	v_writelane_b32 v177, s50, 11
	s_nop 1
	v_readlane_b32 s100, v122, 3
	v_add_f32_e32 v72, v72, v73
	s_lshl_b32 s100, s100, 11
	s_add_u32 s100, s98, s100
	s_addc_u32 s101, s99, 0
	global_load_dwordx4 v[216:219], v178, s[100:101]
	global_load_dwordx4 v[220:223], v178, s[100:101] offset:1024
	s_waitcnt vmcnt(12)
	v_cvt_pk_f32_fp8_e32 v[64:65], v104
	v_pk_fma_f32 v[74:75], v[64:65], v[124:125], 0 op_sel_hi:[1,1,0]
	v_cvt_pk_f32_fp8_sdwa v[66:67], v104 src0_sel:WORD_1
	v_pk_fma_f32 v[74:75], v[66:67], v[126:127], v[74:75]
	v_cvt_pk_f32_fp8_e32 v[68:69], v105
	v_pk_fma_f32 v[74:75], v[68:69], v[128:129], v[74:75]
	v_cvt_pk_f32_fp8_sdwa v[70:71], v105 src0_sel:WORD_1
	v_pk_fma_f32 v[74:75], v[70:71], v[130:131], v[74:75]
	v_cvt_pk_f32_fp8_e32 v[64:65], v106
	v_pk_fma_f32 v[74:75], v[64:65], v[132:133], v[74:75]
	v_cvt_pk_f32_fp8_sdwa v[66:67], v106 src0_sel:WORD_1
	v_pk_fma_f32 v[74:75], v[66:67], v[134:135], v[74:75]
	v_add_f32_dpp v72, v72, v72 quad_perm:[1,0,3,2] row_mask:0xf bank_mask:0xf bound_ctrl:1
	v_cvt_pk_f32_fp8_e32 v[68:69], v107
	v_pk_fma_f32 v[74:75], v[68:69], v[136:137], v[74:75]
	v_cvt_pk_f32_fp8_sdwa v[70:71], v107 src0_sel:WORD_1
	v_add_f32_dpp v72, v72, v72 quad_perm:[2,3,0,1] row_mask:0xf bank_mask:0xf bound_ctrl:1
	v_pk_fma_f32 v[74:75], v[70:71], v[138:139], v[74:75]
	v_cvt_pk_f32_fp8_e32 v[64:65], v108
	v_pk_fma_f32 v[74:75], v[64:65], v[140:141], v[74:75]
	v_add_f32_dpp v72, v72, v72 row_half_mirror row_mask:0xf bank_mask:0xf bound_ctrl:1
	v_cvt_pk_f32_fp8_sdwa v[66:67], v108 src0_sel:WORD_1
	v_pk_fma_f32 v[74:75], v[66:67], v[142:143], v[74:75]
	v_cvt_pk_f32_fp8_e32 v[68:69], v109
	v_add_f32_dpp v72, v72, v72 row_mirror row_mask:0xf bank_mask:0xf bound_ctrl:1
	v_pk_fma_f32 v[74:75], v[68:69], v[144:145], v[74:75]
	v_cvt_pk_f32_fp8_sdwa v[70:71], v109 src0_sel:WORD_1
	v_pk_fma_f32 v[74:75], v[70:71], v[146:147], v[74:75]
	v_add_f32_dpp v72, v72, v72 row_bcast:15 row_mask:0xa bank_mask:0xf
	v_cvt_pk_f32_fp8_e32 v[64:65], v110
	v_pk_fma_f32 v[74:75], v[64:65], v[148:149], v[74:75]
	v_cvt_pk_f32_fp8_sdwa v[66:67], v110 src0_sel:WORD_1
	v_add_f32_dpp v72, v72, v72 row_bcast:31 row_mask:0xc bank_mask:0xf
	v_pk_fma_f32 v[74:75], v[66:67], v[150:151], v[74:75]
	v_cvt_pk_f32_fp8_e32 v[68:69], v111
	v_readlane_b32 s50, v72, 63
	v_pk_fma_f32 v[74:75], v[68:69], v[152:153], v[74:75]
	v_cvt_pk_f32_fp8_sdwa v[70:71], v111 src0_sel:WORD_1
	v_pk_fma_f32 v[74:75], v[70:71], v[154:155], v[74:75]
	v_writelane_b32 v177, s50, 12
	s_nop 1
	v_readlane_b32 s100, v122, 4
	v_add_f32_e32 v74, v74, v75
	s_lshl_b32 s100, s100, 11
	s_add_u32 s100, s98, s100
	s_addc_u32 s101, s99, 0
	global_load_dwordx4 v[224:227], v178, s[100:101]
	global_load_dwordx4 v[228:231], v178, s[100:101] offset:1024
	s_waitcnt vmcnt(12)
	v_cvt_pk_f32_fp8_e32 v[64:65], v12
	v_pk_fma_f32 v[72:73], v[64:65], v[124:125], 0 op_sel_hi:[1,1,0]
	v_cvt_pk_f32_fp8_sdwa v[66:67], v12 src0_sel:WORD_1
	v_pk_fma_f32 v[72:73], v[66:67], v[126:127], v[72:73]
	v_cvt_pk_f32_fp8_e32 v[68:69], v13
	v_pk_fma_f32 v[72:73], v[68:69], v[128:129], v[72:73]
	v_cvt_pk_f32_fp8_sdwa v[70:71], v13 src0_sel:WORD_1
	v_pk_fma_f32 v[72:73], v[70:71], v[130:131], v[72:73]
	v_cvt_pk_f32_fp8_e32 v[64:65], v14
	v_pk_fma_f32 v[72:73], v[64:65], v[132:133], v[72:73]
	v_cvt_pk_f32_fp8_sdwa v[66:67], v14 src0_sel:WORD_1
	v_pk_fma_f32 v[72:73], v[66:67], v[134:135], v[72:73]
	v_add_f32_dpp v74, v74, v74 quad_perm:[1,0,3,2] row_mask:0xf bank_mask:0xf bound_ctrl:1
	v_cvt_pk_f32_fp8_e32 v[68:69], v15
	v_pk_fma_f32 v[72:73], v[68:69], v[136:137], v[72:73]
	v_cvt_pk_f32_fp8_sdwa v[70:71], v15 src0_sel:WORD_1
	v_add_f32_dpp v74, v74, v74 quad_perm:[2,3,0,1] row_mask:0xf bank_mask:0xf bound_ctrl:1
	v_pk_fma_f32 v[72:73], v[70:71], v[138:139], v[72:73]
	v_cvt_pk_f32_fp8_e32 v[64:65], v20
	v_pk_fma_f32 v[72:73], v[64:65], v[140:141], v[72:73]
	v_add_f32_dpp v74, v74, v74 row_half_mirror row_mask:0xf bank_mask:0xf bound_ctrl:1
	v_cvt_pk_f32_fp8_sdwa v[66:67], v20 src0_sel:WORD_1
	v_pk_fma_f32 v[72:73], v[66:67], v[142:143], v[72:73]
	v_cvt_pk_f32_fp8_e32 v[68:69], v21
	v_add_f32_dpp v74, v74, v74 row_mirror row_mask:0xf bank_mask:0xf bound_ctrl:1
	v_pk_fma_f32 v[72:73], v[68:69], v[144:145], v[72:73]
	v_cvt_pk_f32_fp8_sdwa v[70:71], v21 src0_sel:WORD_1
	v_pk_fma_f32 v[72:73], v[70:71], v[146:147], v[72:73]
	v_add_f32_dpp v74, v74, v74 row_bcast:15 row_mask:0xa bank_mask:0xf
	v_cvt_pk_f32_fp8_e32 v[64:65], v22
	v_pk_fma_f32 v[72:73], v[64:65], v[148:149], v[72:73]
	v_cvt_pk_f32_fp8_sdwa v[66:67], v22 src0_sel:WORD_1
	v_add_f32_dpp v74, v74, v74 row_bcast:31 row_mask:0xc bank_mask:0xf
	v_pk_fma_f32 v[72:73], v[66:67], v[150:151], v[72:73]
	v_cvt_pk_f32_fp8_e32 v[68:69], v23
	v_readlane_b32 s50, v74, 63
	v_pk_fma_f32 v[72:73], v[68:69], v[152:153], v[72:73]
	v_cvt_pk_f32_fp8_sdwa v[70:71], v23 src0_sel:WORD_1
	v_pk_fma_f32 v[72:73], v[70:71], v[154:155], v[72:73]
	v_writelane_b32 v177, s50, 13
	s_nop 1
	v_readlane_b32 s100, v122, 5
	v_add_f32_e32 v72, v72, v73
	s_lshl_b32 s100, s100, 11
	s_add_u32 s100, s98, s100
	s_addc_u32 s101, s99, 0
	global_load_dwordx4 v[232:235], v178, s[100:101]
	global_load_dwordx4 v[236:239], v178, s[100:101] offset:1024
	s_waitcnt vmcnt(12)
	v_cvt_pk_f32_fp8_e32 v[64:65], v24
	v_pk_fma_f32 v[74:75], v[64:65], v[124:125], 0 op_sel_hi:[1,1,0]
	v_cvt_pk_f32_fp8_sdwa v[66:67], v24 src0_sel:WORD_1
	v_pk_fma_f32 v[74:75], v[66:67], v[126:127], v[74:75]
	v_cvt_pk_f32_fp8_e32 v[68:69], v25
	v_pk_fma_f32 v[74:75], v[68:69], v[128:129], v[74:75]
	v_cvt_pk_f32_fp8_sdwa v[70:71], v25 src0_sel:WORD_1
	v_pk_fma_f32 v[74:75], v[70:71], v[130:131], v[74:75]
	v_cvt_pk_f32_fp8_e32 v[64:65], v26
	v_pk_fma_f32 v[74:75], v[64:65], v[132:133], v[74:75]
	v_cvt_pk_f32_fp8_sdwa v[66:67], v26 src0_sel:WORD_1
	v_pk_fma_f32 v[74:75], v[66:67], v[134:135], v[74:75]
	v_add_f32_dpp v72, v72, v72 quad_perm:[1,0,3,2] row_mask:0xf bank_mask:0xf bound_ctrl:1
	v_cvt_pk_f32_fp8_e32 v[68:69], v27
	v_pk_fma_f32 v[74:75], v[68:69], v[136:137], v[74:75]
	v_cvt_pk_f32_fp8_sdwa v[70:71], v27 src0_sel:WORD_1
	v_add_f32_dpp v72, v72, v72 quad_perm:[2,3,0,1] row_mask:0xf bank_mask:0xf bound_ctrl:1
	v_pk_fma_f32 v[74:75], v[70:71], v[138:139], v[74:75]
	v_cvt_pk_f32_fp8_e32 v[64:65], v28
	v_pk_fma_f32 v[74:75], v[64:65], v[140:141], v[74:75]
	v_add_f32_dpp v72, v72, v72 row_half_mirror row_mask:0xf bank_mask:0xf bound_ctrl:1
	v_cvt_pk_f32_fp8_sdwa v[66:67], v28 src0_sel:WORD_1
	v_pk_fma_f32 v[74:75], v[66:67], v[142:143], v[74:75]
	v_cvt_pk_f32_fp8_e32 v[68:69], v29
	v_add_f32_dpp v72, v72, v72 row_mirror row_mask:0xf bank_mask:0xf bound_ctrl:1
	v_pk_fma_f32 v[74:75], v[68:69], v[144:145], v[74:75]
	v_cvt_pk_f32_fp8_sdwa v[70:71], v29 src0_sel:WORD_1
	v_pk_fma_f32 v[74:75], v[70:71], v[146:147], v[74:75]
	v_add_f32_dpp v72, v72, v72 row_bcast:15 row_mask:0xa bank_mask:0xf
	v_cvt_pk_f32_fp8_e32 v[64:65], v30
	v_pk_fma_f32 v[74:75], v[64:65], v[148:149], v[74:75]
	v_cvt_pk_f32_fp8_sdwa v[66:67], v30 src0_sel:WORD_1
	v_add_f32_dpp v72, v72, v72 row_bcast:31 row_mask:0xc bank_mask:0xf
	v_pk_fma_f32 v[74:75], v[66:67], v[150:151], v[74:75]
	v_cvt_pk_f32_fp8_e32 v[68:69], v31
	v_readlane_b32 s50, v72, 63
	v_pk_fma_f32 v[74:75], v[68:69], v[152:153], v[74:75]
	v_cvt_pk_f32_fp8_sdwa v[70:71], v31 src0_sel:WORD_1
	v_pk_fma_f32 v[74:75], v[70:71], v[154:155], v[74:75]
	v_writelane_b32 v177, s50, 14
	s_nop 1
	v_add_f32_e32 v74, v74, v75
	v_mul_f32_e32 v179, v173, v176
	v_mul_f32_e32 v179, 0.5, v179
	v_add_f32_dpp v74, v74, v74 quad_perm:[1,0,3,2] row_mask:0xf bank_mask:0xf bound_ctrl:1
	s_nop 0
	s_nop 0
	v_add_f32_dpp v74, v74, v74 quad_perm:[2,3,0,1] row_mask:0xf bank_mask:0xf bound_ctrl:1
	s_nop 0
	s_nop 0
	v_add_f32_dpp v74, v74, v74 row_half_mirror row_mask:0xf bank_mask:0xf bound_ctrl:1
	s_nop 0
	s_nop 0
	v_add_f32_dpp v74, v74, v74 row_mirror row_mask:0xf bank_mask:0xf bound_ctrl:1
	s_nop 0
	s_nop 0
	v_add_f32_dpp v74, v74, v74 row_bcast:15 row_mask:0xa bank_mask:0xf
	s_nop 0
	s_nop 0
	v_add_f32_dpp v74, v74, v74 row_bcast:31 row_mask:0xc bank_mask:0xf
	s_nop 0
	v_readlane_b32 s50, v74, 63
	s_nop 0
	s_nop 0
	v_writelane_b32 v177, s50, 15
	v_mul_f32_e32 v64, v175, v177
	v_mul_f32_e32 v65, 0x3f3504f3, v64
	v_fma_f32 v66, |v65|, s55, v171
	v_fma_f32 v66, |v65|, v66, s56
	v_fma_f32 v66, |v65|, v66, s57
	v_fma_f32 v66, |v65|, v66, s58
	v_fma_f32 v66, |v65|, v66, s59
	v_fma_f32 v66, |v65|, v66, s60
	v_fma_f32 v66, |v65|, v66, |v65|
	v_mul_f32_e32 v67, 0xbfb8aa3b, v66
	v_fma_f32 v68, v66, s61, -v67
	v_rndne_f32_e32 v69, v67
	v_fmac_f32_e32 v68, 0xb2a5705f, v66
	v_sub_f32_e32 v67, v67, v69
	v_add_f32_e32 v67, v67, v68
	v_exp_f32_e32 v67, v67
	v_cmp_nlt_f32_e32 vcc, s62, v66
	v_cvt_i32_f32_e32 v68, v69
	v_ldexp_f32 v67, v67, v68
	v_cndmask_b32_e32 v67, 0, v67, vcc
	v_cmp_ngt_f32_e32 vcc, s63, v66
	v_mul_f32_e32 v68, v65, v65
	v_fmamk_f32 v69, v68, 0xba1345e1, v169
	v_fmaak_f32 v69, v68, v69, 0xbcdac9b8
	v_cndmask_b32_e32 v66, v172, v67, vcc
	v_fmaak_f32 v69, v68, v69, 0x3de703be
	v_fmaak_f32 v69, v68, v69, 0xbec09330
	v_cmp_nlt_f32_e64 vcc, |v65|, 1.0
	v_fmaak_f32 v68, v68, v69, 0x3e0375d0
	v_sub_f32_e32 v70, 1.0, v66
	v_fma_f32 v71, |v65|, v68, |v65|
	v_cndmask_b32_e32 v70, v71, v70, vcc
	v_bfi_b32 v71, s64, v70, v65
	v_mul_f32_e32 v179, v64, v179
	v_add_f32_e32 v71, 1.0, v71
	v_mul_f32_e32 v179, v179, v71
	s_nop 1
	v_readlane_b32 s100, v122, 6
	v_readlane_b32 s50, v179, 0
	s_lshl_b32 s100, s100, 11
	s_add_u32 s100, s98, s100
	s_addc_u32 s101, s99, 0
	global_load_dwordx4 v[242:245], v178, s[100:101]
	global_load_dwordx4 v[246:249], v178, s[100:101] offset:1024
	s_waitcnt vmcnt(12)
	v_mov_b32_e32 v182, s50
	v_cvt_pk_f32_fp8_e32 v[64:65], v192
	v_cvt_pk_f32_fp8_sdwa v[66:67], v192 src0_sel:WORD_1
	v_cvt_pk_f32_fp8_e32 v[68:69], v193
	v_cvt_pk_f32_fp8_sdwa v[70:71], v193 src0_sel:WORD_1
	v_pk_fma_f32 v[60:61], v[182:183], v[64:65], 0 op_sel_hi:[0,1,0]
	v_pk_fma_f32 v[62:63], v[182:183], v[66:67], 0 op_sel_hi:[0,1,0]
	v_pk_fma_f32 v[56:57], v[182:183], v[68:69], 0 op_sel_hi:[0,1,0]
	v_pk_fma_f32 v[58:59], v[182:183], v[70:71], 0 op_sel_hi:[0,1,0]
	v_cvt_pk_f32_fp8_e32 v[64:65], v194
	v_cvt_pk_f32_fp8_sdwa v[66:67], v194 src0_sel:WORD_1
	v_cvt_pk_f32_fp8_e32 v[68:69], v195
	v_cvt_pk_f32_fp8_sdwa v[70:71], v195 src0_sel:WORD_1
	v_pk_fma_f32 v[52:53], v[182:183], v[64:65], 0 op_sel_hi:[0,1,0]
	v_pk_fma_f32 v[54:55], v[182:183], v[66:67], 0 op_sel_hi:[0,1,0]
	v_pk_fma_f32 v[48:49], v[182:183], v[68:69], 0 op_sel_hi:[0,1,0]
	v_pk_fma_f32 v[50:51], v[182:183], v[70:71], 0 op_sel_hi:[0,1,0]
	v_cvt_pk_f32_fp8_e32 v[64:65], v196
	v_cvt_pk_f32_fp8_sdwa v[66:67], v196 src0_sel:WORD_1
	v_cvt_pk_f32_fp8_e32 v[68:69], v197
	v_cvt_pk_f32_fp8_sdwa v[70:71], v197 src0_sel:WORD_1
	v_pk_fma_f32 v[44:45], v[182:183], v[64:65], 0 op_sel_hi:[0,1,0]
	v_pk_fma_f32 v[46:47], v[182:183], v[66:67], 0 op_sel_hi:[0,1,0]
	v_pk_fma_f32 v[40:41], v[182:183], v[68:69], 0 op_sel_hi:[0,1,0]
	v_pk_fma_f32 v[42:43], v[182:183], v[70:71], 0 op_sel_hi:[0,1,0]
	v_cvt_pk_f32_fp8_e32 v[64:65], v198
	v_cvt_pk_f32_fp8_sdwa v[66:67], v198 src0_sel:WORD_1
	v_cvt_pk_f32_fp8_e32 v[68:69], v199
	v_cvt_pk_f32_fp8_sdwa v[70:71], v199 src0_sel:WORD_1
	v_pk_fma_f32 v[36:37], v[182:183], v[64:65], 0 op_sel_hi:[0,1,0]
	v_pk_fma_f32 v[38:39], v[182:183], v[66:67], 0 op_sel_hi:[0,1,0]
	v_pk_fma_f32 v[32:33], v[182:183], v[68:69], 0 op_sel_hi:[0,1,0]
	v_pk_fma_f32 v[34:35], v[182:183], v[70:71], 0 op_sel_hi:[0,1,0]
	s_nop 1
	v_readlane_b32 s100, v122, 7
	v_readlane_b32 s50, v179, 1
	s_lshl_b32 s100, s100, 11
	s_add_u32 s100, s98, s100
	s_addc_u32 s101, s99, 0
	global_load_dwordx4 v[250:253], v178, s[100:101]
	global_load_dwordx4 v[76:79], v178, s[100:101] offset:1024
	s_waitcnt vmcnt(12)
	v_mov_b32_e32 v182, s50
	v_cvt_pk_f32_fp8_e32 v[64:65], v200
	v_cvt_pk_f32_fp8_sdwa v[66:67], v200 src0_sel:WORD_1
	v_cvt_pk_f32_fp8_e32 v[68:69], v201
	v_cvt_pk_f32_fp8_sdwa v[70:71], v201 src0_sel:WORD_1
	v_pk_fma_f32 v[60:61], v[182:183], v[64:65], v[60:61] op_sel_hi:[0,1,1]
	v_pk_fma_f32 v[62:63], v[182:183], v[66:67], v[62:63] op_sel_hi:[0,1,1]
	v_pk_fma_f32 v[56:57], v[182:183], v[68:69], v[56:57] op_sel_hi:[0,1,1]
	v_pk_fma_f32 v[58:59], v[182:183], v[70:71], v[58:59] op_sel_hi:[0,1,1]
	v_cvt_pk_f32_fp8_e32 v[64:65], v202
	v_cvt_pk_f32_fp8_sdwa v[66:67], v202 src0_sel:WORD_1
	v_cvt_pk_f32_fp8_e32 v[68:69], v203
	v_cvt_pk_f32_fp8_sdwa v[70:71], v203 src0_sel:WORD_1
	v_pk_fma_f32 v[52:53], v[182:183], v[64:65], v[52:53] op_sel_hi:[0,1,1]
	v_pk_fma_f32 v[54:55], v[182:183], v[66:67], v[54:55] op_sel_hi:[0,1,1]
	v_pk_fma_f32 v[48:49], v[182:183], v[68:69], v[48:49] op_sel_hi:[0,1,1]
	v_pk_fma_f32 v[50:51], v[182:183], v[70:71], v[50:51] op_sel_hi:[0,1,1]
	v_cvt_pk_f32_fp8_e32 v[64:65], v204
	v_cvt_pk_f32_fp8_sdwa v[66:67], v204 src0_sel:WORD_1
	v_cvt_pk_f32_fp8_e32 v[68:69], v205
	v_cvt_pk_f32_fp8_sdwa v[70:71], v205 src0_sel:WORD_1
	v_pk_fma_f32 v[44:45], v[182:183], v[64:65], v[44:45] op_sel_hi:[0,1,1]
	v_pk_fma_f32 v[46:47], v[182:183], v[66:67], v[46:47] op_sel_hi:[0,1,1]
	v_pk_fma_f32 v[40:41], v[182:183], v[68:69], v[40:41] op_sel_hi:[0,1,1]
	v_pk_fma_f32 v[42:43], v[182:183], v[70:71], v[42:43] op_sel_hi:[0,1,1]
	v_cvt_pk_f32_fp8_e32 v[64:65], v206
	v_cvt_pk_f32_fp8_sdwa v[66:67], v206 src0_sel:WORD_1
	v_cvt_pk_f32_fp8_e32 v[68:69], v207
	v_cvt_pk_f32_fp8_sdwa v[70:71], v207 src0_sel:WORD_1
	v_pk_fma_f32 v[36:37], v[182:183], v[64:65], v[36:37] op_sel_hi:[0,1,1]
	v_pk_fma_f32 v[38:39], v[182:183], v[66:67], v[38:39] op_sel_hi:[0,1,1]
	v_pk_fma_f32 v[32:33], v[182:183], v[68:69], v[32:33] op_sel_hi:[0,1,1]
	v_pk_fma_f32 v[34:35], v[182:183], v[70:71], v[34:35] op_sel_hi:[0,1,1]
	s_nop 1
	v_readlane_b32 s100, v122, 8
	v_readlane_b32 s50, v179, 2
	s_lshl_b32 s100, s100, 11
	s_add_u32 s100, s98, s100
	s_addc_u32 s101, s99, 0
	global_load_dwordx4 v[192:195], v178, s[100:101]
	global_load_dwordx4 v[196:199], v178, s[100:101] offset:1024
	s_waitcnt vmcnt(12)
	v_mov_b32_e32 v182, s50
	v_cvt_pk_f32_fp8_e32 v[64:65], v208
	v_cvt_pk_f32_fp8_sdwa v[66:67], v208 src0_sel:WORD_1
	v_cvt_pk_f32_fp8_e32 v[68:69], v209
	v_cvt_pk_f32_fp8_sdwa v[70:71], v209 src0_sel:WORD_1
	v_pk_fma_f32 v[60:61], v[182:183], v[64:65], v[60:61] op_sel_hi:[0,1,1]
	v_pk_fma_f32 v[62:63], v[182:183], v[66:67], v[62:63] op_sel_hi:[0,1,1]
	v_pk_fma_f32 v[56:57], v[182:183], v[68:69], v[56:57] op_sel_hi:[0,1,1]
	v_pk_fma_f32 v[58:59], v[182:183], v[70:71], v[58:59] op_sel_hi:[0,1,1]
	v_cvt_pk_f32_fp8_e32 v[64:65], v210
	v_cvt_pk_f32_fp8_sdwa v[66:67], v210 src0_sel:WORD_1
	v_cvt_pk_f32_fp8_e32 v[68:69], v211
	v_cvt_pk_f32_fp8_sdwa v[70:71], v211 src0_sel:WORD_1
	v_pk_fma_f32 v[52:53], v[182:183], v[64:65], v[52:53] op_sel_hi:[0,1,1]
	v_pk_fma_f32 v[54:55], v[182:183], v[66:67], v[54:55] op_sel_hi:[0,1,1]
	v_pk_fma_f32 v[48:49], v[182:183], v[68:69], v[48:49] op_sel_hi:[0,1,1]
	v_pk_fma_f32 v[50:51], v[182:183], v[70:71], v[50:51] op_sel_hi:[0,1,1]
	v_cvt_pk_f32_fp8_e32 v[64:65], v212
	v_cvt_pk_f32_fp8_sdwa v[66:67], v212 src0_sel:WORD_1
	v_cvt_pk_f32_fp8_e32 v[68:69], v213
	v_cvt_pk_f32_fp8_sdwa v[70:71], v213 src0_sel:WORD_1
	v_pk_fma_f32 v[44:45], v[182:183], v[64:65], v[44:45] op_sel_hi:[0,1,1]
	v_pk_fma_f32 v[46:47], v[182:183], v[66:67], v[46:47] op_sel_hi:[0,1,1]
	v_pk_fma_f32 v[40:41], v[182:183], v[68:69], v[40:41] op_sel_hi:[0,1,1]
	v_pk_fma_f32 v[42:43], v[182:183], v[70:71], v[42:43] op_sel_hi:[0,1,1]
	v_cvt_pk_f32_fp8_e32 v[64:65], v214
	v_cvt_pk_f32_fp8_sdwa v[66:67], v214 src0_sel:WORD_1
	v_cvt_pk_f32_fp8_e32 v[68:69], v215
	v_cvt_pk_f32_fp8_sdwa v[70:71], v215 src0_sel:WORD_1
	v_pk_fma_f32 v[36:37], v[182:183], v[64:65], v[36:37] op_sel_hi:[0,1,1]
	v_pk_fma_f32 v[38:39], v[182:183], v[66:67], v[38:39] op_sel_hi:[0,1,1]
	v_pk_fma_f32 v[32:33], v[182:183], v[68:69], v[32:33] op_sel_hi:[0,1,1]
	v_pk_fma_f32 v[34:35], v[182:183], v[70:71], v[34:35] op_sel_hi:[0,1,1]
	s_nop 1
	v_readlane_b32 s100, v122, 9
	v_readlane_b32 s50, v179, 3
	s_lshl_b32 s100, s100, 11
	s_add_u32 s100, s98, s100
	s_addc_u32 s101, s99, 0
	global_load_dwordx4 v[200:203], v178, s[100:101]
	global_load_dwordx4 v[204:207], v178, s[100:101] offset:1024
	s_waitcnt vmcnt(12)
	v_mov_b32_e32 v182, s50
	v_cvt_pk_f32_fp8_e32 v[64:65], v216
	v_cvt_pk_f32_fp8_sdwa v[66:67], v216 src0_sel:WORD_1
	v_cvt_pk_f32_fp8_e32 v[68:69], v217
	v_cvt_pk_f32_fp8_sdwa v[70:71], v217 src0_sel:WORD_1
	v_pk_fma_f32 v[60:61], v[182:183], v[64:65], v[60:61] op_sel_hi:[0,1,1]
	v_pk_fma_f32 v[62:63], v[182:183], v[66:67], v[62:63] op_sel_hi:[0,1,1]
	v_pk_fma_f32 v[56:57], v[182:183], v[68:69], v[56:57] op_sel_hi:[0,1,1]
	v_pk_fma_f32 v[58:59], v[182:183], v[70:71], v[58:59] op_sel_hi:[0,1,1]
	v_cvt_pk_f32_fp8_e32 v[64:65], v218
	v_cvt_pk_f32_fp8_sdwa v[66:67], v218 src0_sel:WORD_1
	v_cvt_pk_f32_fp8_e32 v[68:69], v219
	v_cvt_pk_f32_fp8_sdwa v[70:71], v219 src0_sel:WORD_1
	v_pk_fma_f32 v[52:53], v[182:183], v[64:65], v[52:53] op_sel_hi:[0,1,1]
	v_pk_fma_f32 v[54:55], v[182:183], v[66:67], v[54:55] op_sel_hi:[0,1,1]
	v_pk_fma_f32 v[48:49], v[182:183], v[68:69], v[48:49] op_sel_hi:[0,1,1]
	v_pk_fma_f32 v[50:51], v[182:183], v[70:71], v[50:51] op_sel_hi:[0,1,1]
	v_cvt_pk_f32_fp8_e32 v[64:65], v220
	v_cvt_pk_f32_fp8_sdwa v[66:67], v220 src0_sel:WORD_1
	v_cvt_pk_f32_fp8_e32 v[68:69], v221
	v_cvt_pk_f32_fp8_sdwa v[70:71], v221 src0_sel:WORD_1
	v_pk_fma_f32 v[44:45], v[182:183], v[64:65], v[44:45] op_sel_hi:[0,1,1]
	v_pk_fma_f32 v[46:47], v[182:183], v[66:67], v[46:47] op_sel_hi:[0,1,1]
	v_pk_fma_f32 v[40:41], v[182:183], v[68:69], v[40:41] op_sel_hi:[0,1,1]
	v_pk_fma_f32 v[42:43], v[182:183], v[70:71], v[42:43] op_sel_hi:[0,1,1]
	v_cvt_pk_f32_fp8_e32 v[64:65], v222
	v_cvt_pk_f32_fp8_sdwa v[66:67], v222 src0_sel:WORD_1
	v_cvt_pk_f32_fp8_e32 v[68:69], v223
	v_cvt_pk_f32_fp8_sdwa v[70:71], v223 src0_sel:WORD_1
	v_pk_fma_f32 v[36:37], v[182:183], v[64:65], v[36:37] op_sel_hi:[0,1,1]
	v_pk_fma_f32 v[38:39], v[182:183], v[66:67], v[38:39] op_sel_hi:[0,1,1]
	v_pk_fma_f32 v[32:33], v[182:183], v[68:69], v[32:33] op_sel_hi:[0,1,1]
	v_pk_fma_f32 v[34:35], v[182:183], v[70:71], v[34:35] op_sel_hi:[0,1,1]
	s_nop 1
	v_readlane_b32 s100, v122, 10
	v_readlane_b32 s50, v179, 4
	s_lshl_b32 s100, s100, 11
	s_add_u32 s100, s98, s100
	s_addc_u32 s101, s99, 0
	global_load_dwordx4 v[208:211], v178, s[100:101]
	global_load_dwordx4 v[212:215], v178, s[100:101] offset:1024
	s_waitcnt vmcnt(12)
	v_mov_b32_e32 v182, s50
	v_cvt_pk_f32_fp8_e32 v[64:65], v224
	v_cvt_pk_f32_fp8_sdwa v[66:67], v224 src0_sel:WORD_1
	v_cvt_pk_f32_fp8_e32 v[68:69], v225
	v_cvt_pk_f32_fp8_sdwa v[70:71], v225 src0_sel:WORD_1
	v_pk_fma_f32 v[60:61], v[182:183], v[64:65], v[60:61] op_sel_hi:[0,1,1]
	v_pk_fma_f32 v[62:63], v[182:183], v[66:67], v[62:63] op_sel_hi:[0,1,1]
	v_pk_fma_f32 v[56:57], v[182:183], v[68:69], v[56:57] op_sel_hi:[0,1,1]
	v_pk_fma_f32 v[58:59], v[182:183], v[70:71], v[58:59] op_sel_hi:[0,1,1]
	v_cvt_pk_f32_fp8_e32 v[64:65], v226
	v_cvt_pk_f32_fp8_sdwa v[66:67], v226 src0_sel:WORD_1
	v_cvt_pk_f32_fp8_e32 v[68:69], v227
	v_cvt_pk_f32_fp8_sdwa v[70:71], v227 src0_sel:WORD_1
	v_pk_fma_f32 v[52:53], v[182:183], v[64:65], v[52:53] op_sel_hi:[0,1,1]
	v_pk_fma_f32 v[54:55], v[182:183], v[66:67], v[54:55] op_sel_hi:[0,1,1]
	v_pk_fma_f32 v[48:49], v[182:183], v[68:69], v[48:49] op_sel_hi:[0,1,1]
	v_pk_fma_f32 v[50:51], v[182:183], v[70:71], v[50:51] op_sel_hi:[0,1,1]
	v_cvt_pk_f32_fp8_e32 v[64:65], v228
	v_cvt_pk_f32_fp8_sdwa v[66:67], v228 src0_sel:WORD_1
	v_cvt_pk_f32_fp8_e32 v[68:69], v229
	v_cvt_pk_f32_fp8_sdwa v[70:71], v229 src0_sel:WORD_1
	v_pk_fma_f32 v[44:45], v[182:183], v[64:65], v[44:45] op_sel_hi:[0,1,1]
	v_pk_fma_f32 v[46:47], v[182:183], v[66:67], v[46:47] op_sel_hi:[0,1,1]
	v_pk_fma_f32 v[40:41], v[182:183], v[68:69], v[40:41] op_sel_hi:[0,1,1]
	v_pk_fma_f32 v[42:43], v[182:183], v[70:71], v[42:43] op_sel_hi:[0,1,1]
	v_cvt_pk_f32_fp8_e32 v[64:65], v230
	v_cvt_pk_f32_fp8_sdwa v[66:67], v230 src0_sel:WORD_1
	v_cvt_pk_f32_fp8_e32 v[68:69], v231
	v_cvt_pk_f32_fp8_sdwa v[70:71], v231 src0_sel:WORD_1
	v_pk_fma_f32 v[36:37], v[182:183], v[64:65], v[36:37] op_sel_hi:[0,1,1]
	v_pk_fma_f32 v[38:39], v[182:183], v[66:67], v[38:39] op_sel_hi:[0,1,1]
	v_pk_fma_f32 v[32:33], v[182:183], v[68:69], v[32:33] op_sel_hi:[0,1,1]
	v_pk_fma_f32 v[34:35], v[182:183], v[70:71], v[34:35] op_sel_hi:[0,1,1]
	s_nop 1
	v_readlane_b32 s100, v122, 11
	v_readlane_b32 s50, v179, 5
	s_lshl_b32 s100, s100, 11
	s_add_u32 s100, s98, s100
	s_addc_u32 s101, s99, 0
	global_load_dwordx4 v[216:219], v178, s[100:101]
	global_load_dwordx4 v[220:223], v178, s[100:101] offset:1024
	s_waitcnt vmcnt(12)
	v_mov_b32_e32 v182, s50
	v_cvt_pk_f32_fp8_e32 v[64:65], v232
	v_cvt_pk_f32_fp8_sdwa v[66:67], v232 src0_sel:WORD_1
	v_cvt_pk_f32_fp8_e32 v[68:69], v233
	v_cvt_pk_f32_fp8_sdwa v[70:71], v233 src0_sel:WORD_1
	v_pk_fma_f32 v[60:61], v[182:183], v[64:65], v[60:61] op_sel_hi:[0,1,1]
	v_pk_fma_f32 v[62:63], v[182:183], v[66:67], v[62:63] op_sel_hi:[0,1,1]
	v_pk_fma_f32 v[56:57], v[182:183], v[68:69], v[56:57] op_sel_hi:[0,1,1]
	v_pk_fma_f32 v[58:59], v[182:183], v[70:71], v[58:59] op_sel_hi:[0,1,1]
	v_cvt_pk_f32_fp8_e32 v[64:65], v234
	v_cvt_pk_f32_fp8_sdwa v[66:67], v234 src0_sel:WORD_1
	v_cvt_pk_f32_fp8_e32 v[68:69], v235
	v_cvt_pk_f32_fp8_sdwa v[70:71], v235 src0_sel:WORD_1
	v_pk_fma_f32 v[52:53], v[182:183], v[64:65], v[52:53] op_sel_hi:[0,1,1]
	v_pk_fma_f32 v[54:55], v[182:183], v[66:67], v[54:55] op_sel_hi:[0,1,1]
	v_pk_fma_f32 v[48:49], v[182:183], v[68:69], v[48:49] op_sel_hi:[0,1,1]
	v_pk_fma_f32 v[50:51], v[182:183], v[70:71], v[50:51] op_sel_hi:[0,1,1]
	v_cvt_pk_f32_fp8_e32 v[64:65], v236
	v_cvt_pk_f32_fp8_sdwa v[66:67], v236 src0_sel:WORD_1
	v_cvt_pk_f32_fp8_e32 v[68:69], v237
	v_cvt_pk_f32_fp8_sdwa v[70:71], v237 src0_sel:WORD_1
	v_pk_fma_f32 v[44:45], v[182:183], v[64:65], v[44:45] op_sel_hi:[0,1,1]
	v_pk_fma_f32 v[46:47], v[182:183], v[66:67], v[46:47] op_sel_hi:[0,1,1]
	v_pk_fma_f32 v[40:41], v[182:183], v[68:69], v[40:41] op_sel_hi:[0,1,1]
	v_pk_fma_f32 v[42:43], v[182:183], v[70:71], v[42:43] op_sel_hi:[0,1,1]
	v_cvt_pk_f32_fp8_e32 v[64:65], v238
	v_cvt_pk_f32_fp8_sdwa v[66:67], v238 src0_sel:WORD_1
	v_cvt_pk_f32_fp8_e32 v[68:69], v239
	v_cvt_pk_f32_fp8_sdwa v[70:71], v239 src0_sel:WORD_1
	v_pk_fma_f32 v[36:37], v[182:183], v[64:65], v[36:37] op_sel_hi:[0,1,1]
	v_pk_fma_f32 v[38:39], v[182:183], v[66:67], v[38:39] op_sel_hi:[0,1,1]
	v_pk_fma_f32 v[32:33], v[182:183], v[68:69], v[32:33] op_sel_hi:[0,1,1]
	v_pk_fma_f32 v[34:35], v[182:183], v[70:71], v[34:35] op_sel_hi:[0,1,1]
	s_nop 1
	v_readlane_b32 s100, v122, 12
	v_readlane_b32 s50, v179, 6
	s_lshl_b32 s100, s100, 11
	s_add_u32 s100, s98, s100
	s_addc_u32 s101, s99, 0
	global_load_dwordx4 v[224:227], v178, s[100:101]
	global_load_dwordx4 v[228:231], v178, s[100:101] offset:1024
	s_waitcnt vmcnt(12)
	v_mov_b32_e32 v182, s50
	v_cvt_pk_f32_fp8_e32 v[64:65], v242
	v_cvt_pk_f32_fp8_sdwa v[66:67], v242 src0_sel:WORD_1
	v_cvt_pk_f32_fp8_e32 v[68:69], v243
	v_cvt_pk_f32_fp8_sdwa v[70:71], v243 src0_sel:WORD_1
	v_pk_fma_f32 v[60:61], v[182:183], v[64:65], v[60:61] op_sel_hi:[0,1,1]
	v_pk_fma_f32 v[62:63], v[182:183], v[66:67], v[62:63] op_sel_hi:[0,1,1]
	v_pk_fma_f32 v[56:57], v[182:183], v[68:69], v[56:57] op_sel_hi:[0,1,1]
	v_pk_fma_f32 v[58:59], v[182:183], v[70:71], v[58:59] op_sel_hi:[0,1,1]
	v_cvt_pk_f32_fp8_e32 v[64:65], v244
	v_cvt_pk_f32_fp8_sdwa v[66:67], v244 src0_sel:WORD_1
	v_cvt_pk_f32_fp8_e32 v[68:69], v245
	v_cvt_pk_f32_fp8_sdwa v[70:71], v245 src0_sel:WORD_1
	v_pk_fma_f32 v[52:53], v[182:183], v[64:65], v[52:53] op_sel_hi:[0,1,1]
	v_pk_fma_f32 v[54:55], v[182:183], v[66:67], v[54:55] op_sel_hi:[0,1,1]
	v_pk_fma_f32 v[48:49], v[182:183], v[68:69], v[48:49] op_sel_hi:[0,1,1]
	v_pk_fma_f32 v[50:51], v[182:183], v[70:71], v[50:51] op_sel_hi:[0,1,1]
	v_cvt_pk_f32_fp8_e32 v[64:65], v246
	v_cvt_pk_f32_fp8_sdwa v[66:67], v246 src0_sel:WORD_1
	v_cvt_pk_f32_fp8_e32 v[68:69], v247
	v_cvt_pk_f32_fp8_sdwa v[70:71], v247 src0_sel:WORD_1
	v_pk_fma_f32 v[44:45], v[182:183], v[64:65], v[44:45] op_sel_hi:[0,1,1]
	v_pk_fma_f32 v[46:47], v[182:183], v[66:67], v[46:47] op_sel_hi:[0,1,1]
	v_pk_fma_f32 v[40:41], v[182:183], v[68:69], v[40:41] op_sel_hi:[0,1,1]
	v_pk_fma_f32 v[42:43], v[182:183], v[70:71], v[42:43] op_sel_hi:[0,1,1]
	v_cvt_pk_f32_fp8_e32 v[64:65], v248
	v_cvt_pk_f32_fp8_sdwa v[66:67], v248 src0_sel:WORD_1
	v_cvt_pk_f32_fp8_e32 v[68:69], v249
	v_cvt_pk_f32_fp8_sdwa v[70:71], v249 src0_sel:WORD_1
	v_pk_fma_f32 v[36:37], v[182:183], v[64:65], v[36:37] op_sel_hi:[0,1,1]
	v_pk_fma_f32 v[38:39], v[182:183], v[66:67], v[38:39] op_sel_hi:[0,1,1]
	v_pk_fma_f32 v[32:33], v[182:183], v[68:69], v[32:33] op_sel_hi:[0,1,1]
	v_pk_fma_f32 v[34:35], v[182:183], v[70:71], v[34:35] op_sel_hi:[0,1,1]
	s_nop 1
	v_readlane_b32 s100, v122, 13
	v_readlane_b32 s50, v179, 7
	s_lshl_b32 s100, s100, 11
	s_add_u32 s100, s98, s100
	s_addc_u32 s101, s99, 0
	global_load_dwordx4 v[232:235], v178, s[100:101]
	global_load_dwordx4 v[236:239], v178, s[100:101] offset:1024
	s_waitcnt vmcnt(12)
	v_mov_b32_e32 v182, s50
	v_cvt_pk_f32_fp8_e32 v[64:65], v250
	v_cvt_pk_f32_fp8_sdwa v[66:67], v250 src0_sel:WORD_1
	v_cvt_pk_f32_fp8_e32 v[68:69], v251
	v_cvt_pk_f32_fp8_sdwa v[70:71], v251 src0_sel:WORD_1
	v_pk_fma_f32 v[60:61], v[182:183], v[64:65], v[60:61] op_sel_hi:[0,1,1]
	v_pk_fma_f32 v[62:63], v[182:183], v[66:67], v[62:63] op_sel_hi:[0,1,1]
	v_pk_fma_f32 v[56:57], v[182:183], v[68:69], v[56:57] op_sel_hi:[0,1,1]
	v_pk_fma_f32 v[58:59], v[182:183], v[70:71], v[58:59] op_sel_hi:[0,1,1]
	v_cvt_pk_f32_fp8_e32 v[64:65], v252
	v_cvt_pk_f32_fp8_sdwa v[66:67], v252 src0_sel:WORD_1
	v_cvt_pk_f32_fp8_e32 v[68:69], v253
	v_cvt_pk_f32_fp8_sdwa v[70:71], v253 src0_sel:WORD_1
	v_pk_fma_f32 v[52:53], v[182:183], v[64:65], v[52:53] op_sel_hi:[0,1,1]
	v_pk_fma_f32 v[54:55], v[182:183], v[66:67], v[54:55] op_sel_hi:[0,1,1]
	v_pk_fma_f32 v[48:49], v[182:183], v[68:69], v[48:49] op_sel_hi:[0,1,1]
	v_pk_fma_f32 v[50:51], v[182:183], v[70:71], v[50:51] op_sel_hi:[0,1,1]
	v_cvt_pk_f32_fp8_e32 v[64:65], v76
	v_cvt_pk_f32_fp8_sdwa v[66:67], v76 src0_sel:WORD_1
	v_cvt_pk_f32_fp8_e32 v[68:69], v77
	v_cvt_pk_f32_fp8_sdwa v[70:71], v77 src0_sel:WORD_1
	v_pk_fma_f32 v[44:45], v[182:183], v[64:65], v[44:45] op_sel_hi:[0,1,1]
	v_pk_fma_f32 v[46:47], v[182:183], v[66:67], v[46:47] op_sel_hi:[0,1,1]
	v_pk_fma_f32 v[40:41], v[182:183], v[68:69], v[40:41] op_sel_hi:[0,1,1]
	v_pk_fma_f32 v[42:43], v[182:183], v[70:71], v[42:43] op_sel_hi:[0,1,1]
	v_cvt_pk_f32_fp8_e32 v[64:65], v78
	v_cvt_pk_f32_fp8_sdwa v[66:67], v78 src0_sel:WORD_1
	v_cvt_pk_f32_fp8_e32 v[68:69], v79
	v_cvt_pk_f32_fp8_sdwa v[70:71], v79 src0_sel:WORD_1
	v_pk_fma_f32 v[36:37], v[182:183], v[64:65], v[36:37] op_sel_hi:[0,1,1]
	v_pk_fma_f32 v[38:39], v[182:183], v[66:67], v[38:39] op_sel_hi:[0,1,1]
	v_pk_fma_f32 v[32:33], v[182:183], v[68:69], v[32:33] op_sel_hi:[0,1,1]
	v_pk_fma_f32 v[34:35], v[182:183], v[70:71], v[34:35] op_sel_hi:[0,1,1]
	s_nop 1
	v_readlane_b32 s100, v122, 14
	v_readlane_b32 s50, v179, 8
	s_lshl_b32 s100, s100, 11
	s_add_u32 s100, s98, s100
	s_addc_u32 s101, s99, 0
	global_load_dwordx4 v[242:245], v178, s[100:101]
	global_load_dwordx4 v[246:249], v178, s[100:101] offset:1024
	s_waitcnt vmcnt(12)
	v_mov_b32_e32 v182, s50
	v_cvt_pk_f32_fp8_e32 v[64:65], v192
	v_cvt_pk_f32_fp8_sdwa v[66:67], v192 src0_sel:WORD_1
	v_cvt_pk_f32_fp8_e32 v[68:69], v193
	v_cvt_pk_f32_fp8_sdwa v[70:71], v193 src0_sel:WORD_1
	v_pk_fma_f32 v[60:61], v[182:183], v[64:65], v[60:61] op_sel_hi:[0,1,1]
	v_pk_fma_f32 v[62:63], v[182:183], v[66:67], v[62:63] op_sel_hi:[0,1,1]
	v_pk_fma_f32 v[56:57], v[182:183], v[68:69], v[56:57] op_sel_hi:[0,1,1]
	v_pk_fma_f32 v[58:59], v[182:183], v[70:71], v[58:59] op_sel_hi:[0,1,1]
	v_cvt_pk_f32_fp8_e32 v[64:65], v194
	v_cvt_pk_f32_fp8_sdwa v[66:67], v194 src0_sel:WORD_1
	v_cvt_pk_f32_fp8_e32 v[68:69], v195
	v_cvt_pk_f32_fp8_sdwa v[70:71], v195 src0_sel:WORD_1
	v_pk_fma_f32 v[52:53], v[182:183], v[64:65], v[52:53] op_sel_hi:[0,1,1]
	v_pk_fma_f32 v[54:55], v[182:183], v[66:67], v[54:55] op_sel_hi:[0,1,1]
	v_pk_fma_f32 v[48:49], v[182:183], v[68:69], v[48:49] op_sel_hi:[0,1,1]
	v_pk_fma_f32 v[50:51], v[182:183], v[70:71], v[50:51] op_sel_hi:[0,1,1]
	v_cvt_pk_f32_fp8_e32 v[64:65], v196
	v_cvt_pk_f32_fp8_sdwa v[66:67], v196 src0_sel:WORD_1
	v_cvt_pk_f32_fp8_e32 v[68:69], v197
	v_cvt_pk_f32_fp8_sdwa v[70:71], v197 src0_sel:WORD_1
	v_pk_fma_f32 v[44:45], v[182:183], v[64:65], v[44:45] op_sel_hi:[0,1,1]
	v_pk_fma_f32 v[46:47], v[182:183], v[66:67], v[46:47] op_sel_hi:[0,1,1]
	v_pk_fma_f32 v[40:41], v[182:183], v[68:69], v[40:41] op_sel_hi:[0,1,1]
	v_pk_fma_f32 v[42:43], v[182:183], v[70:71], v[42:43] op_sel_hi:[0,1,1]
	v_cvt_pk_f32_fp8_e32 v[64:65], v198
	v_cvt_pk_f32_fp8_sdwa v[66:67], v198 src0_sel:WORD_1
	v_cvt_pk_f32_fp8_e32 v[68:69], v199
	v_cvt_pk_f32_fp8_sdwa v[70:71], v199 src0_sel:WORD_1
	v_pk_fma_f32 v[36:37], v[182:183], v[64:65], v[36:37] op_sel_hi:[0,1,1]
	v_pk_fma_f32 v[38:39], v[182:183], v[66:67], v[38:39] op_sel_hi:[0,1,1]
	v_pk_fma_f32 v[32:33], v[182:183], v[68:69], v[32:33] op_sel_hi:[0,1,1]
	v_pk_fma_f32 v[34:35], v[182:183], v[70:71], v[34:35] op_sel_hi:[0,1,1]
	s_nop 1
	v_readlane_b32 s100, v122, 15
	v_readlane_b32 s50, v179, 9
	s_lshl_b32 s100, s100, 11
	s_add_u32 s100, s98, s100
	s_addc_u32 s101, s99, 0
	global_load_dwordx4 v[250:253], v178, s[100:101]
	global_load_dwordx4 v[76:79], v178, s[100:101] offset:1024
	s_waitcnt vmcnt(12)
	v_mov_b32_e32 v182, s50
	v_cvt_pk_f32_fp8_e32 v[64:65], v200
	v_cvt_pk_f32_fp8_sdwa v[66:67], v200 src0_sel:WORD_1
	v_cvt_pk_f32_fp8_e32 v[68:69], v201
	v_cvt_pk_f32_fp8_sdwa v[70:71], v201 src0_sel:WORD_1
	v_pk_fma_f32 v[60:61], v[182:183], v[64:65], v[60:61] op_sel_hi:[0,1,1]
	v_pk_fma_f32 v[62:63], v[182:183], v[66:67], v[62:63] op_sel_hi:[0,1,1]
	v_pk_fma_f32 v[56:57], v[182:183], v[68:69], v[56:57] op_sel_hi:[0,1,1]
	v_pk_fma_f32 v[58:59], v[182:183], v[70:71], v[58:59] op_sel_hi:[0,1,1]
	v_cvt_pk_f32_fp8_e32 v[64:65], v202
	v_cvt_pk_f32_fp8_sdwa v[66:67], v202 src0_sel:WORD_1
	v_cvt_pk_f32_fp8_e32 v[68:69], v203
	v_cvt_pk_f32_fp8_sdwa v[70:71], v203 src0_sel:WORD_1
	v_pk_fma_f32 v[52:53], v[182:183], v[64:65], v[52:53] op_sel_hi:[0,1,1]
	v_pk_fma_f32 v[54:55], v[182:183], v[66:67], v[54:55] op_sel_hi:[0,1,1]
	v_pk_fma_f32 v[48:49], v[182:183], v[68:69], v[48:49] op_sel_hi:[0,1,1]
	v_pk_fma_f32 v[50:51], v[182:183], v[70:71], v[50:51] op_sel_hi:[0,1,1]
	v_cvt_pk_f32_fp8_e32 v[64:65], v204
	v_cvt_pk_f32_fp8_sdwa v[66:67], v204 src0_sel:WORD_1
	v_cvt_pk_f32_fp8_e32 v[68:69], v205
	v_cvt_pk_f32_fp8_sdwa v[70:71], v205 src0_sel:WORD_1
	v_pk_fma_f32 v[44:45], v[182:183], v[64:65], v[44:45] op_sel_hi:[0,1,1]
	v_pk_fma_f32 v[46:47], v[182:183], v[66:67], v[46:47] op_sel_hi:[0,1,1]
	v_pk_fma_f32 v[40:41], v[182:183], v[68:69], v[40:41] op_sel_hi:[0,1,1]
	v_pk_fma_f32 v[42:43], v[182:183], v[70:71], v[42:43] op_sel_hi:[0,1,1]
	v_cvt_pk_f32_fp8_e32 v[64:65], v206
	v_cvt_pk_f32_fp8_sdwa v[66:67], v206 src0_sel:WORD_1
	v_cvt_pk_f32_fp8_e32 v[68:69], v207
	v_cvt_pk_f32_fp8_sdwa v[70:71], v207 src0_sel:WORD_1
	v_pk_fma_f32 v[36:37], v[182:183], v[64:65], v[36:37] op_sel_hi:[0,1,1]
	v_pk_fma_f32 v[38:39], v[182:183], v[66:67], v[38:39] op_sel_hi:[0,1,1]
	v_pk_fma_f32 v[32:33], v[182:183], v[68:69], v[32:33] op_sel_hi:[0,1,1]
	v_pk_fma_f32 v[34:35], v[182:183], v[70:71], v[34:35] op_sel_hi:[0,1,1]
	s_nop 1
	v_readlane_b32 s100, v174, 0
	v_readlane_b32 s50, v179, 10
	s_lshl_b32 s100, s100, 11
	s_add_u32 s100, s96, s100
	s_addc_u32 s101, s97, 0
	global_load_dwordx4 v[0:3], v178, s[100:101]
	global_load_dwordx4 v[4:7], v178, s[100:101] offset:1024
	s_waitcnt vmcnt(12)
	v_mov_b32_e32 v182, s50
	v_cvt_pk_f32_fp8_e32 v[64:65], v208
	v_cvt_pk_f32_fp8_sdwa v[66:67], v208 src0_sel:WORD_1
	v_cvt_pk_f32_fp8_e32 v[68:69], v209
	v_cvt_pk_f32_fp8_sdwa v[70:71], v209 src0_sel:WORD_1
	v_pk_fma_f32 v[60:61], v[182:183], v[64:65], v[60:61] op_sel_hi:[0,1,1]
	v_pk_fma_f32 v[62:63], v[182:183], v[66:67], v[62:63] op_sel_hi:[0,1,1]
	v_pk_fma_f32 v[56:57], v[182:183], v[68:69], v[56:57] op_sel_hi:[0,1,1]
	v_pk_fma_f32 v[58:59], v[182:183], v[70:71], v[58:59] op_sel_hi:[0,1,1]
	v_cvt_pk_f32_fp8_e32 v[64:65], v210
	v_cvt_pk_f32_fp8_sdwa v[66:67], v210 src0_sel:WORD_1
	v_cvt_pk_f32_fp8_e32 v[68:69], v211
	v_cvt_pk_f32_fp8_sdwa v[70:71], v211 src0_sel:WORD_1
	v_pk_fma_f32 v[52:53], v[182:183], v[64:65], v[52:53] op_sel_hi:[0,1,1]
	v_pk_fma_f32 v[54:55], v[182:183], v[66:67], v[54:55] op_sel_hi:[0,1,1]
	v_pk_fma_f32 v[48:49], v[182:183], v[68:69], v[48:49] op_sel_hi:[0,1,1]
	v_pk_fma_f32 v[50:51], v[182:183], v[70:71], v[50:51] op_sel_hi:[0,1,1]
	v_cvt_pk_f32_fp8_e32 v[64:65], v212
	v_cvt_pk_f32_fp8_sdwa v[66:67], v212 src0_sel:WORD_1
	v_cvt_pk_f32_fp8_e32 v[68:69], v213
	v_cvt_pk_f32_fp8_sdwa v[70:71], v213 src0_sel:WORD_1
	v_pk_fma_f32 v[44:45], v[182:183], v[64:65], v[44:45] op_sel_hi:[0,1,1]
	v_pk_fma_f32 v[46:47], v[182:183], v[66:67], v[46:47] op_sel_hi:[0,1,1]
	v_pk_fma_f32 v[40:41], v[182:183], v[68:69], v[40:41] op_sel_hi:[0,1,1]
	v_pk_fma_f32 v[42:43], v[182:183], v[70:71], v[42:43] op_sel_hi:[0,1,1]
	v_cvt_pk_f32_fp8_e32 v[64:65], v214
	v_cvt_pk_f32_fp8_sdwa v[66:67], v214 src0_sel:WORD_1
	v_cvt_pk_f32_fp8_e32 v[68:69], v215
	v_cvt_pk_f32_fp8_sdwa v[70:71], v215 src0_sel:WORD_1
	v_pk_fma_f32 v[36:37], v[182:183], v[64:65], v[36:37] op_sel_hi:[0,1,1]
	v_pk_fma_f32 v[38:39], v[182:183], v[66:67], v[38:39] op_sel_hi:[0,1,1]
	v_pk_fma_f32 v[32:33], v[182:183], v[68:69], v[32:33] op_sel_hi:[0,1,1]
	v_pk_fma_f32 v[34:35], v[182:183], v[70:71], v[34:35] op_sel_hi:[0,1,1]
	s_nop 1
	v_readlane_b32 s100, v174, 1
	v_readlane_b32 s50, v179, 11
	s_lshl_b32 s100, s100, 11
	s_add_u32 s100, s96, s100
	s_addc_u32 s101, s97, 0
	global_load_dwordx4 v[8:11], v178, s[100:101]
	global_load_dwordx4 v[16:19], v178, s[100:101] offset:1024
	s_waitcnt vmcnt(12)
	v_mov_b32_e32 v182, s50
	v_cvt_pk_f32_fp8_e32 v[64:65], v216
	v_cvt_pk_f32_fp8_sdwa v[66:67], v216 src0_sel:WORD_1
	v_cvt_pk_f32_fp8_e32 v[68:69], v217
	v_cvt_pk_f32_fp8_sdwa v[70:71], v217 src0_sel:WORD_1
	v_pk_fma_f32 v[60:61], v[182:183], v[64:65], v[60:61] op_sel_hi:[0,1,1]
	v_pk_fma_f32 v[62:63], v[182:183], v[66:67], v[62:63] op_sel_hi:[0,1,1]
	v_pk_fma_f32 v[56:57], v[182:183], v[68:69], v[56:57] op_sel_hi:[0,1,1]
	v_pk_fma_f32 v[58:59], v[182:183], v[70:71], v[58:59] op_sel_hi:[0,1,1]
	v_cvt_pk_f32_fp8_e32 v[64:65], v218
	v_cvt_pk_f32_fp8_sdwa v[66:67], v218 src0_sel:WORD_1
	v_cvt_pk_f32_fp8_e32 v[68:69], v219
	v_cvt_pk_f32_fp8_sdwa v[70:71], v219 src0_sel:WORD_1
	v_pk_fma_f32 v[52:53], v[182:183], v[64:65], v[52:53] op_sel_hi:[0,1,1]
	v_pk_fma_f32 v[54:55], v[182:183], v[66:67], v[54:55] op_sel_hi:[0,1,1]
	v_pk_fma_f32 v[48:49], v[182:183], v[68:69], v[48:49] op_sel_hi:[0,1,1]
	v_pk_fma_f32 v[50:51], v[182:183], v[70:71], v[50:51] op_sel_hi:[0,1,1]
	v_cvt_pk_f32_fp8_e32 v[64:65], v220
	v_cvt_pk_f32_fp8_sdwa v[66:67], v220 src0_sel:WORD_1
	v_cvt_pk_f32_fp8_e32 v[68:69], v221
	v_cvt_pk_f32_fp8_sdwa v[70:71], v221 src0_sel:WORD_1
	v_pk_fma_f32 v[44:45], v[182:183], v[64:65], v[44:45] op_sel_hi:[0,1,1]
	v_pk_fma_f32 v[46:47], v[182:183], v[66:67], v[46:47] op_sel_hi:[0,1,1]
	v_pk_fma_f32 v[40:41], v[182:183], v[68:69], v[40:41] op_sel_hi:[0,1,1]
	v_pk_fma_f32 v[42:43], v[182:183], v[70:71], v[42:43] op_sel_hi:[0,1,1]
	v_cvt_pk_f32_fp8_e32 v[64:65], v222
	v_cvt_pk_f32_fp8_sdwa v[66:67], v222 src0_sel:WORD_1
	v_cvt_pk_f32_fp8_e32 v[68:69], v223
	v_cvt_pk_f32_fp8_sdwa v[70:71], v223 src0_sel:WORD_1
	v_pk_fma_f32 v[36:37], v[182:183], v[64:65], v[36:37] op_sel_hi:[0,1,1]
	v_pk_fma_f32 v[38:39], v[182:183], v[66:67], v[38:39] op_sel_hi:[0,1,1]
	v_pk_fma_f32 v[32:33], v[182:183], v[68:69], v[32:33] op_sel_hi:[0,1,1]
	v_pk_fma_f32 v[34:35], v[182:183], v[70:71], v[34:35] op_sel_hi:[0,1,1]
	s_nop 1
	v_readlane_b32 s100, v174, 2
	v_readlane_b32 s50, v179, 12
	s_lshl_b32 s100, s100, 11
	s_add_u32 s100, s96, s100
	s_addc_u32 s101, s97, 0
	global_load_dwordx4 v[80:83], v178, s[100:101]
	global_load_dwordx4 v[84:87], v178, s[100:101] offset:1024
	s_waitcnt vmcnt(12)
	v_mov_b32_e32 v182, s50
	v_cvt_pk_f32_fp8_e32 v[64:65], v224
	v_cvt_pk_f32_fp8_sdwa v[66:67], v224 src0_sel:WORD_1
	v_cvt_pk_f32_fp8_e32 v[68:69], v225
	v_cvt_pk_f32_fp8_sdwa v[70:71], v225 src0_sel:WORD_1
	v_pk_fma_f32 v[60:61], v[182:183], v[64:65], v[60:61] op_sel_hi:[0,1,1]
	v_pk_fma_f32 v[62:63], v[182:183], v[66:67], v[62:63] op_sel_hi:[0,1,1]
	v_pk_fma_f32 v[56:57], v[182:183], v[68:69], v[56:57] op_sel_hi:[0,1,1]
	v_pk_fma_f32 v[58:59], v[182:183], v[70:71], v[58:59] op_sel_hi:[0,1,1]
	v_cvt_pk_f32_fp8_e32 v[64:65], v226
	v_cvt_pk_f32_fp8_sdwa v[66:67], v226 src0_sel:WORD_1
	v_cvt_pk_f32_fp8_e32 v[68:69], v227
	v_cvt_pk_f32_fp8_sdwa v[70:71], v227 src0_sel:WORD_1
	v_pk_fma_f32 v[52:53], v[182:183], v[64:65], v[52:53] op_sel_hi:[0,1,1]
	v_pk_fma_f32 v[54:55], v[182:183], v[66:67], v[54:55] op_sel_hi:[0,1,1]
	v_pk_fma_f32 v[48:49], v[182:183], v[68:69], v[48:49] op_sel_hi:[0,1,1]
	v_pk_fma_f32 v[50:51], v[182:183], v[70:71], v[50:51] op_sel_hi:[0,1,1]
	v_cvt_pk_f32_fp8_e32 v[64:65], v228
	v_cvt_pk_f32_fp8_sdwa v[66:67], v228 src0_sel:WORD_1
	v_cvt_pk_f32_fp8_e32 v[68:69], v229
	v_cvt_pk_f32_fp8_sdwa v[70:71], v229 src0_sel:WORD_1
	v_pk_fma_f32 v[44:45], v[182:183], v[64:65], v[44:45] op_sel_hi:[0,1,1]
	v_pk_fma_f32 v[46:47], v[182:183], v[66:67], v[46:47] op_sel_hi:[0,1,1]
	v_pk_fma_f32 v[40:41], v[182:183], v[68:69], v[40:41] op_sel_hi:[0,1,1]
	v_pk_fma_f32 v[42:43], v[182:183], v[70:71], v[42:43] op_sel_hi:[0,1,1]
	v_cvt_pk_f32_fp8_e32 v[64:65], v230
	v_cvt_pk_f32_fp8_sdwa v[66:67], v230 src0_sel:WORD_1
	v_cvt_pk_f32_fp8_e32 v[68:69], v231
	v_cvt_pk_f32_fp8_sdwa v[70:71], v231 src0_sel:WORD_1
	v_pk_fma_f32 v[36:37], v[182:183], v[64:65], v[36:37] op_sel_hi:[0,1,1]
	v_pk_fma_f32 v[38:39], v[182:183], v[66:67], v[38:39] op_sel_hi:[0,1,1]
	v_pk_fma_f32 v[32:33], v[182:183], v[68:69], v[32:33] op_sel_hi:[0,1,1]
	v_pk_fma_f32 v[34:35], v[182:183], v[70:71], v[34:35] op_sel_hi:[0,1,1]
	s_nop 1
	v_readlane_b32 s100, v174, 3
	v_readlane_b32 s50, v179, 13
	s_lshl_b32 s100, s100, 11
	s_add_u32 s100, s96, s100
	s_addc_u32 s101, s97, 0
	global_load_dwordx4 v[88:91], v178, s[100:101]
	global_load_dwordx4 v[92:95], v178, s[100:101] offset:1024
	s_waitcnt vmcnt(12)
	v_mov_b32_e32 v182, s50
	v_cvt_pk_f32_fp8_e32 v[64:65], v232
	v_cvt_pk_f32_fp8_sdwa v[66:67], v232 src0_sel:WORD_1
	v_cvt_pk_f32_fp8_e32 v[68:69], v233
	v_cvt_pk_f32_fp8_sdwa v[70:71], v233 src0_sel:WORD_1
	v_pk_fma_f32 v[60:61], v[182:183], v[64:65], v[60:61] op_sel_hi:[0,1,1]
	v_pk_fma_f32 v[62:63], v[182:183], v[66:67], v[62:63] op_sel_hi:[0,1,1]
	v_pk_fma_f32 v[56:57], v[182:183], v[68:69], v[56:57] op_sel_hi:[0,1,1]
	v_pk_fma_f32 v[58:59], v[182:183], v[70:71], v[58:59] op_sel_hi:[0,1,1]
	v_cvt_pk_f32_fp8_e32 v[64:65], v234
	v_cvt_pk_f32_fp8_sdwa v[66:67], v234 src0_sel:WORD_1
	v_cvt_pk_f32_fp8_e32 v[68:69], v235
	v_cvt_pk_f32_fp8_sdwa v[70:71], v235 src0_sel:WORD_1
	v_pk_fma_f32 v[52:53], v[182:183], v[64:65], v[52:53] op_sel_hi:[0,1,1]
	v_pk_fma_f32 v[54:55], v[182:183], v[66:67], v[54:55] op_sel_hi:[0,1,1]
	v_pk_fma_f32 v[48:49], v[182:183], v[68:69], v[48:49] op_sel_hi:[0,1,1]
	v_pk_fma_f32 v[50:51], v[182:183], v[70:71], v[50:51] op_sel_hi:[0,1,1]
	v_cvt_pk_f32_fp8_e32 v[64:65], v236
	v_cvt_pk_f32_fp8_sdwa v[66:67], v236 src0_sel:WORD_1
	v_cvt_pk_f32_fp8_e32 v[68:69], v237
	v_cvt_pk_f32_fp8_sdwa v[70:71], v237 src0_sel:WORD_1
	v_pk_fma_f32 v[44:45], v[182:183], v[64:65], v[44:45] op_sel_hi:[0,1,1]
	v_pk_fma_f32 v[46:47], v[182:183], v[66:67], v[46:47] op_sel_hi:[0,1,1]
	v_pk_fma_f32 v[40:41], v[182:183], v[68:69], v[40:41] op_sel_hi:[0,1,1]
	v_pk_fma_f32 v[42:43], v[182:183], v[70:71], v[42:43] op_sel_hi:[0,1,1]
	v_cvt_pk_f32_fp8_e32 v[64:65], v238
	v_cvt_pk_f32_fp8_sdwa v[66:67], v238 src0_sel:WORD_1
	v_cvt_pk_f32_fp8_e32 v[68:69], v239
	v_cvt_pk_f32_fp8_sdwa v[70:71], v239 src0_sel:WORD_1
	v_pk_fma_f32 v[36:37], v[182:183], v[64:65], v[36:37] op_sel_hi:[0,1,1]
	v_pk_fma_f32 v[38:39], v[182:183], v[66:67], v[38:39] op_sel_hi:[0,1,1]
	v_pk_fma_f32 v[32:33], v[182:183], v[68:69], v[32:33] op_sel_hi:[0,1,1]
	v_pk_fma_f32 v[34:35], v[182:183], v[70:71], v[34:35] op_sel_hi:[0,1,1]
	s_nop 1
	v_readlane_b32 s100, v174, 4
	v_readlane_b32 s50, v179, 14
	s_lshl_b32 s100, s100, 11
	s_add_u32 s100, s96, s100
	s_addc_u32 s101, s97, 0
	global_load_dwordx4 v[96:99], v178, s[100:101]
	global_load_dwordx4 v[100:103], v178, s[100:101] offset:1024
	s_waitcnt vmcnt(12)
	v_mov_b32_e32 v182, s50
	v_cvt_pk_f32_fp8_e32 v[64:65], v242
	v_cvt_pk_f32_fp8_sdwa v[66:67], v242 src0_sel:WORD_1
	v_cvt_pk_f32_fp8_e32 v[68:69], v243
	v_cvt_pk_f32_fp8_sdwa v[70:71], v243 src0_sel:WORD_1
	v_pk_fma_f32 v[60:61], v[182:183], v[64:65], v[60:61] op_sel_hi:[0,1,1]
	v_pk_fma_f32 v[62:63], v[182:183], v[66:67], v[62:63] op_sel_hi:[0,1,1]
	v_pk_fma_f32 v[56:57], v[182:183], v[68:69], v[56:57] op_sel_hi:[0,1,1]
	v_pk_fma_f32 v[58:59], v[182:183], v[70:71], v[58:59] op_sel_hi:[0,1,1]
	v_cvt_pk_f32_fp8_e32 v[64:65], v244
	v_cvt_pk_f32_fp8_sdwa v[66:67], v244 src0_sel:WORD_1
	v_cvt_pk_f32_fp8_e32 v[68:69], v245
	v_cvt_pk_f32_fp8_sdwa v[70:71], v245 src0_sel:WORD_1
	v_pk_fma_f32 v[52:53], v[182:183], v[64:65], v[52:53] op_sel_hi:[0,1,1]
	v_pk_fma_f32 v[54:55], v[182:183], v[66:67], v[54:55] op_sel_hi:[0,1,1]
	v_pk_fma_f32 v[48:49], v[182:183], v[68:69], v[48:49] op_sel_hi:[0,1,1]
	v_pk_fma_f32 v[50:51], v[182:183], v[70:71], v[50:51] op_sel_hi:[0,1,1]
	v_cvt_pk_f32_fp8_e32 v[64:65], v246
	v_cvt_pk_f32_fp8_sdwa v[66:67], v246 src0_sel:WORD_1
	v_cvt_pk_f32_fp8_e32 v[68:69], v247
	v_cvt_pk_f32_fp8_sdwa v[70:71], v247 src0_sel:WORD_1
	v_pk_fma_f32 v[44:45], v[182:183], v[64:65], v[44:45] op_sel_hi:[0,1,1]
	v_pk_fma_f32 v[46:47], v[182:183], v[66:67], v[46:47] op_sel_hi:[0,1,1]
	v_pk_fma_f32 v[40:41], v[182:183], v[68:69], v[40:41] op_sel_hi:[0,1,1]
	v_pk_fma_f32 v[42:43], v[182:183], v[70:71], v[42:43] op_sel_hi:[0,1,1]
	v_cvt_pk_f32_fp8_e32 v[64:65], v248
	v_cvt_pk_f32_fp8_sdwa v[66:67], v248 src0_sel:WORD_1
	v_cvt_pk_f32_fp8_e32 v[68:69], v249
	v_cvt_pk_f32_fp8_sdwa v[70:71], v249 src0_sel:WORD_1
	v_pk_fma_f32 v[36:37], v[182:183], v[64:65], v[36:37] op_sel_hi:[0,1,1]
	v_pk_fma_f32 v[38:39], v[182:183], v[66:67], v[38:39] op_sel_hi:[0,1,1]
	v_pk_fma_f32 v[32:33], v[182:183], v[68:69], v[32:33] op_sel_hi:[0,1,1]
	v_pk_fma_f32 v[34:35], v[182:183], v[70:71], v[34:35] op_sel_hi:[0,1,1]
	s_nop 1
	v_readlane_b32 s100, v174, 5
	v_readlane_b32 s50, v179, 15
	s_lshl_b32 s100, s100, 11
	s_add_u32 s100, s96, s100
	s_addc_u32 s101, s97, 0
	global_load_dwordx4 v[104:107], v178, s[100:101]
	global_load_dwordx4 v[108:111], v178, s[100:101] offset:1024
	s_waitcnt vmcnt(12)
	v_mov_b32_e32 v182, s50
	v_cvt_pk_f32_fp8_e32 v[64:65], v250
	v_cvt_pk_f32_fp8_sdwa v[66:67], v250 src0_sel:WORD_1
	v_cvt_pk_f32_fp8_e32 v[68:69], v251
	v_cvt_pk_f32_fp8_sdwa v[70:71], v251 src0_sel:WORD_1
	v_pk_fma_f32 v[60:61], v[182:183], v[64:65], v[60:61] op_sel_hi:[0,1,1]
	v_pk_fma_f32 v[62:63], v[182:183], v[66:67], v[62:63] op_sel_hi:[0,1,1]
	v_pk_fma_f32 v[56:57], v[182:183], v[68:69], v[56:57] op_sel_hi:[0,1,1]
	v_pk_fma_f32 v[58:59], v[182:183], v[70:71], v[58:59] op_sel_hi:[0,1,1]
	v_cvt_pk_f32_fp8_e32 v[64:65], v252
	v_cvt_pk_f32_fp8_sdwa v[66:67], v252 src0_sel:WORD_1
	v_cvt_pk_f32_fp8_e32 v[68:69], v253
	v_cvt_pk_f32_fp8_sdwa v[70:71], v253 src0_sel:WORD_1
	v_pk_fma_f32 v[52:53], v[182:183], v[64:65], v[52:53] op_sel_hi:[0,1,1]
	v_pk_fma_f32 v[54:55], v[182:183], v[66:67], v[54:55] op_sel_hi:[0,1,1]
	v_pk_fma_f32 v[48:49], v[182:183], v[68:69], v[48:49] op_sel_hi:[0,1,1]
	v_pk_fma_f32 v[50:51], v[182:183], v[70:71], v[50:51] op_sel_hi:[0,1,1]
	v_cvt_pk_f32_fp8_e32 v[64:65], v76
	v_cvt_pk_f32_fp8_sdwa v[66:67], v76 src0_sel:WORD_1
	v_cvt_pk_f32_fp8_e32 v[68:69], v77
	v_cvt_pk_f32_fp8_sdwa v[70:71], v77 src0_sel:WORD_1
	v_pk_fma_f32 v[44:45], v[182:183], v[64:65], v[44:45] op_sel_hi:[0,1,1]
	v_pk_fma_f32 v[46:47], v[182:183], v[66:67], v[46:47] op_sel_hi:[0,1,1]
	v_pk_fma_f32 v[40:41], v[182:183], v[68:69], v[40:41] op_sel_hi:[0,1,1]
	v_pk_fma_f32 v[42:43], v[182:183], v[70:71], v[42:43] op_sel_hi:[0,1,1]
	v_cvt_pk_f32_fp8_e32 v[64:65], v78
	v_cvt_pk_f32_fp8_sdwa v[66:67], v78 src0_sel:WORD_1
	v_cvt_pk_f32_fp8_e32 v[68:69], v79
	v_cvt_pk_f32_fp8_sdwa v[70:71], v79 src0_sel:WORD_1
	v_pk_fma_f32 v[36:37], v[182:183], v[64:65], v[36:37] op_sel_hi:[0,1,1]
	v_pk_fma_f32 v[38:39], v[182:183], v[66:67], v[38:39] op_sel_hi:[0,1,1]
	v_pk_fma_f32 v[32:33], v[182:183], v[68:69], v[32:33] op_sel_hi:[0,1,1]
	v_pk_fma_f32 v[34:35], v[182:183], v[70:71], v[34:35] op_sel_hi:[0,1,1]
	s_branch .LBB0_2776
